# v32 + first load segment of a K-loop iteration issues the 8 B-fragment ds_reads before the scalar address preamble
# baseline (speedup 1.0000x reference)
.LBB0_394:
	ds_read_b128 v[178:181], v153
	ds_read_b128 v[182:185], v153 offset:1024
	ds_read_b128 v[186:189], v153 offset:2048
	ds_read_b128 v[190:193], v153 offset:3072
	ds_read_b128 v[194:197], v153 offset:4096
	ds_read_b128 v[198:201], v153 offset:5120
	ds_read_b128 v[208:211], v153 offset:6144
	ds_read_b128 v[212:215], v153 offset:7168
	s_add_u32 s0, s24, 0xfff80080
	s_addc_u32 s1, s25, -1
	s_add_i32 s33, 0, 0x10000
	s_cmp_eq_u32 s60, 28
	s_cselect_b32 s29, s7, s1
	s_cselect_b32 s28, s19, s0
	s_cselect_b32 s27, s17, s59
	s_cselect_b32 s26, s49, s58
	s_add_i32 s55, 0, 0x14000
	v_add_u32_e32 v158, s33, v151
	v_add_u32_e32 v174, s55, v151
	ds_read_b128 v[142:145], v158
	ds_read_b128 v[146:149], v158 offset:1024
	ds_read_b128 v[154:157], v158 offset:2048
	ds_read_b128 v[158:161], v158 offset:3072
	ds_read_b128 v[162:165], v174
	ds_read_b128 v[166:169], v174 offset:1024
	ds_read_b128 v[170:173], v174 offset:2048
	ds_read_b128 v[174:177], v174 offset:3072
	v_lshl_add_u64 v[204:205], s[24:25], 0, v[138:139]
	s_add_i32 m0, s9, 0xc000
	global_load_lds_dwordx4 v[204:205], off
	v_lshl_add_u64 v[204:205], s[24:25], 0, v[140:141]
	s_add_i32 m0, s9, 0xe000
	s_nop 0
	global_load_lds_dwordx4 v[204:205], off
	s_waitcnt vmcnt(8)
	s_waitcnt lgkmcnt(0)
	s_setprio 1
	s_barrier
	v_mfma_f32_16x16x32_bf16 v[126:129], v[142:145], v[178:181], v[126:129]
	v_mfma_f32_16x16x32_bf16 v[122:125], v[154:157], v[178:181], v[122:125]
	v_mfma_f32_16x16x32_bf16 v[110:113], v[142:145], v[186:189], v[110:113]
	v_mfma_f32_16x16x32_bf16 v[106:109], v[154:157], v[186:189], v[106:109]
	v_mfma_f32_16x16x32_bf16 v[94:97], v[142:145], v[194:197], v[94:97]
	v_mfma_f32_16x16x32_bf16 v[90:93], v[154:157], v[194:197], v[90:93]
	v_mfma_f32_16x16x32_bf16 v[78:81], v[142:145], v[208:211], v[78:81]
	v_mfma_f32_16x16x32_bf16 v[74:77], v[154:157], v[208:211], v[74:77]
	v_mfma_f32_16x16x32_bf16 v[126:129], v[146:149], v[182:185], v[126:129]
	v_mfma_f32_16x16x32_bf16 v[122:125], v[158:161], v[182:185], v[122:125]
	v_mfma_f32_16x16x32_bf16 v[110:113], v[146:149], v[190:193], v[110:113]
	v_mfma_f32_16x16x32_bf16 v[106:109], v[158:161], v[190:193], v[106:109]
	v_mfma_f32_16x16x32_bf16 v[94:97], v[146:149], v[198:201], v[94:97]
	v_mfma_f32_16x16x32_bf16 v[90:93], v[158:161], v[198:201], v[90:93]
	v_mfma_f32_16x16x32_bf16 v[78:81], v[146:149], v[212:215], v[78:81]
	v_mfma_f32_16x16x32_bf16 v[74:77], v[158:161], v[212:215], v[74:77]
	s_setprio 0
	s_setprio 1
	v_mfma_f32_16x16x32_bf16 v[118:121], v[162:165], v[178:181], v[118:121]
	v_mfma_f32_16x16x32_bf16 v[114:117], v[170:173], v[178:181], v[114:117]
	v_mfma_f32_16x16x32_bf16 v[102:105], v[162:165], v[186:189], v[102:105]
	v_mfma_f32_16x16x32_bf16 v[98:101], v[170:173], v[186:189], v[98:101]
	v_mfma_f32_16x16x32_bf16 v[86:89], v[162:165], v[194:197], v[86:89]
	v_mfma_f32_16x16x32_bf16 v[82:85], v[170:173], v[194:197], v[82:85]
	v_mfma_f32_16x16x32_bf16 v[70:73], v[162:165], v[208:211], v[70:73]
	v_mfma_f32_16x16x32_bf16 v[66:69], v[170:173], v[208:211], v[66:69]
	v_mfma_f32_16x16x32_bf16 v[118:121], v[166:169], v[182:185], v[118:121]
	v_mfma_f32_16x16x32_bf16 v[114:117], v[174:177], v[182:185], v[114:117]
	v_mfma_f32_16x16x32_bf16 v[102:105], v[166:169], v[190:193], v[102:105]
	v_mfma_f32_16x16x32_bf16 v[98:101], v[174:177], v[190:193], v[98:101]
	v_mfma_f32_16x16x32_bf16 v[86:89], v[166:169], v[198:201], v[86:89]
	v_mfma_f32_16x16x32_bf16 v[82:85], v[174:177], v[198:201], v[82:85]
	v_mfma_f32_16x16x32_bf16 v[70:73], v[166:169], v[212:215], v[70:73]
	v_mfma_f32_16x16x32_bf16 v[66:69], v[174:177], v[212:215], v[66:69]
	s_barrier
	s_setprio 0
	s_add_i32 s0, s33, s34
	v_lshl_add_u64 v[204:205], s[26:27], 0, v[132:133]
	s_mov_b32 m0, s0
	ds_read_b128 v[178:181], v153 offset:16384
	ds_read_b128 v[182:185], v153 offset:17408
	ds_read_b128 v[186:189], v153 offset:18432
	ds_read_b128 v[190:193], v153 offset:19456
	ds_read_b128 v[194:197], v153 offset:20480
	ds_read_b128 v[198:201], v153 offset:21504
	ds_read_b128 v[208:211], v153 offset:22528
	ds_read_b128 v[212:215], v153 offset:23552
	global_load_lds_dwordx4 v[204:205], off
	s_add_i32 m0, s0, 0x2000
	s_add_u32 s0, s26, 0x80000
	v_lshl_add_u64 v[216:217], s[26:27], 0, v[136:137]
	s_addc_u32 s1, s27, 0
	s_add_i32 s33, s55, s34
	global_load_lds_dwordx4 v[216:217], off
	v_lshl_add_u64 v[218:219], s[0:1], 0, v[132:133]
	s_mov_b32 m0, s33
	v_lshl_add_u64 v[220:221], s[28:29], 0, v[134:135]
	global_load_lds_dwordx4 v[218:219], off
	v_lshl_add_u64 v[218:219], s[0:1], 0, v[136:137]
	s_add_i32 m0, s33, 0x2000
	s_nop 0
	global_load_lds_dwordx4 v[218:219], off
	v_lshl_add_u64 v[218:219], s[28:29], 0, v[130:131]
	s_mov_b32 m0, s9
	s_nop 0
	global_load_lds_dwordx4 v[218:219], off
	s_mov_b32 m0, s35
	s_nop 0
	global_load_lds_dwordx4 v[220:221], off
	s_waitcnt vmcnt(8)
	s_waitcnt lgkmcnt(0)
	s_setprio 1
	s_barrier
	v_mfma_f32_16x16x32_bf16 v[62:65], v[142:145], v[178:181], v[62:65]
	v_mfma_f32_16x16x32_bf16 v[58:61], v[154:157], v[178:181], v[58:61]
	v_mfma_f32_16x16x32_bf16 v[46:49], v[142:145], v[186:189], v[46:49]
	v_mfma_f32_16x16x32_bf16 v[42:45], v[154:157], v[186:189], v[42:45]
	v_mfma_f32_16x16x32_bf16 v[30:33], v[142:145], v[194:197], v[30:33]
	v_mfma_f32_16x16x32_bf16 v[26:29], v[154:157], v[194:197], v[26:29]
	v_mfma_f32_16x16x32_bf16 v[14:17], v[142:145], v[208:211], v[14:17]
	v_mfma_f32_16x16x32_bf16 v[10:13], v[154:157], v[208:211], v[10:13]
	v_mfma_f32_16x16x32_bf16 v[62:65], v[146:149], v[182:185], v[62:65]
	v_mfma_f32_16x16x32_bf16 v[58:61], v[158:161], v[182:185], v[58:61]
	v_mfma_f32_16x16x32_bf16 v[46:49], v[146:149], v[190:193], v[46:49]
	v_mfma_f32_16x16x32_bf16 v[42:45], v[158:161], v[190:193], v[42:45]
	v_mfma_f32_16x16x32_bf16 v[30:33], v[146:149], v[198:201], v[30:33]
	v_mfma_f32_16x16x32_bf16 v[26:29], v[158:161], v[198:201], v[26:29]
	v_mfma_f32_16x16x32_bf16 v[14:17], v[146:149], v[212:215], v[14:17]
	v_mfma_f32_16x16x32_bf16 v[10:13], v[158:161], v[212:215], v[10:13]
	s_setprio 0
	s_setprio 1
	v_mfma_f32_16x16x32_bf16 v[54:57], v[162:165], v[178:181], v[54:57]
	v_mfma_f32_16x16x32_bf16 v[50:53], v[170:173], v[178:181], v[50:53]
	v_mfma_f32_16x16x32_bf16 v[38:41], v[162:165], v[186:189], v[38:41]
	v_mfma_f32_16x16x32_bf16 v[34:37], v[170:173], v[186:189], v[34:37]
	v_mfma_f32_16x16x32_bf16 v[22:25], v[162:165], v[194:197], v[22:25]
	v_mfma_f32_16x16x32_bf16 v[18:21], v[170:173], v[194:197], v[18:21]
	v_mfma_f32_16x16x32_bf16 v[6:9], v[162:165], v[208:211], v[6:9]
	v_mfma_f32_16x16x32_bf16 v[2:5], v[170:173], v[208:211], v[2:5]
	v_mfma_f32_16x16x32_bf16 v[54:57], v[166:169], v[182:185], v[54:57]
	v_mfma_f32_16x16x32_bf16 v[50:53], v[174:177], v[182:185], v[50:53]
	v_mfma_f32_16x16x32_bf16 v[38:41], v[166:169], v[190:193], v[38:41]
	v_mfma_f32_16x16x32_bf16 v[34:37], v[174:177], v[190:193], v[34:37]
	v_mfma_f32_16x16x32_bf16 v[22:25], v[166:169], v[198:201], v[22:25]
	v_mfma_f32_16x16x32_bf16 v[18:21], v[174:177], v[198:201], v[18:21]
	v_mfma_f32_16x16x32_bf16 v[6:9], v[166:169], v[212:215], v[6:9]
	v_mfma_f32_16x16x32_bf16 v[2:5], v[174:177], v[212:215], v[2:5]
	s_barrier
	s_setprio 0
	s_add_i32 s33, 0, 0x18000
	s_add_i32 s55, 0, 0x1c000
	v_add_u32_e32 v158, s33, v151
	v_add_u32_e32 v174, s55, v151
	ds_read_b128 v[142:145], v158
	ds_read_b128 v[146:149], v158 offset:1024
	ds_read_b128 v[154:157], v158 offset:2048
	ds_read_b128 v[158:161], v158 offset:3072
	ds_read_b128 v[162:165], v174
	ds_read_b128 v[166:169], v174 offset:1024
	ds_read_b128 v[170:173], v174 offset:2048
	ds_read_b128 v[174:177], v174 offset:3072
	s_add_u32 s0, s28, 0x80000
	s_addc_u32 s1, s29, 0
	s_mov_b32 m0, s36
	v_lshl_add_u64 v[222:223], s[0:1], 0, v[130:131]
	ds_read_b128 v[178:181], v153 offset:32768
	ds_read_b128 v[182:185], v153 offset:33792
	ds_read_b128 v[186:189], v153 offset:34816
	ds_read_b128 v[190:193], v153 offset:35840
	ds_read_b128 v[194:197], v153 offset:36864
	ds_read_b128 v[198:201], v153 offset:37888
	ds_read_b128 v[208:211], v153 offset:38912
	ds_read_b128 v[212:215], v153 offset:39936
	global_load_lds_dwordx4 v[222:223], off
	v_lshl_add_u64 v[222:223], s[0:1], 0, v[134:135]
	s_mov_b32 m0, s37
	s_nop 0
	global_load_lds_dwordx4 v[222:223], off
	s_waitcnt vmcnt(8)
	s_waitcnt lgkmcnt(0)
	s_setprio 1
	s_barrier
	v_mfma_f32_16x16x32_bf16 v[126:129], v[142:145], v[178:181], v[126:129]
	v_mfma_f32_16x16x32_bf16 v[122:125], v[154:157], v[178:181], v[122:125]
	v_mfma_f32_16x16x32_bf16 v[110:113], v[142:145], v[186:189], v[110:113]
	v_mfma_f32_16x16x32_bf16 v[106:109], v[154:157], v[186:189], v[106:109]
	v_mfma_f32_16x16x32_bf16 v[94:97], v[142:145], v[194:197], v[94:97]
	v_mfma_f32_16x16x32_bf16 v[90:93], v[154:157], v[194:197], v[90:93]
	v_mfma_f32_16x16x32_bf16 v[78:81], v[142:145], v[208:211], v[78:81]
	v_mfma_f32_16x16x32_bf16 v[74:77], v[154:157], v[208:211], v[74:77]
	v_mfma_f32_16x16x32_bf16 v[126:129], v[146:149], v[182:185], v[126:129]
	v_mfma_f32_16x16x32_bf16 v[122:125], v[158:161], v[182:185], v[122:125]
	v_mfma_f32_16x16x32_bf16 v[110:113], v[146:149], v[190:193], v[110:113]
	v_mfma_f32_16x16x32_bf16 v[106:109], v[158:161], v[190:193], v[106:109]
	v_mfma_f32_16x16x32_bf16 v[94:97], v[146:149], v[198:201], v[94:97]
	v_mfma_f32_16x16x32_bf16 v[90:93], v[158:161], v[198:201], v[90:93]
	v_mfma_f32_16x16x32_bf16 v[78:81], v[146:149], v[212:215], v[78:81]
	v_mfma_f32_16x16x32_bf16 v[74:77], v[158:161], v[212:215], v[74:77]
	s_setprio 0
	s_setprio 1
	v_mfma_f32_16x16x32_bf16 v[118:121], v[162:165], v[178:181], v[118:121]
	v_mfma_f32_16x16x32_bf16 v[114:117], v[170:173], v[178:181], v[114:117]
	v_mfma_f32_16x16x32_bf16 v[102:105], v[162:165], v[186:189], v[102:105]
	v_mfma_f32_16x16x32_bf16 v[98:101], v[170:173], v[186:189], v[98:101]
	v_mfma_f32_16x16x32_bf16 v[86:89], v[162:165], v[194:197], v[86:89]
	v_mfma_f32_16x16x32_bf16 v[82:85], v[170:173], v[194:197], v[82:85]
	v_mfma_f32_16x16x32_bf16 v[70:73], v[162:165], v[208:211], v[70:73]
	v_mfma_f32_16x16x32_bf16 v[66:69], v[170:173], v[208:211], v[66:69]
	v_mfma_f32_16x16x32_bf16 v[118:121], v[166:169], v[182:185], v[118:121]
	v_mfma_f32_16x16x32_bf16 v[114:117], v[174:177], v[182:185], v[114:117]
	v_mfma_f32_16x16x32_bf16 v[102:105], v[166:169], v[190:193], v[102:105]
	v_mfma_f32_16x16x32_bf16 v[98:101], v[174:177], v[190:193], v[98:101]
	v_mfma_f32_16x16x32_bf16 v[86:89], v[166:169], v[198:201], v[86:89]
	v_mfma_f32_16x16x32_bf16 v[82:85], v[174:177], v[198:201], v[82:85]
	v_mfma_f32_16x16x32_bf16 v[70:73], v[166:169], v[212:215], v[70:73]
	v_mfma_f32_16x16x32_bf16 v[66:69], v[174:177], v[212:215], v[66:69]
	s_barrier
	s_setprio 0
	s_add_i32 s0, s33, s34
	v_lshl_add_u64 v[204:205], v[204:205], 0, s[80:81]
	s_mov_b32 m0, s0
	ds_read_b128 v[178:181], v153 offset:49152
	ds_read_b128 v[182:185], v153 offset:50176
	ds_read_b128 v[186:189], v153 offset:51200
	ds_read_b128 v[190:193], v153 offset:52224
	ds_read_b128 v[194:197], v153 offset:53248
	ds_read_b128 v[198:201], v153 offset:54272
	ds_read_b128 v[208:211], v153 offset:55296
	ds_read_b128 v[212:215], v153 offset:56320
	global_load_lds_dwordx4 v[204:205], off
	s_add_i32 m0, s0, 0x2000
	s_add_u32 s0, s26, 0x80080
	v_lshl_add_u64 v[204:205], v[216:217], 0, s[80:81]
	s_addc_u32 s1, s27, 0
	s_add_i32 s26, s55, s34
	global_load_lds_dwordx4 v[204:205], off
	v_lshl_add_u64 v[204:205], s[0:1], 0, v[132:133]
	s_mov_b32 m0, s26
	s_nop 0
	global_load_lds_dwordx4 v[204:205], off
	v_lshl_add_u64 v[204:205], s[0:1], 0, v[136:137]
	s_add_i32 m0, s26, 0x2000
	s_nop 0
	global_load_lds_dwordx4 v[204:205], off
	v_lshl_add_u64 v[204:205], v[218:219], 0, s[80:81]
	s_mov_b32 m0, s39
	s_nop 0
	global_load_lds_dwordx4 v[204:205], off
	v_lshl_add_u64 v[204:205], v[220:221], 0, s[80:81]
	s_mov_b32 m0, s40
	s_nop 0
	global_load_lds_dwordx4 v[204:205], off
	s_waitcnt vmcnt(8)
	s_waitcnt lgkmcnt(0)
	s_setprio 1
	s_barrier
	v_mfma_f32_16x16x32_bf16 v[62:65], v[142:145], v[178:181], v[62:65]
	v_mfma_f32_16x16x32_bf16 v[58:61], v[154:157], v[178:181], v[58:61]
	v_mfma_f32_16x16x32_bf16 v[46:49], v[142:145], v[186:189], v[46:49]
	v_mfma_f32_16x16x32_bf16 v[42:45], v[154:157], v[186:189], v[42:45]
	v_mfma_f32_16x16x32_bf16 v[30:33], v[142:145], v[194:197], v[30:33]
	v_mfma_f32_16x16x32_bf16 v[26:29], v[154:157], v[194:197], v[26:29]
	v_mfma_f32_16x16x32_bf16 v[14:17], v[142:145], v[208:211], v[14:17]
	v_mfma_f32_16x16x32_bf16 v[10:13], v[154:157], v[208:211], v[10:13]
	v_mfma_f32_16x16x32_bf16 v[62:65], v[146:149], v[182:185], v[62:65]
	v_mfma_f32_16x16x32_bf16 v[58:61], v[158:161], v[182:185], v[58:61]
	v_mfma_f32_16x16x32_bf16 v[46:49], v[146:149], v[190:193], v[46:49]
	v_mfma_f32_16x16x32_bf16 v[42:45], v[158:161], v[190:193], v[42:45]
	v_mfma_f32_16x16x32_bf16 v[30:33], v[146:149], v[198:201], v[30:33]
	v_mfma_f32_16x16x32_bf16 v[26:29], v[158:161], v[198:201], v[26:29]
	v_mfma_f32_16x16x32_bf16 v[14:17], v[146:149], v[212:215], v[14:17]
	v_mfma_f32_16x16x32_bf16 v[10:13], v[158:161], v[212:215], v[10:13]
	s_setprio 0
	s_setprio 1
	v_mfma_f32_16x16x32_bf16 v[54:57], v[162:165], v[178:181], v[54:57]
	v_mfma_f32_16x16x32_bf16 v[50:53], v[170:173], v[178:181], v[50:53]
	v_mfma_f32_16x16x32_bf16 v[38:41], v[162:165], v[186:189], v[38:41]
	v_mfma_f32_16x16x32_bf16 v[34:37], v[170:173], v[186:189], v[34:37]
	v_mfma_f32_16x16x32_bf16 v[22:25], v[162:165], v[194:197], v[22:25]
	v_mfma_f32_16x16x32_bf16 v[18:21], v[170:173], v[194:197], v[18:21]
	v_mfma_f32_16x16x32_bf16 v[6:9], v[162:165], v[208:211], v[6:9]
	v_mfma_f32_16x16x32_bf16 v[2:5], v[170:173], v[208:211], v[2:5]
	v_mfma_f32_16x16x32_bf16 v[54:57], v[166:169], v[182:185], v[54:57]
	v_mfma_f32_16x16x32_bf16 v[50:53], v[174:177], v[182:185], v[50:53]
	v_mfma_f32_16x16x32_bf16 v[38:41], v[166:169], v[190:193], v[38:41]
	v_mfma_f32_16x16x32_bf16 v[34:37], v[174:177], v[190:193], v[34:37]
	v_mfma_f32_16x16x32_bf16 v[22:25], v[166:169], v[198:201], v[22:25]
	v_mfma_f32_16x16x32_bf16 v[18:21], v[174:177], v[198:201], v[18:21]
	v_mfma_f32_16x16x32_bf16 v[6:9], v[166:169], v[212:215], v[6:9]
	v_mfma_f32_16x16x32_bf16 v[2:5], v[174:177], v[212:215], v[2:5]
	s_barrier
	s_setprio 0
	s_add_i32 s60, s60, 2
	s_add_u32 s24, s24, 0x100
	s_addc_u32 s25, s25, 0
	s_add_u32 s58, s58, 0x100
	s_addc_u32 s59, s59, 0
	s_cmp_gt_u32 s60, 29
	s_cbranch_scc0 .LBB0_394
	s_and_b64 vcc, exec, s[14:15]
	s_cbranch_vccz .LBB0_397
	s_barrier

.LBB0_692:
	ds_read_b128 v[146:149], v239
	ds_read_b128 v[158:161], v239 offset:1024
	ds_read_b128 v[166:169], v239 offset:2048
	ds_read_b128 v[174:177], v239 offset:3072
	ds_read_b128 v[178:181], v239 offset:4096
	ds_read_b128 v[182:185], v239 offset:5120
	ds_read_b128 v[186:189], v239 offset:6144
	ds_read_b128 v[190:193], v239 offset:7168
	s_add_u32 s0, s18, 0xfff00080
	s_addc_u32 s1, s19, -1
	s_add_i32 s33, 0, 0x10000
	s_cmp_eq_u32 s61, 60
	s_cselect_b32 s23, s11, s1
	s_cselect_b32 s22, s49, s0
	s_cselect_b32 s21, s9, s60
	s_cselect_b32 s20, s58, s59
	s_add_i32 s55, 0, 0x14000
	v_add_u32_e32 v98, s33, v205
	v_add_u32_e32 v134, s55, v205
	ds_read_b128 v[78:81], v98
	ds_read_b128 v[86:89], v98 offset:1024
	ds_read_b128 v[94:97], v98 offset:2048
	ds_read_b128 v[98:101], v98 offset:3072
	ds_read_b128 v[106:109], v134
	ds_read_b128 v[110:113], v134 offset:1024
	ds_read_b128 v[126:129], v134 offset:2048
	ds_read_b128 v[134:137], v134 offset:3072
	v_lshl_add_u64 v[194:195], s[18:19], 0, v[214:215]
	s_add_i32 m0, s27, 0xc000
	global_load_lds_dwordx4 v[194:195], off
	v_lshl_add_u64 v[194:195], s[18:19], 0, v[216:217]
	s_add_i32 m0, s27, 0xe000
	s_nop 0
	global_load_lds_dwordx4 v[194:195], off
	s_waitcnt vmcnt(8)
	s_waitcnt lgkmcnt(0)
	s_setprio 1
	s_barrier
	v_mfma_f32_16x16x32_bf16 v[170:173], v[78:81], v[146:149], v[170:173]
	v_mfma_f32_16x16x32_bf16 v[162:165], v[94:97], v[146:149], v[162:165]
	v_mfma_f32_16x16x32_bf16 v[142:145], v[78:81], v[166:169], v[142:145]
	v_mfma_f32_16x16x32_bf16 v[138:141], v[94:97], v[166:169], v[138:141]
	v_mfma_f32_16x16x32_bf16 v[118:121], v[78:81], v[178:181], v[118:121]
	v_mfma_f32_16x16x32_bf16 v[114:117], v[94:97], v[178:181], v[114:117]
	v_mfma_f32_16x16x32_bf16 v[82:85], v[78:81], v[186:189], v[82:85]
	v_mfma_f32_16x16x32_bf16 v[74:77], v[94:97], v[186:189], v[74:77]
	v_mfma_f32_16x16x32_bf16 v[170:173], v[86:89], v[158:161], v[170:173]
	v_mfma_f32_16x16x32_bf16 v[162:165], v[98:101], v[158:161], v[162:165]
	v_mfma_f32_16x16x32_bf16 v[142:145], v[86:89], v[174:177], v[142:145]
	v_mfma_f32_16x16x32_bf16 v[138:141], v[98:101], v[174:177], v[138:141]
	v_mfma_f32_16x16x32_bf16 v[118:121], v[86:89], v[182:185], v[118:121]
	v_mfma_f32_16x16x32_bf16 v[114:117], v[98:101], v[182:185], v[114:117]
	v_mfma_f32_16x16x32_bf16 v[82:85], v[86:89], v[190:193], v[82:85]
	v_mfma_f32_16x16x32_bf16 v[74:77], v[98:101], v[190:193], v[74:77]
	s_setprio 0
	s_setprio 1
	v_mfma_f32_16x16x32_bf16 v[154:157], v[106:109], v[146:149], v[154:157]
	v_mfma_f32_16x16x32_bf16 v[130:133], v[106:109], v[166:169], v[130:133]
	v_mfma_f32_16x16x32_bf16 v[122:125], v[126:129], v[166:169], v[122:125]
	v_mfma_f32_16x16x32_bf16 v[102:105], v[106:109], v[178:181], v[102:105]
	v_mfma_f32_16x16x32_bf16 v[90:93], v[126:129], v[178:181], v[90:93]
	v_mfma_f32_16x16x32_bf16 v[70:73], v[106:109], v[186:189], v[70:73]
	v_mfma_f32_16x16x32_bf16 v[66:69], v[126:129], v[186:189], v[66:69]
	v_mfma_f32_16x16x32_bf16 v[154:157], v[110:113], v[158:161], v[154:157]
	v_mfma_f32_16x16x32_bf16 v[146:149], v[126:129], v[146:149], v[150:153]
	v_mfma_f32_16x16x32_bf16 v[130:133], v[110:113], v[174:177], v[130:133]
	v_mfma_f32_16x16x32_bf16 v[122:125], v[134:137], v[174:177], v[122:125]
	v_mfma_f32_16x16x32_bf16 v[102:105], v[110:113], v[182:185], v[102:105]
	v_mfma_f32_16x16x32_bf16 v[90:93], v[134:137], v[182:185], v[90:93]
	v_mfma_f32_16x16x32_bf16 v[70:73], v[110:113], v[190:193], v[70:73]
	v_mfma_f32_16x16x32_bf16 v[66:69], v[134:137], v[190:193], v[66:69]
	v_mfma_f32_16x16x32_bf16 v[146:149], v[134:137], v[158:161], v[146:149]
	s_barrier
	s_setprio 0
	s_add_i32 s0, s33, s26
	v_lshl_add_u64 v[194:195], s[20:21], 0, v[202:203]
	s_mov_b32 m0, s0
	ds_read_b128 v[150:153], v239 offset:16384
	ds_read_b128 v[158:161], v239 offset:17408
	ds_read_b128 v[166:169], v239 offset:18432
	ds_read_b128 v[174:177], v239 offset:19456
	ds_read_b128 v[178:181], v239 offset:20480
	ds_read_b128 v[182:185], v239 offset:21504
	ds_read_b128 v[186:189], v239 offset:22528
	ds_read_b128 v[190:193], v239 offset:23552
	global_load_lds_dwordx4 v[194:195], off
	s_add_i32 m0, s0, 0x2000
	s_add_u32 s0, s20, 0x100000
	v_lshl_add_u64 v[196:197], s[20:21], 0, v[208:209]
	s_addc_u32 s1, s21, 0
	s_add_i32 s33, s55, s26
	global_load_lds_dwordx4 v[196:197], off
	v_lshl_add_u64 v[198:199], s[0:1], 0, v[202:203]
	s_mov_b32 m0, s33
	v_lshl_add_u64 v[200:201], s[22:23], 0, v[210:211]
	global_load_lds_dwordx4 v[198:199], off
	v_lshl_add_u64 v[198:199], s[0:1], 0, v[208:209]
	s_add_i32 m0, s33, 0x2000
	s_nop 0
	global_load_lds_dwordx4 v[198:199], off
	v_lshl_add_u64 v[198:199], s[22:23], 0, v[212:213]
	s_mov_b32 m0, s27
	s_nop 0
	global_load_lds_dwordx4 v[198:199], off
	s_mov_b32 m0, s28
	s_nop 0
	global_load_lds_dwordx4 v[200:201], off
	s_waitcnt vmcnt(8)
	s_waitcnt lgkmcnt(0)
	s_setprio 1
	s_barrier
	v_mfma_f32_16x16x32_bf16 v[62:65], v[78:81], v[150:153], v[62:65]
	v_mfma_f32_16x16x32_bf16 v[58:61], v[94:97], v[150:153], v[58:61]
	v_mfma_f32_16x16x32_bf16 v[46:49], v[78:81], v[166:169], v[46:49]
	v_mfma_f32_16x16x32_bf16 v[42:45], v[94:97], v[166:169], v[42:45]
	v_mfma_f32_16x16x32_bf16 v[30:33], v[78:81], v[178:181], v[30:33]
	v_mfma_f32_16x16x32_bf16 v[26:29], v[94:97], v[178:181], v[26:29]
	v_mfma_f32_16x16x32_bf16 v[14:17], v[78:81], v[186:189], v[14:17]
	v_mfma_f32_16x16x32_bf16 v[10:13], v[94:97], v[186:189], v[10:13]
	v_mfma_f32_16x16x32_bf16 v[62:65], v[86:89], v[158:161], v[62:65]
	v_mfma_f32_16x16x32_bf16 v[58:61], v[98:101], v[158:161], v[58:61]
	v_mfma_f32_16x16x32_bf16 v[46:49], v[86:89], v[174:177], v[46:49]
	v_mfma_f32_16x16x32_bf16 v[42:45], v[98:101], v[174:177], v[42:45]
	v_mfma_f32_16x16x32_bf16 v[30:33], v[86:89], v[182:185], v[30:33]
	v_mfma_f32_16x16x32_bf16 v[26:29], v[98:101], v[182:185], v[26:29]
	v_mfma_f32_16x16x32_bf16 v[14:17], v[86:89], v[190:193], v[14:17]
	v_mfma_f32_16x16x32_bf16 v[10:13], v[98:101], v[190:193], v[10:13]
	s_setprio 0
	s_setprio 1
	v_mfma_f32_16x16x32_bf16 v[54:57], v[106:109], v[150:153], v[54:57]
	v_mfma_f32_16x16x32_bf16 v[50:53], v[126:129], v[150:153], v[50:53]
	v_mfma_f32_16x16x32_bf16 v[38:41], v[106:109], v[166:169], v[38:41]
	v_mfma_f32_16x16x32_bf16 v[34:37], v[126:129], v[166:169], v[34:37]
	v_mfma_f32_16x16x32_bf16 v[22:25], v[106:109], v[178:181], v[22:25]
	v_mfma_f32_16x16x32_bf16 v[18:21], v[126:129], v[178:181], v[18:21]
	v_mfma_f32_16x16x32_bf16 v[6:9], v[106:109], v[186:189], v[6:9]
	v_mfma_f32_16x16x32_bf16 v[2:5], v[126:129], v[186:189], v[2:5]
	v_mfma_f32_16x16x32_bf16 v[54:57], v[110:113], v[158:161], v[54:57]
	v_mfma_f32_16x16x32_bf16 v[50:53], v[134:137], v[158:161], v[50:53]
	v_mfma_f32_16x16x32_bf16 v[38:41], v[110:113], v[174:177], v[38:41]
	v_mfma_f32_16x16x32_bf16 v[34:37], v[134:137], v[174:177], v[34:37]
	v_mfma_f32_16x16x32_bf16 v[22:25], v[110:113], v[182:185], v[22:25]
	v_mfma_f32_16x16x32_bf16 v[18:21], v[134:137], v[182:185], v[18:21]
	v_mfma_f32_16x16x32_bf16 v[6:9], v[110:113], v[190:193], v[6:9]
	v_mfma_f32_16x16x32_bf16 v[2:5], v[134:137], v[190:193], v[2:5]
	s_barrier
	s_setprio 0
	s_add_i32 s33, 0, 0x18000
	s_add_i32 s55, 0, 0x1c000
	v_add_u32_e32 v98, s33, v205
	v_add_u32_e32 v134, s55, v205
	ds_read_b128 v[78:81], v98
	ds_read_b128 v[86:89], v98 offset:1024
	ds_read_b128 v[94:97], v98 offset:2048
	ds_read_b128 v[98:101], v98 offset:3072
	ds_read_b128 v[106:109], v134
	ds_read_b128 v[110:113], v134 offset:1024
	ds_read_b128 v[126:129], v134 offset:2048
	ds_read_b128 v[134:137], v134 offset:3072
	s_add_u32 s0, s22, 0x100000
	s_addc_u32 s1, s23, 0
	s_mov_b32 m0, s29
	v_lshl_add_u64 v[206:207], s[0:1], 0, v[212:213]
	ds_read_b128 v[150:153], v239 offset:32768
	ds_read_b128 v[158:161], v239 offset:33792
	ds_read_b128 v[166:169], v239 offset:34816
	ds_read_b128 v[174:177], v239 offset:35840
	ds_read_b128 v[178:181], v239 offset:36864
	ds_read_b128 v[182:185], v239 offset:37888
	ds_read_b128 v[186:189], v239 offset:38912
	ds_read_b128 v[190:193], v239 offset:39936
	global_load_lds_dwordx4 v[206:207], off
	v_lshl_add_u64 v[206:207], s[0:1], 0, v[210:211]
	s_mov_b32 m0, s30
	s_nop 0
	global_load_lds_dwordx4 v[206:207], off
	s_waitcnt vmcnt(8)
	s_waitcnt lgkmcnt(0)
	s_setprio 1
	s_barrier
	v_mfma_f32_16x16x32_bf16 v[170:173], v[78:81], v[150:153], v[170:173]
	v_mfma_f32_16x16x32_bf16 v[162:165], v[94:97], v[150:153], v[162:165]
	v_mfma_f32_16x16x32_bf16 v[142:145], v[78:81], v[166:169], v[142:145]
	v_mfma_f32_16x16x32_bf16 v[138:141], v[94:97], v[166:169], v[138:141]
	v_mfma_f32_16x16x32_bf16 v[118:121], v[78:81], v[178:181], v[118:121]
	v_mfma_f32_16x16x32_bf16 v[114:117], v[94:97], v[178:181], v[114:117]
	v_mfma_f32_16x16x32_bf16 v[82:85], v[78:81], v[186:189], v[82:85]
	v_mfma_f32_16x16x32_bf16 v[74:77], v[94:97], v[186:189], v[74:77]
	v_mfma_f32_16x16x32_bf16 v[170:173], v[86:89], v[158:161], v[170:173]
	v_mfma_f32_16x16x32_bf16 v[162:165], v[98:101], v[158:161], v[162:165]
	v_mfma_f32_16x16x32_bf16 v[142:145], v[86:89], v[174:177], v[142:145]
	v_mfma_f32_16x16x32_bf16 v[138:141], v[98:101], v[174:177], v[138:141]
	v_mfma_f32_16x16x32_bf16 v[118:121], v[86:89], v[182:185], v[118:121]
	v_mfma_f32_16x16x32_bf16 v[114:117], v[98:101], v[182:185], v[114:117]
	v_mfma_f32_16x16x32_bf16 v[82:85], v[86:89], v[190:193], v[82:85]
	v_mfma_f32_16x16x32_bf16 v[74:77], v[98:101], v[190:193], v[74:77]
	s_setprio 0
	s_setprio 1
	v_mfma_f32_16x16x32_bf16 v[154:157], v[106:109], v[150:153], v[154:157]
	v_mfma_f32_16x16x32_bf16 v[146:149], v[126:129], v[150:153], v[146:149]
	v_mfma_f32_16x16x32_bf16 v[130:133], v[106:109], v[166:169], v[130:133]
	v_mfma_f32_16x16x32_bf16 v[122:125], v[126:129], v[166:169], v[122:125]
	v_mfma_f32_16x16x32_bf16 v[102:105], v[106:109], v[178:181], v[102:105]
	v_mfma_f32_16x16x32_bf16 v[90:93], v[126:129], v[178:181], v[90:93]
	v_mfma_f32_16x16x32_bf16 v[70:73], v[106:109], v[186:189], v[70:73]
	v_mfma_f32_16x16x32_bf16 v[66:69], v[126:129], v[186:189], v[66:69]
	v_mfma_f32_16x16x32_bf16 v[154:157], v[110:113], v[158:161], v[154:157]
	v_mfma_f32_16x16x32_bf16 v[150:153], v[134:137], v[158:161], v[146:149]
	v_mfma_f32_16x16x32_bf16 v[130:133], v[110:113], v[174:177], v[130:133]
	v_mfma_f32_16x16x32_bf16 v[122:125], v[134:137], v[174:177], v[122:125]
	v_mfma_f32_16x16x32_bf16 v[102:105], v[110:113], v[182:185], v[102:105]
	v_mfma_f32_16x16x32_bf16 v[90:93], v[134:137], v[182:185], v[90:93]
	v_mfma_f32_16x16x32_bf16 v[70:73], v[110:113], v[190:193], v[70:73]
	v_mfma_f32_16x16x32_bf16 v[66:69], v[134:137], v[190:193], v[66:69]
	s_barrier
	s_setprio 0
	s_add_i32 s0, s33, s26
	v_lshl_add_u64 v[194:195], v[194:195], 0, s[80:81]
	s_mov_b32 m0, s0
	ds_read_b128 v[146:149], v239 offset:49152
	ds_read_b128 v[158:161], v239 offset:50176
	ds_read_b128 v[166:169], v239 offset:51200
	ds_read_b128 v[174:177], v239 offset:52224
	ds_read_b128 v[178:181], v239 offset:53248
	ds_read_b128 v[182:185], v239 offset:54272
	ds_read_b128 v[186:189], v239 offset:55296
	ds_read_b128 v[190:193], v239 offset:56320
	global_load_lds_dwordx4 v[194:195], off
	s_add_i32 m0, s0, 0x2000
	s_add_u32 s0, s20, 0x100080
	v_lshl_add_u64 v[194:195], v[196:197], 0, s[80:81]
	s_addc_u32 s1, s21, 0
	s_add_i32 s20, s55, s26
	global_load_lds_dwordx4 v[194:195], off
	v_lshl_add_u64 v[194:195], s[0:1], 0, v[202:203]
	s_mov_b32 m0, s20
	s_nop 0
	global_load_lds_dwordx4 v[194:195], off
	v_lshl_add_u64 v[194:195], s[0:1], 0, v[208:209]
	s_add_i32 m0, s20, 0x2000
	s_nop 0
	global_load_lds_dwordx4 v[194:195], off
	v_lshl_add_u64 v[194:195], v[198:199], 0, s[80:81]
	s_mov_b32 m0, s35
	s_nop 0
	global_load_lds_dwordx4 v[194:195], off
	v_lshl_add_u64 v[194:195], v[200:201], 0, s[80:81]
	s_mov_b32 m0, s36
	s_nop 0
	global_load_lds_dwordx4 v[194:195], off
	s_waitcnt vmcnt(8)
	s_waitcnt lgkmcnt(0)
	s_setprio 1
	s_barrier
	v_mfma_f32_16x16x32_bf16 v[62:65], v[78:81], v[146:149], v[62:65]
	v_mfma_f32_16x16x32_bf16 v[58:61], v[94:97], v[146:149], v[58:61]
	v_mfma_f32_16x16x32_bf16 v[46:49], v[78:81], v[166:169], v[46:49]
	v_mfma_f32_16x16x32_bf16 v[42:45], v[94:97], v[166:169], v[42:45]
	v_mfma_f32_16x16x32_bf16 v[30:33], v[78:81], v[178:181], v[30:33]
	v_mfma_f32_16x16x32_bf16 v[26:29], v[94:97], v[178:181], v[26:29]
	v_mfma_f32_16x16x32_bf16 v[14:17], v[78:81], v[186:189], v[14:17]
	v_mfma_f32_16x16x32_bf16 v[10:13], v[94:97], v[186:189], v[10:13]
	v_mfma_f32_16x16x32_bf16 v[62:65], v[86:89], v[158:161], v[62:65]
	v_mfma_f32_16x16x32_bf16 v[58:61], v[98:101], v[158:161], v[58:61]
	v_mfma_f32_16x16x32_bf16 v[46:49], v[86:89], v[174:177], v[46:49]
	v_mfma_f32_16x16x32_bf16 v[42:45], v[98:101], v[174:177], v[42:45]
	v_mfma_f32_16x16x32_bf16 v[30:33], v[86:89], v[182:185], v[30:33]
	v_mfma_f32_16x16x32_bf16 v[26:29], v[98:101], v[182:185], v[26:29]
	v_mfma_f32_16x16x32_bf16 v[14:17], v[86:89], v[190:193], v[14:17]
	v_mfma_f32_16x16x32_bf16 v[10:13], v[98:101], v[190:193], v[10:13]
	s_setprio 0
	s_setprio 1
	v_mfma_f32_16x16x32_bf16 v[54:57], v[106:109], v[146:149], v[54:57]
	v_mfma_f32_16x16x32_bf16 v[50:53], v[126:129], v[146:149], v[50:53]
	v_mfma_f32_16x16x32_bf16 v[38:41], v[106:109], v[166:169], v[38:41]
	v_mfma_f32_16x16x32_bf16 v[34:37], v[126:129], v[166:169], v[34:37]
	v_mfma_f32_16x16x32_bf16 v[22:25], v[106:109], v[178:181], v[22:25]
	v_mfma_f32_16x16x32_bf16 v[18:21], v[126:129], v[178:181], v[18:21]
	v_mfma_f32_16x16x32_bf16 v[6:9], v[106:109], v[186:189], v[6:9]
	v_mfma_f32_16x16x32_bf16 v[2:5], v[126:129], v[186:189], v[2:5]
	v_mfma_f32_16x16x32_bf16 v[54:57], v[110:113], v[158:161], v[54:57]
	v_mfma_f32_16x16x32_bf16 v[50:53], v[134:137], v[158:161], v[50:53]
	v_mfma_f32_16x16x32_bf16 v[38:41], v[110:113], v[174:177], v[38:41]
	v_mfma_f32_16x16x32_bf16 v[34:37], v[134:137], v[174:177], v[34:37]
	v_mfma_f32_16x16x32_bf16 v[22:25], v[110:113], v[182:185], v[22:25]
	v_mfma_f32_16x16x32_bf16 v[18:21], v[134:137], v[182:185], v[18:21]
	v_mfma_f32_16x16x32_bf16 v[6:9], v[110:113], v[190:193], v[6:9]
	v_mfma_f32_16x16x32_bf16 v[2:5], v[134:137], v[190:193], v[2:5]
	s_barrier
	s_setprio 0
	s_add_i32 s61, s61, 2
	s_add_u32 s18, s18, 0x100
	s_addc_u32 s19, s19, 0
	s_add_u32 s59, s59, 0x100
	s_addc_u32 s60, s60, 0
	s_cmp_gt_u32 s61, 61
	s_cbranch_scc0 .LBB0_692
	s_and_b64 vcc, exec, s[6:7]
	s_cbranch_vccz .LBB0_695
	s_barrier

.LBB0_712:
	ds_read_b128 v[172:175], v139
	ds_read_b128 v[176:179], v139 offset:1024
	ds_read_b128 v[180:183], v139 offset:2048
	ds_read_b128 v[184:187], v139 offset:3072
	ds_read_b128 v[188:191], v139 offset:4096
	ds_read_b128 v[192:195], v139 offset:5120
	ds_read_b128 v[196:199], v139 offset:6144
	ds_read_b128 v[208:211], v139 offset:7168
	s_add_u32 s0, s18, 0xfff00080
	s_addc_u32 s1, s19, -1
	s_add_i32 s33, 0, 0x10000
	s_cmp_eq_u32 s49, 4
	s_cselect_b32 s23, s15, s1
	s_cselect_b32 s22, s14, s0
	s_cselect_b32 s21, s17, s11
	s_cselect_b32 s20, s16, s9
	s_add_i32 s55, 0, 0x14000
	v_add_u32_e32 v152, s33, v136
	v_add_u32_e32 v168, s55, v136
	ds_read_b128 v[140:143], v152
	ds_read_b128 v[144:147], v152 offset:1024
	ds_read_b128 v[148:151], v152 offset:2048
	ds_read_b128 v[152:155], v152 offset:3072
	ds_read_b128 v[156:159], v168
	ds_read_b128 v[160:163], v168 offset:1024
	ds_read_b128 v[164:167], v168 offset:2048
	ds_read_b128 v[168:171], v168 offset:3072
	v_lshl_add_u64 v[200:201], s[18:19], 0, v[132:133]
	s_add_i32 m0, s27, 0xc000
	global_load_lds_dwordx4 v[200:201], off
	v_lshl_add_u64 v[200:201], s[18:19], 0, v[134:135]
	s_add_i32 m0, s27, 0xe000
	s_nop 0
	global_load_lds_dwordx4 v[200:201], off
	s_waitcnt vmcnt(8)
	s_waitcnt lgkmcnt(0)
	s_setprio 1
	s_barrier
	v_mfma_f32_16x16x32_bf16 v[126:129], v[140:143], v[172:175], v[126:129]
	v_mfma_f32_16x16x32_bf16 v[122:125], v[148:151], v[172:175], v[122:125]
	v_mfma_f32_16x16x32_bf16 v[118:121], v[140:143], v[180:183], v[118:121]
	v_mfma_f32_16x16x32_bf16 v[114:117], v[148:151], v[180:183], v[114:117]
	v_mfma_f32_16x16x32_bf16 v[106:109], v[140:143], v[188:191], v[106:109]
	v_mfma_f32_16x16x32_bf16 v[98:101], v[148:151], v[188:191], v[98:101]
	v_mfma_f32_16x16x32_bf16 v[90:93], v[140:143], v[196:199], v[90:93]
	v_mfma_f32_16x16x32_bf16 v[82:85], v[148:151], v[196:199], v[82:85]
	v_mfma_f32_16x16x32_bf16 v[126:129], v[144:147], v[176:179], v[126:129]
	v_mfma_f32_16x16x32_bf16 v[122:125], v[152:155], v[176:179], v[122:125]
	v_mfma_f32_16x16x32_bf16 v[118:121], v[144:147], v[184:187], v[118:121]
	v_mfma_f32_16x16x32_bf16 v[114:117], v[152:155], v[184:187], v[114:117]
	v_mfma_f32_16x16x32_bf16 v[106:109], v[144:147], v[192:195], v[106:109]
	v_mfma_f32_16x16x32_bf16 v[98:101], v[152:155], v[192:195], v[98:101]
	v_mfma_f32_16x16x32_bf16 v[90:93], v[144:147], v[208:211], v[90:93]
	v_mfma_f32_16x16x32_bf16 v[82:85], v[152:155], v[208:211], v[82:85]
	s_setprio 0
	s_setprio 1
	v_mfma_f32_16x16x32_bf16 v[110:113], v[156:159], v[172:175], v[110:113]
	v_mfma_f32_16x16x32_bf16 v[102:105], v[164:167], v[172:175], v[102:105]
	v_mfma_f32_16x16x32_bf16 v[94:97], v[156:159], v[180:183], v[94:97]
	v_mfma_f32_16x16x32_bf16 v[86:89], v[164:167], v[180:183], v[86:89]
	v_mfma_f32_16x16x32_bf16 v[78:81], v[156:159], v[188:191], v[78:81]
	v_mfma_f32_16x16x32_bf16 v[74:77], v[164:167], v[188:191], v[74:77]
	v_mfma_f32_16x16x32_bf16 v[70:73], v[156:159], v[196:199], v[70:73]
	v_mfma_f32_16x16x32_bf16 v[66:69], v[164:167], v[196:199], v[66:69]
	v_mfma_f32_16x16x32_bf16 v[110:113], v[160:163], v[176:179], v[110:113]
	v_mfma_f32_16x16x32_bf16 v[102:105], v[168:171], v[176:179], v[102:105]
	v_mfma_f32_16x16x32_bf16 v[94:97], v[160:163], v[184:187], v[94:97]
	v_mfma_f32_16x16x32_bf16 v[86:89], v[168:171], v[184:187], v[86:89]
	v_mfma_f32_16x16x32_bf16 v[78:81], v[160:163], v[192:195], v[78:81]
	v_mfma_f32_16x16x32_bf16 v[74:77], v[168:171], v[192:195], v[74:77]
	v_mfma_f32_16x16x32_bf16 v[70:73], v[160:163], v[208:211], v[70:73]
	v_mfma_f32_16x16x32_bf16 v[66:69], v[168:171], v[208:211], v[66:69]
	s_barrier
	s_setprio 0
	s_add_i32 s0, s33, s26
	v_lshl_add_u64 v[200:201], s[20:21], 0, v[202:203]
	s_mov_b32 m0, s0
	ds_read_b128 v[172:175], v139 offset:16384
	ds_read_b128 v[176:179], v139 offset:17408
	ds_read_b128 v[180:183], v139 offset:18432
	ds_read_b128 v[184:187], v139 offset:19456
	ds_read_b128 v[188:191], v139 offset:20480
	ds_read_b128 v[192:195], v139 offset:21504
	ds_read_b128 v[196:199], v139 offset:22528
	ds_read_b128 v[208:211], v139 offset:23552
	global_load_lds_dwordx4 v[200:201], off
	s_add_i32 m0, s0, 0x2000
	s_add_u32 s0, s20, 0x100000
	v_lshl_add_u64 v[204:205], s[20:21], 0, v[130:131]
	s_addc_u32 s1, s21, 0
	s_add_i32 s33, s55, s26
	global_load_lds_dwordx4 v[204:205], off
	v_lshl_add_u64 v[206:207], s[0:1], 0, v[202:203]
	s_mov_b32 m0, s33
	v_lshl_add_u64 v[212:213], s[22:23], 0, v[130:131]
	global_load_lds_dwordx4 v[206:207], off
	v_lshl_add_u64 v[206:207], s[0:1], 0, v[130:131]
	s_add_i32 m0, s33, 0x2000
	s_nop 0
	global_load_lds_dwordx4 v[206:207], off
	v_lshl_add_u64 v[206:207], s[22:23], 0, v[202:203]
	s_mov_b32 m0, s27
	s_nop 0
	global_load_lds_dwordx4 v[206:207], off
	s_mov_b32 m0, s28
	s_nop 0
	global_load_lds_dwordx4 v[212:213], off
	s_waitcnt vmcnt(8)
	s_waitcnt lgkmcnt(0)
	s_setprio 1
	s_barrier
	v_mfma_f32_16x16x32_bf16 v[62:65], v[140:143], v[172:175], v[62:65]
	v_mfma_f32_16x16x32_bf16 v[58:61], v[148:151], v[172:175], v[58:61]
	v_mfma_f32_16x16x32_bf16 v[54:57], v[140:143], v[180:183], v[54:57]
	v_mfma_f32_16x16x32_bf16 v[50:53], v[148:151], v[180:183], v[50:53]
	v_mfma_f32_16x16x32_bf16 v[38:41], v[140:143], v[188:191], v[38:41]
	v_mfma_f32_16x16x32_bf16 v[34:37], v[148:151], v[188:191], v[34:37]
	v_mfma_f32_16x16x32_bf16 v[22:25], v[140:143], v[196:199], v[22:25]
	v_mfma_f32_16x16x32_bf16 v[18:21], v[148:151], v[196:199], v[18:21]
	v_mfma_f32_16x16x32_bf16 v[62:65], v[144:147], v[176:179], v[62:65]
	v_mfma_f32_16x16x32_bf16 v[58:61], v[152:155], v[176:179], v[58:61]
	v_mfma_f32_16x16x32_bf16 v[54:57], v[144:147], v[184:187], v[54:57]
	v_mfma_f32_16x16x32_bf16 v[50:53], v[152:155], v[184:187], v[50:53]
	v_mfma_f32_16x16x32_bf16 v[38:41], v[144:147], v[192:195], v[38:41]
	v_mfma_f32_16x16x32_bf16 v[34:37], v[152:155], v[192:195], v[34:37]
	v_mfma_f32_16x16x32_bf16 v[22:25], v[144:147], v[208:211], v[22:25]
	v_mfma_f32_16x16x32_bf16 v[18:21], v[152:155], v[208:211], v[18:21]
	s_setprio 0
	s_setprio 1
	v_mfma_f32_16x16x32_bf16 v[46:49], v[156:159], v[172:175], v[46:49]
	v_mfma_f32_16x16x32_bf16 v[42:45], v[164:167], v[172:175], v[42:45]
	v_mfma_f32_16x16x32_bf16 v[30:33], v[156:159], v[180:183], v[30:33]
	v_mfma_f32_16x16x32_bf16 v[26:29], v[164:167], v[180:183], v[26:29]
	v_mfma_f32_16x16x32_bf16 v[14:17], v[156:159], v[188:191], v[14:17]
	v_mfma_f32_16x16x32_bf16 v[10:13], v[164:167], v[188:191], v[10:13]
	v_mfma_f32_16x16x32_bf16 v[6:9], v[156:159], v[196:199], v[6:9]
	v_mfma_f32_16x16x32_bf16 v[2:5], v[164:167], v[196:199], v[2:5]
	v_mfma_f32_16x16x32_bf16 v[46:49], v[160:163], v[176:179], v[46:49]
	v_mfma_f32_16x16x32_bf16 v[42:45], v[168:171], v[176:179], v[42:45]
	v_mfma_f32_16x16x32_bf16 v[30:33], v[160:163], v[184:187], v[30:33]
	v_mfma_f32_16x16x32_bf16 v[26:29], v[168:171], v[184:187], v[26:29]
	v_mfma_f32_16x16x32_bf16 v[14:17], v[160:163], v[192:195], v[14:17]
	v_mfma_f32_16x16x32_bf16 v[10:13], v[168:171], v[192:195], v[10:13]
	v_mfma_f32_16x16x32_bf16 v[6:9], v[160:163], v[208:211], v[6:9]
	v_mfma_f32_16x16x32_bf16 v[2:5], v[168:171], v[208:211], v[2:5]
	s_barrier
	s_setprio 0
	s_add_i32 s33, 0, 0x18000
	s_add_i32 s55, 0, 0x1c000
	v_add_u32_e32 v152, s33, v136
	v_add_u32_e32 v168, s55, v136
	ds_read_b128 v[140:143], v152
	ds_read_b128 v[144:147], v152 offset:1024
	ds_read_b128 v[148:151], v152 offset:2048
	ds_read_b128 v[152:155], v152 offset:3072
	ds_read_b128 v[156:159], v168
	ds_read_b128 v[160:163], v168 offset:1024
	ds_read_b128 v[164:167], v168 offset:2048
	ds_read_b128 v[168:171], v168 offset:3072
	s_add_u32 s0, s22, 0x100000
	s_addc_u32 s1, s23, 0
	s_mov_b32 m0, s29
	v_lshl_add_u64 v[214:215], s[0:1], 0, v[202:203]
	ds_read_b128 v[172:175], v139 offset:32768
	ds_read_b128 v[176:179], v139 offset:33792
	ds_read_b128 v[180:183], v139 offset:34816
	ds_read_b128 v[184:187], v139 offset:35840
	ds_read_b128 v[188:191], v139 offset:36864
	ds_read_b128 v[192:195], v139 offset:37888
	ds_read_b128 v[196:199], v139 offset:38912
	ds_read_b128 v[208:211], v139 offset:39936
	global_load_lds_dwordx4 v[214:215], off
	v_lshl_add_u64 v[214:215], s[0:1], 0, v[130:131]
	s_mov_b32 m0, s30
	s_nop 0
	global_load_lds_dwordx4 v[214:215], off
	s_waitcnt vmcnt(8)
	s_waitcnt lgkmcnt(0)
	s_setprio 1
	s_barrier
	v_mfma_f32_16x16x32_bf16 v[126:129], v[140:143], v[172:175], v[126:129]
	v_mfma_f32_16x16x32_bf16 v[122:125], v[148:151], v[172:175], v[122:125]
	v_mfma_f32_16x16x32_bf16 v[118:121], v[140:143], v[180:183], v[118:121]
	v_mfma_f32_16x16x32_bf16 v[114:117], v[148:151], v[180:183], v[114:117]
	v_mfma_f32_16x16x32_bf16 v[106:109], v[140:143], v[188:191], v[106:109]
	v_mfma_f32_16x16x32_bf16 v[98:101], v[148:151], v[188:191], v[98:101]
	v_mfma_f32_16x16x32_bf16 v[90:93], v[140:143], v[196:199], v[90:93]
	v_mfma_f32_16x16x32_bf16 v[82:85], v[148:151], v[196:199], v[82:85]
	v_mfma_f32_16x16x32_bf16 v[126:129], v[144:147], v[176:179], v[126:129]
	v_mfma_f32_16x16x32_bf16 v[122:125], v[152:155], v[176:179], v[122:125]
	v_mfma_f32_16x16x32_bf16 v[118:121], v[144:147], v[184:187], v[118:121]
	v_mfma_f32_16x16x32_bf16 v[114:117], v[152:155], v[184:187], v[114:117]
	v_mfma_f32_16x16x32_bf16 v[106:109], v[144:147], v[192:195], v[106:109]
	v_mfma_f32_16x16x32_bf16 v[98:101], v[152:155], v[192:195], v[98:101]
	v_mfma_f32_16x16x32_bf16 v[90:93], v[144:147], v[208:211], v[90:93]
	v_mfma_f32_16x16x32_bf16 v[82:85], v[152:155], v[208:211], v[82:85]
	s_setprio 0
	s_setprio 1
	v_mfma_f32_16x16x32_bf16 v[110:113], v[156:159], v[172:175], v[110:113]
	v_mfma_f32_16x16x32_bf16 v[102:105], v[164:167], v[172:175], v[102:105]
	v_mfma_f32_16x16x32_bf16 v[94:97], v[156:159], v[180:183], v[94:97]
	v_mfma_f32_16x16x32_bf16 v[86:89], v[164:167], v[180:183], v[86:89]
	v_mfma_f32_16x16x32_bf16 v[78:81], v[156:159], v[188:191], v[78:81]
	v_mfma_f32_16x16x32_bf16 v[74:77], v[164:167], v[188:191], v[74:77]
	v_mfma_f32_16x16x32_bf16 v[70:73], v[156:159], v[196:199], v[70:73]
	v_mfma_f32_16x16x32_bf16 v[66:69], v[164:167], v[196:199], v[66:69]
	v_mfma_f32_16x16x32_bf16 v[110:113], v[160:163], v[176:179], v[110:113]
	v_mfma_f32_16x16x32_bf16 v[102:105], v[168:171], v[176:179], v[102:105]
	v_mfma_f32_16x16x32_bf16 v[94:97], v[160:163], v[184:187], v[94:97]
	v_mfma_f32_16x16x32_bf16 v[86:89], v[168:171], v[184:187], v[86:89]
	v_mfma_f32_16x16x32_bf16 v[78:81], v[160:163], v[192:195], v[78:81]
	v_mfma_f32_16x16x32_bf16 v[74:77], v[168:171], v[192:195], v[74:77]
	v_mfma_f32_16x16x32_bf16 v[70:73], v[160:163], v[208:211], v[70:73]
	v_mfma_f32_16x16x32_bf16 v[66:69], v[168:171], v[208:211], v[66:69]
	s_barrier
	s_setprio 0
	s_add_i32 s0, s33, s26
	v_lshl_add_u64 v[200:201], v[200:201], 0, s[80:81]
	s_mov_b32 m0, s0
	ds_read_b128 v[172:175], v139 offset:49152
	ds_read_b128 v[176:179], v139 offset:50176
	ds_read_b128 v[180:183], v139 offset:51200
	ds_read_b128 v[184:187], v139 offset:52224
	ds_read_b128 v[188:191], v139 offset:53248
	ds_read_b128 v[192:195], v139 offset:54272
	ds_read_b128 v[196:199], v139 offset:55296
	ds_read_b128 v[208:211], v139 offset:56320
	global_load_lds_dwordx4 v[200:201], off
	s_add_i32 m0, s0, 0x2000
	s_add_u32 s0, s20, 0x100080
	v_lshl_add_u64 v[200:201], v[204:205], 0, s[80:81]
	s_addc_u32 s1, s21, 0
	s_add_i32 s20, s55, s26
	global_load_lds_dwordx4 v[200:201], off
	v_lshl_add_u64 v[200:201], s[0:1], 0, v[202:203]
	s_mov_b32 m0, s20
	s_nop 0
	global_load_lds_dwordx4 v[200:201], off
	v_lshl_add_u64 v[200:201], s[0:1], 0, v[130:131]
	s_add_i32 m0, s20, 0x2000
	s_nop 0
	global_load_lds_dwordx4 v[200:201], off
	v_lshl_add_u64 v[200:201], v[206:207], 0, s[80:81]
	s_mov_b32 m0, s31
	s_nop 0
	global_load_lds_dwordx4 v[200:201], off
	v_lshl_add_u64 v[200:201], v[212:213], 0, s[80:81]
	s_mov_b32 m0, s34
	s_nop 0
	global_load_lds_dwordx4 v[200:201], off
	s_waitcnt vmcnt(8)
	s_waitcnt lgkmcnt(0)
	s_setprio 1
	s_barrier
	v_mfma_f32_16x16x32_bf16 v[62:65], v[140:143], v[172:175], v[62:65]
	v_mfma_f32_16x16x32_bf16 v[58:61], v[148:151], v[172:175], v[58:61]
	v_mfma_f32_16x16x32_bf16 v[54:57], v[140:143], v[180:183], v[54:57]
	v_mfma_f32_16x16x32_bf16 v[50:53], v[148:151], v[180:183], v[50:53]
	v_mfma_f32_16x16x32_bf16 v[38:41], v[140:143], v[188:191], v[38:41]
	v_mfma_f32_16x16x32_bf16 v[34:37], v[148:151], v[188:191], v[34:37]
	v_mfma_f32_16x16x32_bf16 v[22:25], v[140:143], v[196:199], v[22:25]
	v_mfma_f32_16x16x32_bf16 v[18:21], v[148:151], v[196:199], v[18:21]
	v_mfma_f32_16x16x32_bf16 v[62:65], v[144:147], v[176:179], v[62:65]
	v_mfma_f32_16x16x32_bf16 v[58:61], v[152:155], v[176:179], v[58:61]
	v_mfma_f32_16x16x32_bf16 v[54:57], v[144:147], v[184:187], v[54:57]
	v_mfma_f32_16x16x32_bf16 v[50:53], v[152:155], v[184:187], v[50:53]
	v_mfma_f32_16x16x32_bf16 v[38:41], v[144:147], v[192:195], v[38:41]
	v_mfma_f32_16x16x32_bf16 v[34:37], v[152:155], v[192:195], v[34:37]
	v_mfma_f32_16x16x32_bf16 v[22:25], v[144:147], v[208:211], v[22:25]
	v_mfma_f32_16x16x32_bf16 v[18:21], v[152:155], v[208:211], v[18:21]
	s_setprio 0
	s_setprio 1
	v_mfma_f32_16x16x32_bf16 v[46:49], v[156:159], v[172:175], v[46:49]
	v_mfma_f32_16x16x32_bf16 v[42:45], v[164:167], v[172:175], v[42:45]
	v_mfma_f32_16x16x32_bf16 v[30:33], v[156:159], v[180:183], v[30:33]
	v_mfma_f32_16x16x32_bf16 v[26:29], v[164:167], v[180:183], v[26:29]
	v_mfma_f32_16x16x32_bf16 v[14:17], v[156:159], v[188:191], v[14:17]
	v_mfma_f32_16x16x32_bf16 v[10:13], v[164:167], v[188:191], v[10:13]
	v_mfma_f32_16x16x32_bf16 v[6:9], v[156:159], v[196:199], v[6:9]
	v_mfma_f32_16x16x32_bf16 v[2:5], v[164:167], v[196:199], v[2:5]
	v_mfma_f32_16x16x32_bf16 v[46:49], v[160:163], v[176:179], v[46:49]
	v_mfma_f32_16x16x32_bf16 v[42:45], v[168:171], v[176:179], v[42:45]
	v_mfma_f32_16x16x32_bf16 v[30:33], v[160:163], v[184:187], v[30:33]
	v_mfma_f32_16x16x32_bf16 v[26:29], v[168:171], v[184:187], v[26:29]
	v_mfma_f32_16x16x32_bf16 v[14:17], v[160:163], v[192:195], v[14:17]
	v_mfma_f32_16x16x32_bf16 v[10:13], v[168:171], v[192:195], v[10:13]
	v_mfma_f32_16x16x32_bf16 v[6:9], v[160:163], v[208:211], v[6:9]
	v_mfma_f32_16x16x32_bf16 v[2:5], v[168:171], v[208:211], v[2:5]
	s_barrier
	s_setprio 0
	s_add_i32 s49, s49, 2
	s_add_u32 s18, s18, 0x100
	s_addc_u32 s19, s19, 0
	s_add_u32 s9, s9, 0x100
	s_addc_u32 s11, s11, 0
	s_cmp_gt_u32 s49, 5
	s_cbranch_scc0 .LBB0_712
	s_and_b64 vcc, exec, s[6:7]
	s_cbranch_vccz .LBB0_715
	s_barrier

.LBB0_837:
	ds_read_b128 v[178:181], v145
	ds_read_b128 v[182:185], v145 offset:1024
	ds_read_b128 v[186:189], v145 offset:2048
	ds_read_b128 v[190:193], v145 offset:3072
	ds_read_b128 v[194:197], v145 offset:4096
	ds_read_b128 v[198:201], v145 offset:5120
	ds_read_b128 v[208:211], v145 offset:6144
	ds_read_b128 v[212:215], v145 offset:7168
	s_add_u32 s0, s18, 0xfff80080
	s_addc_u32 s1, s19, -1
	s_add_i32 s33, 0, 0x10000
	s_cmp_eq_u32 s59, 28
	s_cselect_b32 s23, s11, s1
	s_cselect_b32 s22, s38, s0
	v_add_u32_e32 v140, s33, v143
	s_cselect_b32 s21, s9, s58
	s_cselect_b32 s20, s39, s49
	s_add_i32 s55, 0, 0x14000
	ds_read_b128 v[146:149], v140
	ds_read_b128 v[150:153], v140 offset:1024
	ds_read_b128 v[154:157], v140 offset:2048
	ds_read_b128 v[158:161], v140 offset:3072
	v_add_u32_e32 v140, s55, v143
	ds_read_b128 v[162:165], v140
	ds_read_b128 v[166:169], v140 offset:1024
	ds_read_b128 v[170:173], v140 offset:2048
	ds_read_b128 v[174:177], v140 offset:3072
	v_lshl_add_u64 v[140:141], s[18:19], 0, v[136:137]
	s_add_i32 m0, s27, 0xc000
	global_load_lds_dwordx4 v[140:141], off
	v_lshl_add_u64 v[140:141], s[18:19], 0, v[138:139]
	s_add_i32 m0, s27, 0xe000
	s_nop 0
	global_load_lds_dwordx4 v[140:141], off
	s_waitcnt vmcnt(8)
	s_waitcnt lgkmcnt(0)
	s_setprio 1
	s_barrier
	v_mfma_f32_16x16x32_bf16 v[126:129], v[146:149], v[178:181], v[126:129]
	v_mfma_f32_16x16x32_bf16 v[118:121], v[154:157], v[178:181], v[118:121]
	v_mfma_f32_16x16x32_bf16 v[110:113], v[146:149], v[186:189], v[110:113]
	v_mfma_f32_16x16x32_bf16 v[102:105], v[154:157], v[186:189], v[102:105]
	v_mfma_f32_16x16x32_bf16 v[94:97], v[146:149], v[194:197], v[94:97]
	v_mfma_f32_16x16x32_bf16 v[86:89], v[154:157], v[194:197], v[86:89]
	v_mfma_f32_16x16x32_bf16 v[78:81], v[146:149], v[208:211], v[78:81]
	v_mfma_f32_16x16x32_bf16 v[70:73], v[154:157], v[208:211], v[70:73]
	v_mfma_f32_16x16x32_bf16 v[126:129], v[150:153], v[182:185], v[126:129]
	v_mfma_f32_16x16x32_bf16 v[118:121], v[158:161], v[182:185], v[118:121]
	v_mfma_f32_16x16x32_bf16 v[110:113], v[150:153], v[190:193], v[110:113]
	v_mfma_f32_16x16x32_bf16 v[102:105], v[158:161], v[190:193], v[102:105]
	v_mfma_f32_16x16x32_bf16 v[94:97], v[150:153], v[198:201], v[94:97]
	v_mfma_f32_16x16x32_bf16 v[86:89], v[158:161], v[198:201], v[86:89]
	v_mfma_f32_16x16x32_bf16 v[78:81], v[150:153], v[212:215], v[78:81]
	v_mfma_f32_16x16x32_bf16 v[70:73], v[158:161], v[212:215], v[70:73]
	s_setprio 0
	s_setprio 1
	v_mfma_f32_16x16x32_bf16 v[122:125], v[162:165], v[178:181], v[122:125]
	v_mfma_f32_16x16x32_bf16 v[114:117], v[170:173], v[178:181], v[114:117]
	v_mfma_f32_16x16x32_bf16 v[106:109], v[162:165], v[186:189], v[106:109]
	v_mfma_f32_16x16x32_bf16 v[98:101], v[170:173], v[186:189], v[98:101]
	v_mfma_f32_16x16x32_bf16 v[90:93], v[162:165], v[194:197], v[90:93]
	v_mfma_f32_16x16x32_bf16 v[82:85], v[170:173], v[194:197], v[82:85]
	v_mfma_f32_16x16x32_bf16 v[74:77], v[162:165], v[208:211], v[74:77]
	v_mfma_f32_16x16x32_bf16 v[66:69], v[170:173], v[208:211], v[66:69]
	v_mfma_f32_16x16x32_bf16 v[122:125], v[166:169], v[182:185], v[122:125]
	v_mfma_f32_16x16x32_bf16 v[114:117], v[174:177], v[182:185], v[114:117]
	v_mfma_f32_16x16x32_bf16 v[106:109], v[166:169], v[190:193], v[106:109]
	v_mfma_f32_16x16x32_bf16 v[98:101], v[174:177], v[190:193], v[98:101]
	v_mfma_f32_16x16x32_bf16 v[90:93], v[166:169], v[198:201], v[90:93]
	v_mfma_f32_16x16x32_bf16 v[82:85], v[174:177], v[198:201], v[82:85]
	v_mfma_f32_16x16x32_bf16 v[74:77], v[166:169], v[212:215], v[74:77]
	v_mfma_f32_16x16x32_bf16 v[66:69], v[174:177], v[212:215], v[66:69]
	s_barrier
	s_setprio 0
	s_add_i32 s0, s33, s26
	v_lshl_add_u64 v[140:141], s[20:21], 0, v[202:203]
	s_mov_b32 m0, s0
	ds_read_b128 v[178:181], v145 offset:16384
	ds_read_b128 v[182:185], v145 offset:17408
	ds_read_b128 v[186:189], v145 offset:18432
	ds_read_b128 v[190:193], v145 offset:19456
	ds_read_b128 v[194:197], v145 offset:20480
	ds_read_b128 v[198:201], v145 offset:21504
	ds_read_b128 v[208:211], v145 offset:22528
	ds_read_b128 v[212:215], v145 offset:23552
	global_load_lds_dwordx4 v[140:141], off
	s_add_i32 m0, s0, 0x2000
	s_add_u32 s0, s20, 0x80000
	v_lshl_add_u64 v[204:205], s[20:21], 0, v[130:131]
	s_addc_u32 s1, s21, 0
	s_add_i32 s33, s55, s26
	global_load_lds_dwordx4 v[204:205], off
	v_lshl_add_u64 v[206:207], s[0:1], 0, v[202:203]
	s_mov_b32 m0, s33
	v_lshl_add_u64 v[216:217], s[22:23], 0, v[132:133]
	global_load_lds_dwordx4 v[206:207], off
	v_lshl_add_u64 v[206:207], s[0:1], 0, v[130:131]
	s_add_i32 m0, s33, 0x2000
	s_nop 0
	global_load_lds_dwordx4 v[206:207], off
	v_lshl_add_u64 v[206:207], s[22:23], 0, v[134:135]
	s_mov_b32 m0, s27
	s_nop 0
	global_load_lds_dwordx4 v[206:207], off
	s_mov_b32 m0, s28
	s_nop 0
	global_load_lds_dwordx4 v[216:217], off
	s_waitcnt vmcnt(8)
	s_waitcnt lgkmcnt(0)
	s_setprio 1
	s_barrier
	v_mfma_f32_16x16x32_bf16 v[62:65], v[146:149], v[178:181], v[62:65]
	v_mfma_f32_16x16x32_bf16 v[54:57], v[154:157], v[178:181], v[54:57]
	v_mfma_f32_16x16x32_bf16 v[46:49], v[146:149], v[186:189], v[46:49]
	v_mfma_f32_16x16x32_bf16 v[38:41], v[154:157], v[186:189], v[38:41]
	v_mfma_f32_16x16x32_bf16 v[30:33], v[146:149], v[194:197], v[30:33]
	v_mfma_f32_16x16x32_bf16 v[22:25], v[154:157], v[194:197], v[22:25]
	v_mfma_f32_16x16x32_bf16 v[14:17], v[146:149], v[208:211], v[14:17]
	v_mfma_f32_16x16x32_bf16 v[6:9], v[154:157], v[208:211], v[6:9]
	v_mfma_f32_16x16x32_bf16 v[62:65], v[150:153], v[182:185], v[62:65]
	v_mfma_f32_16x16x32_bf16 v[54:57], v[158:161], v[182:185], v[54:57]
	v_mfma_f32_16x16x32_bf16 v[46:49], v[150:153], v[190:193], v[46:49]
	v_mfma_f32_16x16x32_bf16 v[38:41], v[158:161], v[190:193], v[38:41]
	v_mfma_f32_16x16x32_bf16 v[30:33], v[150:153], v[198:201], v[30:33]
	v_mfma_f32_16x16x32_bf16 v[22:25], v[158:161], v[198:201], v[22:25]
	v_mfma_f32_16x16x32_bf16 v[14:17], v[150:153], v[212:215], v[14:17]
	v_mfma_f32_16x16x32_bf16 v[6:9], v[158:161], v[212:215], v[6:9]
	s_setprio 0
	s_setprio 1
	v_mfma_f32_16x16x32_bf16 v[58:61], v[162:165], v[178:181], v[58:61]
	v_mfma_f32_16x16x32_bf16 v[50:53], v[170:173], v[178:181], v[50:53]
	v_mfma_f32_16x16x32_bf16 v[42:45], v[162:165], v[186:189], v[42:45]
	v_mfma_f32_16x16x32_bf16 v[34:37], v[170:173], v[186:189], v[34:37]
	v_mfma_f32_16x16x32_bf16 v[26:29], v[162:165], v[194:197], v[26:29]
	v_mfma_f32_16x16x32_bf16 v[18:21], v[170:173], v[194:197], v[18:21]
	v_mfma_f32_16x16x32_bf16 v[10:13], v[162:165], v[208:211], v[10:13]
	v_mfma_f32_16x16x32_bf16 v[2:5], v[170:173], v[208:211], v[2:5]
	v_mfma_f32_16x16x32_bf16 v[58:61], v[166:169], v[182:185], v[58:61]
	v_mfma_f32_16x16x32_bf16 v[50:53], v[174:177], v[182:185], v[50:53]
	v_mfma_f32_16x16x32_bf16 v[42:45], v[166:169], v[190:193], v[42:45]
	v_mfma_f32_16x16x32_bf16 v[34:37], v[174:177], v[190:193], v[34:37]
	v_mfma_f32_16x16x32_bf16 v[26:29], v[166:169], v[198:201], v[26:29]
	v_mfma_f32_16x16x32_bf16 v[18:21], v[174:177], v[198:201], v[18:21]
	v_mfma_f32_16x16x32_bf16 v[10:13], v[166:169], v[212:215], v[10:13]
	v_mfma_f32_16x16x32_bf16 v[2:5], v[174:177], v[212:215], v[2:5]
	s_barrier
	s_setprio 0
	s_add_i32 s33, 0, 0x18000
	s_add_i32 s55, 0, 0x1c000
	v_add_u32_e32 v158, s33, v143
	v_add_u32_e32 v174, s55, v143
	ds_read_b128 v[146:149], v158
	ds_read_b128 v[150:153], v158 offset:1024
	ds_read_b128 v[154:157], v158 offset:2048
	ds_read_b128 v[158:161], v158 offset:3072
	ds_read_b128 v[162:165], v174
	ds_read_b128 v[166:169], v174 offset:1024
	ds_read_b128 v[170:173], v174 offset:2048
	ds_read_b128 v[174:177], v174 offset:3072
	s_add_u32 s0, s22, 0x80000
	s_addc_u32 s1, s23, 0
	s_mov_b32 m0, s29
	v_lshl_add_u64 v[218:219], s[0:1], 0, v[134:135]
	ds_read_b128 v[178:181], v145 offset:32768
	ds_read_b128 v[182:185], v145 offset:33792
	ds_read_b128 v[186:189], v145 offset:34816
	ds_read_b128 v[190:193], v145 offset:35840
	ds_read_b128 v[194:197], v145 offset:36864
	ds_read_b128 v[198:201], v145 offset:37888
	ds_read_b128 v[208:211], v145 offset:38912
	ds_read_b128 v[212:215], v145 offset:39936
	global_load_lds_dwordx4 v[218:219], off
	v_lshl_add_u64 v[218:219], s[0:1], 0, v[132:133]
	s_mov_b32 m0, s30
	s_nop 0
	global_load_lds_dwordx4 v[218:219], off
	s_waitcnt vmcnt(8)
	s_waitcnt lgkmcnt(0)
	s_setprio 1
	s_barrier
	v_mfma_f32_16x16x32_bf16 v[126:129], v[146:149], v[178:181], v[126:129]
	v_mfma_f32_16x16x32_bf16 v[118:121], v[154:157], v[178:181], v[118:121]
	v_mfma_f32_16x16x32_bf16 v[110:113], v[146:149], v[186:189], v[110:113]
	v_mfma_f32_16x16x32_bf16 v[102:105], v[154:157], v[186:189], v[102:105]
	v_mfma_f32_16x16x32_bf16 v[94:97], v[146:149], v[194:197], v[94:97]
	v_mfma_f32_16x16x32_bf16 v[86:89], v[154:157], v[194:197], v[86:89]
	v_mfma_f32_16x16x32_bf16 v[78:81], v[146:149], v[208:211], v[78:81]
	v_mfma_f32_16x16x32_bf16 v[70:73], v[154:157], v[208:211], v[70:73]
	v_mfma_f32_16x16x32_bf16 v[126:129], v[150:153], v[182:185], v[126:129]
	v_mfma_f32_16x16x32_bf16 v[118:121], v[158:161], v[182:185], v[118:121]
	v_mfma_f32_16x16x32_bf16 v[110:113], v[150:153], v[190:193], v[110:113]
	v_mfma_f32_16x16x32_bf16 v[102:105], v[158:161], v[190:193], v[102:105]
	v_mfma_f32_16x16x32_bf16 v[94:97], v[150:153], v[198:201], v[94:97]
	v_mfma_f32_16x16x32_bf16 v[86:89], v[158:161], v[198:201], v[86:89]
	v_mfma_f32_16x16x32_bf16 v[78:81], v[150:153], v[212:215], v[78:81]
	v_mfma_f32_16x16x32_bf16 v[70:73], v[158:161], v[212:215], v[70:73]
	s_setprio 0
	s_setprio 1
	v_mfma_f32_16x16x32_bf16 v[122:125], v[162:165], v[178:181], v[122:125]
	v_mfma_f32_16x16x32_bf16 v[114:117], v[170:173], v[178:181], v[114:117]
	v_mfma_f32_16x16x32_bf16 v[106:109], v[162:165], v[186:189], v[106:109]
	v_mfma_f32_16x16x32_bf16 v[98:101], v[170:173], v[186:189], v[98:101]
	v_mfma_f32_16x16x32_bf16 v[90:93], v[162:165], v[194:197], v[90:93]
	v_mfma_f32_16x16x32_bf16 v[82:85], v[170:173], v[194:197], v[82:85]
	v_mfma_f32_16x16x32_bf16 v[74:77], v[162:165], v[208:211], v[74:77]
	v_mfma_f32_16x16x32_bf16 v[66:69], v[170:173], v[208:211], v[66:69]
	v_mfma_f32_16x16x32_bf16 v[122:125], v[166:169], v[182:185], v[122:125]
	v_mfma_f32_16x16x32_bf16 v[114:117], v[174:177], v[182:185], v[114:117]
	v_mfma_f32_16x16x32_bf16 v[106:109], v[166:169], v[190:193], v[106:109]
	v_mfma_f32_16x16x32_bf16 v[98:101], v[174:177], v[190:193], v[98:101]
	v_mfma_f32_16x16x32_bf16 v[90:93], v[166:169], v[198:201], v[90:93]
	v_mfma_f32_16x16x32_bf16 v[82:85], v[174:177], v[198:201], v[82:85]
	v_mfma_f32_16x16x32_bf16 v[74:77], v[166:169], v[212:215], v[74:77]
	v_mfma_f32_16x16x32_bf16 v[66:69], v[174:177], v[212:215], v[66:69]
	s_barrier
	s_setprio 0
	s_add_i32 s0, s33, s26
	v_lshl_add_u64 v[140:141], v[140:141], 0, s[80:81]
	s_mov_b32 m0, s0
	ds_read_b128 v[178:181], v145 offset:49152
	ds_read_b128 v[182:185], v145 offset:50176
	ds_read_b128 v[186:189], v145 offset:51200
	ds_read_b128 v[190:193], v145 offset:52224
	ds_read_b128 v[194:197], v145 offset:53248
	ds_read_b128 v[198:201], v145 offset:54272
	ds_read_b128 v[208:211], v145 offset:55296
	ds_read_b128 v[212:215], v145 offset:56320
	global_load_lds_dwordx4 v[140:141], off
	s_add_i32 m0, s0, 0x2000
	s_add_u32 s0, s20, 0x80080
	v_lshl_add_u64 v[140:141], v[204:205], 0, s[80:81]
	s_addc_u32 s1, s21, 0
	s_add_i32 s20, s55, s26
	global_load_lds_dwordx4 v[140:141], off
	v_lshl_add_u64 v[140:141], s[0:1], 0, v[202:203]
	s_mov_b32 m0, s20
	s_nop 0
	global_load_lds_dwordx4 v[140:141], off
	v_lshl_add_u64 v[140:141], s[0:1], 0, v[130:131]
	s_add_i32 m0, s20, 0x2000
	s_nop 0
	global_load_lds_dwordx4 v[140:141], off
	v_lshl_add_u64 v[140:141], v[206:207], 0, s[80:81]
	s_mov_b32 m0, s31
	s_nop 0
	global_load_lds_dwordx4 v[140:141], off
	v_lshl_add_u64 v[140:141], v[216:217], 0, s[80:81]
	s_mov_b32 m0, s34
	s_nop 0
	global_load_lds_dwordx4 v[140:141], off
	s_waitcnt vmcnt(8)
	s_waitcnt lgkmcnt(0)
	s_setprio 1
	s_barrier
	v_mfma_f32_16x16x32_bf16 v[62:65], v[146:149], v[178:181], v[62:65]
	v_mfma_f32_16x16x32_bf16 v[54:57], v[154:157], v[178:181], v[54:57]
	v_mfma_f32_16x16x32_bf16 v[46:49], v[146:149], v[186:189], v[46:49]
	v_mfma_f32_16x16x32_bf16 v[38:41], v[154:157], v[186:189], v[38:41]
	v_mfma_f32_16x16x32_bf16 v[30:33], v[146:149], v[194:197], v[30:33]
	v_mfma_f32_16x16x32_bf16 v[22:25], v[154:157], v[194:197], v[22:25]
	v_mfma_f32_16x16x32_bf16 v[14:17], v[146:149], v[208:211], v[14:17]
	v_mfma_f32_16x16x32_bf16 v[6:9], v[154:157], v[208:211], v[6:9]
	v_mfma_f32_16x16x32_bf16 v[62:65], v[150:153], v[182:185], v[62:65]
	v_mfma_f32_16x16x32_bf16 v[54:57], v[158:161], v[182:185], v[54:57]
	v_mfma_f32_16x16x32_bf16 v[46:49], v[150:153], v[190:193], v[46:49]
	v_mfma_f32_16x16x32_bf16 v[38:41], v[158:161], v[190:193], v[38:41]
	v_mfma_f32_16x16x32_bf16 v[30:33], v[150:153], v[198:201], v[30:33]
	v_mfma_f32_16x16x32_bf16 v[22:25], v[158:161], v[198:201], v[22:25]
	v_mfma_f32_16x16x32_bf16 v[14:17], v[150:153], v[212:215], v[14:17]
	v_mfma_f32_16x16x32_bf16 v[6:9], v[158:161], v[212:215], v[6:9]
	s_setprio 0
	s_setprio 1
	v_mfma_f32_16x16x32_bf16 v[58:61], v[162:165], v[178:181], v[58:61]
	v_mfma_f32_16x16x32_bf16 v[50:53], v[170:173], v[178:181], v[50:53]
	v_mfma_f32_16x16x32_bf16 v[42:45], v[162:165], v[186:189], v[42:45]
	v_mfma_f32_16x16x32_bf16 v[34:37], v[170:173], v[186:189], v[34:37]
	v_mfma_f32_16x16x32_bf16 v[26:29], v[162:165], v[194:197], v[26:29]
	v_mfma_f32_16x16x32_bf16 v[18:21], v[170:173], v[194:197], v[18:21]
	v_mfma_f32_16x16x32_bf16 v[10:13], v[162:165], v[208:211], v[10:13]
	v_mfma_f32_16x16x32_bf16 v[2:5], v[170:173], v[208:211], v[2:5]
	v_mfma_f32_16x16x32_bf16 v[58:61], v[166:169], v[182:185], v[58:61]
	v_mfma_f32_16x16x32_bf16 v[50:53], v[174:177], v[182:185], v[50:53]
	v_mfma_f32_16x16x32_bf16 v[42:45], v[166:169], v[190:193], v[42:45]
	v_mfma_f32_16x16x32_bf16 v[34:37], v[174:177], v[190:193], v[34:37]
	v_mfma_f32_16x16x32_bf16 v[26:29], v[166:169], v[198:201], v[26:29]
	v_mfma_f32_16x16x32_bf16 v[18:21], v[174:177], v[198:201], v[18:21]
	v_mfma_f32_16x16x32_bf16 v[10:13], v[166:169], v[212:215], v[10:13]
	v_mfma_f32_16x16x32_bf16 v[2:5], v[174:177], v[212:215], v[2:5]
	s_barrier
	s_setprio 0
	s_add_i32 s59, s59, 2
	s_add_u32 s18, s18, 0x100
	s_addc_u32 s19, s19, 0
	s_add_u32 s49, s49, 0x100
	s_addc_u32 s58, s58, 0
	s_cmp_gt_u32 s59, 29
	s_cbranch_scc0 .LBB0_837
	s_and_b64 vcc, exec, s[6:7]
	s_cbranch_vccz .LBB0_840
	s_barrier

.LBB0_970:
	ds_read_b128 v[146:149], v239
	ds_read_b128 v[158:161], v239 offset:1024
	ds_read_b128 v[166:169], v239 offset:2048
	ds_read_b128 v[174:177], v239 offset:3072
	ds_read_b128 v[178:181], v239 offset:4096
	ds_read_b128 v[182:185], v239 offset:5120
	ds_read_b128 v[186:189], v239 offset:6144
	ds_read_b128 v[190:193], v239 offset:7168
	s_add_u32 s16, s2, 0x100
	s_addc_u32 s17, s3, 0
	s_add_i32 s0, 0, 0x10000
	s_cmpk_eq_i32 s59, 0x54
	s_cselect_b32 s21, s7, s17
	s_cselect_b32 s20, s6, s16
	s_cselect_b32 s19, s15, s58
	s_cselect_b32 s18, s14, s49
	s_add_i32 s33, 0, 0x14000
	v_add_u32_e32 v98, s0, v205
	v_add_u32_e32 v134, s33, v205
	ds_read_b128 v[78:81], v98
	ds_read_b128 v[82:85], v98 offset:1024
	ds_read_b128 v[94:97], v98 offset:2048
	ds_read_b128 v[98:101], v98 offset:3072
	ds_read_b128 v[106:109], v134
	ds_read_b128 v[110:113], v134 offset:1024
	ds_read_b128 v[126:129], v134 offset:2048
	ds_read_b128 v[134:137], v134 offset:3072
	v_lshl_add_u64 v[194:195], s[2:3], 0, v[214:215]
	s_add_i32 m0, s25, 0xc000
	global_load_lds_dwordx4 v[194:195], off
	v_lshl_add_u64 v[194:195], s[2:3], 0, v[216:217]
	s_add_i32 m0, s25, 0xe000
	s_nop 0
	global_load_lds_dwordx4 v[194:195], off
	s_waitcnt vmcnt(8)
	s_waitcnt lgkmcnt(0)
	s_setprio 1
	s_barrier
	v_mfma_f32_16x16x32_bf16 v[170:173], v[78:81], v[146:149], v[170:173]
	v_mfma_f32_16x16x32_bf16 v[162:165], v[94:97], v[146:149], v[162:165]
	v_mfma_f32_16x16x32_bf16 v[142:145], v[78:81], v[166:169], v[142:145]
	v_mfma_f32_16x16x32_bf16 v[138:141], v[94:97], v[166:169], v[138:141]
	v_mfma_f32_16x16x32_bf16 v[118:121], v[78:81], v[178:181], v[118:121]
	v_mfma_f32_16x16x32_bf16 v[114:117], v[94:97], v[178:181], v[114:117]
	v_mfma_f32_16x16x32_bf16 v[86:89], v[78:81], v[186:189], v[86:89]
	v_mfma_f32_16x16x32_bf16 v[74:77], v[94:97], v[186:189], v[74:77]
	v_mfma_f32_16x16x32_bf16 v[170:173], v[82:85], v[158:161], v[170:173]
	v_mfma_f32_16x16x32_bf16 v[162:165], v[98:101], v[158:161], v[162:165]
	v_mfma_f32_16x16x32_bf16 v[142:145], v[82:85], v[174:177], v[142:145]
	v_mfma_f32_16x16x32_bf16 v[138:141], v[98:101], v[174:177], v[138:141]
	v_mfma_f32_16x16x32_bf16 v[118:121], v[82:85], v[182:185], v[118:121]
	v_mfma_f32_16x16x32_bf16 v[114:117], v[98:101], v[182:185], v[114:117]
	v_mfma_f32_16x16x32_bf16 v[86:89], v[82:85], v[190:193], v[86:89]
	v_mfma_f32_16x16x32_bf16 v[74:77], v[98:101], v[190:193], v[74:77]
	s_setprio 0
	s_setprio 1
	v_mfma_f32_16x16x32_bf16 v[154:157], v[106:109], v[146:149], v[154:157]
	v_mfma_f32_16x16x32_bf16 v[130:133], v[106:109], v[166:169], v[130:133]
	v_mfma_f32_16x16x32_bf16 v[122:125], v[126:129], v[166:169], v[122:125]
	v_mfma_f32_16x16x32_bf16 v[102:105], v[106:109], v[178:181], v[102:105]
	v_mfma_f32_16x16x32_bf16 v[90:93], v[126:129], v[178:181], v[90:93]
	v_mfma_f32_16x16x32_bf16 v[70:73], v[106:109], v[186:189], v[70:73]
	v_mfma_f32_16x16x32_bf16 v[66:69], v[126:129], v[186:189], v[66:69]
	v_mfma_f32_16x16x32_bf16 v[154:157], v[110:113], v[158:161], v[154:157]
	v_mfma_f32_16x16x32_bf16 v[146:149], v[126:129], v[146:149], v[150:153]
	v_mfma_f32_16x16x32_bf16 v[130:133], v[110:113], v[174:177], v[130:133]
	v_mfma_f32_16x16x32_bf16 v[122:125], v[134:137], v[174:177], v[122:125]
	v_mfma_f32_16x16x32_bf16 v[102:105], v[110:113], v[182:185], v[102:105]
	v_mfma_f32_16x16x32_bf16 v[90:93], v[134:137], v[182:185], v[90:93]
	v_mfma_f32_16x16x32_bf16 v[70:73], v[110:113], v[190:193], v[70:73]
	v_mfma_f32_16x16x32_bf16 v[66:69], v[134:137], v[190:193], v[66:69]
	v_mfma_f32_16x16x32_bf16 v[146:149], v[134:137], v[158:161], v[146:149]
	s_barrier
	s_setprio 0
	s_add_i32 s0, s0, s24
	v_lshl_add_u64 v[194:195], s[18:19], 0, v[202:203]
	s_mov_b32 m0, s0
	ds_read_b128 v[150:153], v239 offset:16384
	ds_read_b128 v[158:161], v239 offset:17408
	ds_read_b128 v[166:169], v239 offset:18432
	ds_read_b128 v[174:177], v239 offset:19456
	ds_read_b128 v[178:181], v239 offset:20480
	ds_read_b128 v[182:185], v239 offset:21504
	ds_read_b128 v[186:189], v239 offset:22528
	ds_read_b128 v[190:193], v239 offset:23552
	global_load_lds_dwordx4 v[194:195], off
	s_add_i32 m0, s0, 0x2000
	s_add_u32 s0, s18, 0x160000
	v_lshl_add_u64 v[196:197], s[18:19], 0, v[208:209]
	s_addc_u32 s1, s19, 0
	s_add_i32 s2, s33, s24
	global_load_lds_dwordx4 v[196:197], off
	v_lshl_add_u64 v[198:199], s[0:1], 0, v[202:203]
	s_mov_b32 m0, s2
	v_lshl_add_u64 v[200:201], s[20:21], 0, v[210:211]
	global_load_lds_dwordx4 v[198:199], off
	v_lshl_add_u64 v[198:199], s[0:1], 0, v[208:209]
	s_add_i32 m0, s2, 0x2000
	s_nop 0
	global_load_lds_dwordx4 v[198:199], off
	v_lshl_add_u64 v[198:199], s[20:21], 0, v[212:213]
	s_mov_b32 m0, s25
	s_nop 0
	global_load_lds_dwordx4 v[198:199], off
	s_mov_b32 m0, s26
	s_nop 0
	global_load_lds_dwordx4 v[200:201], off
	s_waitcnt vmcnt(8)
	s_waitcnt lgkmcnt(0)
	s_setprio 1
	s_barrier
	v_mfma_f32_16x16x32_bf16 v[62:65], v[78:81], v[150:153], v[62:65]
	v_mfma_f32_16x16x32_bf16 v[58:61], v[94:97], v[150:153], v[58:61]
	v_mfma_f32_16x16x32_bf16 v[46:49], v[78:81], v[166:169], v[46:49]
	v_mfma_f32_16x16x32_bf16 v[42:45], v[94:97], v[166:169], v[42:45]
	v_mfma_f32_16x16x32_bf16 v[30:33], v[78:81], v[178:181], v[30:33]
	v_mfma_f32_16x16x32_bf16 v[26:29], v[94:97], v[178:181], v[26:29]
	v_mfma_f32_16x16x32_bf16 v[14:17], v[78:81], v[186:189], v[14:17]
	v_mfma_f32_16x16x32_bf16 v[10:13], v[94:97], v[186:189], v[10:13]
	v_mfma_f32_16x16x32_bf16 v[62:65], v[82:85], v[158:161], v[62:65]
	v_mfma_f32_16x16x32_bf16 v[58:61], v[98:101], v[158:161], v[58:61]
	v_mfma_f32_16x16x32_bf16 v[46:49], v[82:85], v[174:177], v[46:49]
	v_mfma_f32_16x16x32_bf16 v[42:45], v[98:101], v[174:177], v[42:45]
	v_mfma_f32_16x16x32_bf16 v[30:33], v[82:85], v[182:185], v[30:33]
	v_mfma_f32_16x16x32_bf16 v[26:29], v[98:101], v[182:185], v[26:29]
	v_mfma_f32_16x16x32_bf16 v[14:17], v[82:85], v[190:193], v[14:17]
	v_mfma_f32_16x16x32_bf16 v[10:13], v[98:101], v[190:193], v[10:13]
	s_setprio 0
	s_setprio 1
	v_mfma_f32_16x16x32_bf16 v[54:57], v[106:109], v[150:153], v[54:57]
	v_mfma_f32_16x16x32_bf16 v[50:53], v[126:129], v[150:153], v[50:53]
	v_mfma_f32_16x16x32_bf16 v[38:41], v[106:109], v[166:169], v[38:41]
	v_mfma_f32_16x16x32_bf16 v[34:37], v[126:129], v[166:169], v[34:37]
	v_mfma_f32_16x16x32_bf16 v[22:25], v[106:109], v[178:181], v[22:25]
	v_mfma_f32_16x16x32_bf16 v[18:21], v[126:129], v[178:181], v[18:21]
	v_mfma_f32_16x16x32_bf16 v[6:9], v[106:109], v[186:189], v[6:9]
	v_mfma_f32_16x16x32_bf16 v[2:5], v[126:129], v[186:189], v[2:5]
	v_mfma_f32_16x16x32_bf16 v[54:57], v[110:113], v[158:161], v[54:57]
	v_mfma_f32_16x16x32_bf16 v[50:53], v[134:137], v[158:161], v[50:53]
	v_mfma_f32_16x16x32_bf16 v[38:41], v[110:113], v[174:177], v[38:41]
	v_mfma_f32_16x16x32_bf16 v[34:37], v[134:137], v[174:177], v[34:37]
	v_mfma_f32_16x16x32_bf16 v[22:25], v[110:113], v[182:185], v[22:25]
	v_mfma_f32_16x16x32_bf16 v[18:21], v[134:137], v[182:185], v[18:21]
	v_mfma_f32_16x16x32_bf16 v[6:9], v[110:113], v[190:193], v[6:9]
	v_mfma_f32_16x16x32_bf16 v[2:5], v[134:137], v[190:193], v[2:5]
	s_barrier
	s_setprio 0
	s_add_i32 s2, 0, 0x18000
	s_add_i32 s3, 0, 0x1c000
	v_add_u32_e32 v98, s2, v205
	v_add_u32_e32 v134, s3, v205
	ds_read_b128 v[78:81], v98
	ds_read_b128 v[82:85], v98 offset:1024
	ds_read_b128 v[94:97], v98 offset:2048
	ds_read_b128 v[98:101], v98 offset:3072
	ds_read_b128 v[106:109], v134
	ds_read_b128 v[110:113], v134 offset:1024
	ds_read_b128 v[126:129], v134 offset:2048
	ds_read_b128 v[134:137], v134 offset:3072
	s_add_u32 s0, s20, 0x160000
	s_addc_u32 s1, s21, 0
	s_mov_b32 m0, s27
	v_lshl_add_u64 v[206:207], s[0:1], 0, v[212:213]
	ds_read_b128 v[150:153], v239 offset:32768
	ds_read_b128 v[158:161], v239 offset:33792
	ds_read_b128 v[166:169], v239 offset:34816
	ds_read_b128 v[174:177], v239 offset:35840
	ds_read_b128 v[178:181], v239 offset:36864
	ds_read_b128 v[182:185], v239 offset:37888
	ds_read_b128 v[186:189], v239 offset:38912
	ds_read_b128 v[190:193], v239 offset:39936
	global_load_lds_dwordx4 v[206:207], off
	v_lshl_add_u64 v[206:207], s[0:1], 0, v[210:211]
	s_mov_b32 m0, s28
	s_nop 0
	global_load_lds_dwordx4 v[206:207], off
	s_waitcnt vmcnt(8)
	s_waitcnt lgkmcnt(0)
	s_setprio 1
	s_barrier
	v_mfma_f32_16x16x32_bf16 v[170:173], v[78:81], v[150:153], v[170:173]
	v_mfma_f32_16x16x32_bf16 v[162:165], v[94:97], v[150:153], v[162:165]
	v_mfma_f32_16x16x32_bf16 v[142:145], v[78:81], v[166:169], v[142:145]
	v_mfma_f32_16x16x32_bf16 v[138:141], v[94:97], v[166:169], v[138:141]
	v_mfma_f32_16x16x32_bf16 v[118:121], v[78:81], v[178:181], v[118:121]
	v_mfma_f32_16x16x32_bf16 v[114:117], v[94:97], v[178:181], v[114:117]
	v_mfma_f32_16x16x32_bf16 v[86:89], v[78:81], v[186:189], v[86:89]
	v_mfma_f32_16x16x32_bf16 v[74:77], v[94:97], v[186:189], v[74:77]
	v_mfma_f32_16x16x32_bf16 v[170:173], v[82:85], v[158:161], v[170:173]
	v_mfma_f32_16x16x32_bf16 v[162:165], v[98:101], v[158:161], v[162:165]
	v_mfma_f32_16x16x32_bf16 v[142:145], v[82:85], v[174:177], v[142:145]
	v_mfma_f32_16x16x32_bf16 v[138:141], v[98:101], v[174:177], v[138:141]
	v_mfma_f32_16x16x32_bf16 v[118:121], v[82:85], v[182:185], v[118:121]
	v_mfma_f32_16x16x32_bf16 v[114:117], v[98:101], v[182:185], v[114:117]
	v_mfma_f32_16x16x32_bf16 v[86:89], v[82:85], v[190:193], v[86:89]
	v_mfma_f32_16x16x32_bf16 v[74:77], v[98:101], v[190:193], v[74:77]
	s_setprio 0
	s_setprio 1
	v_mfma_f32_16x16x32_bf16 v[154:157], v[106:109], v[150:153], v[154:157]
	v_mfma_f32_16x16x32_bf16 v[146:149], v[126:129], v[150:153], v[146:149]
	v_mfma_f32_16x16x32_bf16 v[130:133], v[106:109], v[166:169], v[130:133]
	v_mfma_f32_16x16x32_bf16 v[122:125], v[126:129], v[166:169], v[122:125]
	v_mfma_f32_16x16x32_bf16 v[102:105], v[106:109], v[178:181], v[102:105]
	v_mfma_f32_16x16x32_bf16 v[90:93], v[126:129], v[178:181], v[90:93]
	v_mfma_f32_16x16x32_bf16 v[70:73], v[106:109], v[186:189], v[70:73]
	v_mfma_f32_16x16x32_bf16 v[66:69], v[126:129], v[186:189], v[66:69]
	v_mfma_f32_16x16x32_bf16 v[154:157], v[110:113], v[158:161], v[154:157]
	v_mfma_f32_16x16x32_bf16 v[150:153], v[134:137], v[158:161], v[146:149]
	v_mfma_f32_16x16x32_bf16 v[130:133], v[110:113], v[174:177], v[130:133]
	v_mfma_f32_16x16x32_bf16 v[122:125], v[134:137], v[174:177], v[122:125]
	v_mfma_f32_16x16x32_bf16 v[102:105], v[110:113], v[182:185], v[102:105]
	v_mfma_f32_16x16x32_bf16 v[90:93], v[134:137], v[182:185], v[90:93]
	v_mfma_f32_16x16x32_bf16 v[70:73], v[110:113], v[190:193], v[70:73]
	v_mfma_f32_16x16x32_bf16 v[66:69], v[134:137], v[190:193], v[66:69]
	s_barrier
	s_setprio 0
	s_add_i32 s0, s2, s24
	v_lshl_add_u64 v[194:195], v[194:195], 0, s[80:81]
	s_mov_b32 m0, s0
	ds_read_b128 v[146:149], v239 offset:49152
	ds_read_b128 v[158:161], v239 offset:50176
	ds_read_b128 v[166:169], v239 offset:51200
	ds_read_b128 v[174:177], v239 offset:52224
	ds_read_b128 v[178:181], v239 offset:53248
	ds_read_b128 v[182:185], v239 offset:54272
	ds_read_b128 v[186:189], v239 offset:55296
	ds_read_b128 v[190:193], v239 offset:56320
	global_load_lds_dwordx4 v[194:195], off
	s_add_i32 m0, s0, 0x2000
	s_add_u32 s0, s18, 0x160080
	v_lshl_add_u64 v[194:195], v[196:197], 0, s[80:81]
	s_addc_u32 s1, s19, 0
	s_add_i32 s2, s3, s24
	global_load_lds_dwordx4 v[194:195], off
	v_lshl_add_u64 v[194:195], s[0:1], 0, v[202:203]
	s_mov_b32 m0, s2
	s_nop 0
	global_load_lds_dwordx4 v[194:195], off
	v_lshl_add_u64 v[194:195], s[0:1], 0, v[208:209]
	s_add_i32 m0, s2, 0x2000
	s_nop 0
	global_load_lds_dwordx4 v[194:195], off
	v_lshl_add_u64 v[194:195], v[198:199], 0, s[80:81]
	s_mov_b32 m0, s31
	s_nop 0
	global_load_lds_dwordx4 v[194:195], off
	v_lshl_add_u64 v[194:195], v[200:201], 0, s[80:81]
	s_mov_b32 m0, s34
	s_nop 0
	global_load_lds_dwordx4 v[194:195], off
	s_waitcnt vmcnt(8)
	s_waitcnt lgkmcnt(0)
	s_setprio 1
	s_barrier
	v_mfma_f32_16x16x32_bf16 v[62:65], v[78:81], v[146:149], v[62:65]
	v_mfma_f32_16x16x32_bf16 v[58:61], v[94:97], v[146:149], v[58:61]
	v_mfma_f32_16x16x32_bf16 v[46:49], v[78:81], v[166:169], v[46:49]
	v_mfma_f32_16x16x32_bf16 v[42:45], v[94:97], v[166:169], v[42:45]
	v_mfma_f32_16x16x32_bf16 v[30:33], v[78:81], v[178:181], v[30:33]
	v_mfma_f32_16x16x32_bf16 v[26:29], v[94:97], v[178:181], v[26:29]
	v_mfma_f32_16x16x32_bf16 v[14:17], v[78:81], v[186:189], v[14:17]
	v_mfma_f32_16x16x32_bf16 v[10:13], v[94:97], v[186:189], v[10:13]
	v_mfma_f32_16x16x32_bf16 v[62:65], v[82:85], v[158:161], v[62:65]
	v_mfma_f32_16x16x32_bf16 v[58:61], v[98:101], v[158:161], v[58:61]
	v_mfma_f32_16x16x32_bf16 v[46:49], v[82:85], v[174:177], v[46:49]
	v_mfma_f32_16x16x32_bf16 v[42:45], v[98:101], v[174:177], v[42:45]
	v_mfma_f32_16x16x32_bf16 v[30:33], v[82:85], v[182:185], v[30:33]
	v_mfma_f32_16x16x32_bf16 v[26:29], v[98:101], v[182:185], v[26:29]
	v_mfma_f32_16x16x32_bf16 v[14:17], v[82:85], v[190:193], v[14:17]
	v_mfma_f32_16x16x32_bf16 v[10:13], v[98:101], v[190:193], v[10:13]
	s_setprio 0
	s_setprio 1
	v_mfma_f32_16x16x32_bf16 v[54:57], v[106:109], v[146:149], v[54:57]
	v_mfma_f32_16x16x32_bf16 v[50:53], v[126:129], v[146:149], v[50:53]
	v_mfma_f32_16x16x32_bf16 v[38:41], v[106:109], v[166:169], v[38:41]
	v_mfma_f32_16x16x32_bf16 v[34:37], v[126:129], v[166:169], v[34:37]
	v_mfma_f32_16x16x32_bf16 v[22:25], v[106:109], v[178:181], v[22:25]
	v_mfma_f32_16x16x32_bf16 v[18:21], v[126:129], v[178:181], v[18:21]
	v_mfma_f32_16x16x32_bf16 v[6:9], v[106:109], v[186:189], v[6:9]
	v_mfma_f32_16x16x32_bf16 v[2:5], v[126:129], v[186:189], v[2:5]
	v_mfma_f32_16x16x32_bf16 v[54:57], v[110:113], v[158:161], v[54:57]
	v_mfma_f32_16x16x32_bf16 v[50:53], v[134:137], v[158:161], v[50:53]
	v_mfma_f32_16x16x32_bf16 v[38:41], v[110:113], v[174:177], v[38:41]
	v_mfma_f32_16x16x32_bf16 v[34:37], v[134:137], v[174:177], v[34:37]
	v_mfma_f32_16x16x32_bf16 v[22:25], v[110:113], v[182:185], v[22:25]
	v_mfma_f32_16x16x32_bf16 v[18:21], v[134:137], v[182:185], v[18:21]
	v_mfma_f32_16x16x32_bf16 v[6:9], v[110:113], v[190:193], v[6:9]
	v_mfma_f32_16x16x32_bf16 v[2:5], v[134:137], v[190:193], v[2:5]
	s_barrier
	s_setprio 0
	s_add_i32 s59, s59, 2
	s_add_u32 s49, s49, 0x100
	s_addc_u32 s58, s58, 0
	s_cmpk_gt_u32 s59, 0x55
	s_mov_b64 s[2:3], s[16:17]
	s_cbranch_scc0 .LBB0_970
	s_and_b64 vcc, exec, s[10:11]
	s_cbranch_vccz .LBB0_973
	s_barrier

.LBB0_990:
	ds_read_b128 v[172:175], v139
	ds_read_b128 v[176:179], v139 offset:1024
	ds_read_b128 v[180:183], v139 offset:2048
	ds_read_b128 v[184:187], v139 offset:3072
	ds_read_b128 v[188:191], v139 offset:4096
	ds_read_b128 v[192:195], v139 offset:5120
	ds_read_b128 v[196:199], v139 offset:6144
	ds_read_b128 v[208:211], v139 offset:7168
	s_add_u32 s4, s2, 0x100
	s_addc_u32 s5, s3, 0
	s_add_i32 s0, 0, 0x10000
	s_cmp_eq_u32 s59, 4
	s_cselect_b32 s21, s15, s5
	s_cselect_b32 s20, s14, s4
	s_cselect_b32 s19, s17, s58
	s_cselect_b32 s18, s16, s49
	s_add_i32 s33, 0, 0x14000
	v_add_u32_e32 v152, s0, v136
	v_add_u32_e32 v168, s33, v136
	ds_read_b128 v[140:143], v152
	ds_read_b128 v[144:147], v152 offset:1024
	ds_read_b128 v[148:151], v152 offset:2048
	ds_read_b128 v[152:155], v152 offset:3072
	ds_read_b128 v[156:159], v168
	ds_read_b128 v[160:163], v168 offset:1024
	ds_read_b128 v[164:167], v168 offset:2048
	ds_read_b128 v[168:171], v168 offset:3072
	v_lshl_add_u64 v[200:201], s[2:3], 0, v[132:133]
	s_add_i32 m0, s25, 0xc000
	global_load_lds_dwordx4 v[200:201], off
	v_lshl_add_u64 v[200:201], s[2:3], 0, v[134:135]
	s_add_i32 m0, s25, 0xe000
	s_nop 0
	global_load_lds_dwordx4 v[200:201], off
	s_waitcnt vmcnt(8)
	s_waitcnt lgkmcnt(0)
	s_setprio 1
	s_barrier
	v_mfma_f32_16x16x32_bf16 v[126:129], v[140:143], v[172:175], v[126:129]
	v_mfma_f32_16x16x32_bf16 v[122:125], v[148:151], v[172:175], v[122:125]
	v_mfma_f32_16x16x32_bf16 v[118:121], v[140:143], v[180:183], v[118:121]
	v_mfma_f32_16x16x32_bf16 v[114:117], v[148:151], v[180:183], v[114:117]
	v_mfma_f32_16x16x32_bf16 v[106:109], v[140:143], v[188:191], v[106:109]
	v_mfma_f32_16x16x32_bf16 v[98:101], v[148:151], v[188:191], v[98:101]
	v_mfma_f32_16x16x32_bf16 v[90:93], v[140:143], v[196:199], v[90:93]
	v_mfma_f32_16x16x32_bf16 v[82:85], v[148:151], v[196:199], v[82:85]
	v_mfma_f32_16x16x32_bf16 v[126:129], v[144:147], v[176:179], v[126:129]
	v_mfma_f32_16x16x32_bf16 v[122:125], v[152:155], v[176:179], v[122:125]
	v_mfma_f32_16x16x32_bf16 v[118:121], v[144:147], v[184:187], v[118:121]
	v_mfma_f32_16x16x32_bf16 v[114:117], v[152:155], v[184:187], v[114:117]
	v_mfma_f32_16x16x32_bf16 v[106:109], v[144:147], v[192:195], v[106:109]
	v_mfma_f32_16x16x32_bf16 v[98:101], v[152:155], v[192:195], v[98:101]
	v_mfma_f32_16x16x32_bf16 v[90:93], v[144:147], v[208:211], v[90:93]
	v_mfma_f32_16x16x32_bf16 v[82:85], v[152:155], v[208:211], v[82:85]
	s_setprio 0
	s_setprio 1
	v_mfma_f32_16x16x32_bf16 v[110:113], v[156:159], v[172:175], v[110:113]
	v_mfma_f32_16x16x32_bf16 v[102:105], v[164:167], v[172:175], v[102:105]
	v_mfma_f32_16x16x32_bf16 v[94:97], v[156:159], v[180:183], v[94:97]
	v_mfma_f32_16x16x32_bf16 v[86:89], v[164:167], v[180:183], v[86:89]
	v_mfma_f32_16x16x32_bf16 v[78:81], v[156:159], v[188:191], v[78:81]
	v_mfma_f32_16x16x32_bf16 v[74:77], v[164:167], v[188:191], v[74:77]
	v_mfma_f32_16x16x32_bf16 v[70:73], v[156:159], v[196:199], v[70:73]
	v_mfma_f32_16x16x32_bf16 v[66:69], v[164:167], v[196:199], v[66:69]
	v_mfma_f32_16x16x32_bf16 v[110:113], v[160:163], v[176:179], v[110:113]
	v_mfma_f32_16x16x32_bf16 v[102:105], v[168:171], v[176:179], v[102:105]
	v_mfma_f32_16x16x32_bf16 v[94:97], v[160:163], v[184:187], v[94:97]
	v_mfma_f32_16x16x32_bf16 v[86:89], v[168:171], v[184:187], v[86:89]
	v_mfma_f32_16x16x32_bf16 v[78:81], v[160:163], v[192:195], v[78:81]
	v_mfma_f32_16x16x32_bf16 v[74:77], v[168:171], v[192:195], v[74:77]
	v_mfma_f32_16x16x32_bf16 v[70:73], v[160:163], v[208:211], v[70:73]
	v_mfma_f32_16x16x32_bf16 v[66:69], v[168:171], v[208:211], v[66:69]
	s_barrier
	s_setprio 0
	s_add_i32 s0, s0, s24
	v_lshl_add_u64 v[200:201], s[18:19], 0, v[202:203]
	s_mov_b32 m0, s0
	ds_read_b128 v[172:175], v139 offset:16384
	ds_read_b128 v[176:179], v139 offset:17408
	ds_read_b128 v[180:183], v139 offset:18432
	ds_read_b128 v[184:187], v139 offset:19456
	ds_read_b128 v[188:191], v139 offset:20480
	ds_read_b128 v[192:195], v139 offset:21504
	ds_read_b128 v[196:199], v139 offset:22528
	ds_read_b128 v[208:211], v139 offset:23552
	global_load_lds_dwordx4 v[200:201], off
	s_add_i32 m0, s0, 0x2000
	s_add_u32 s0, s18, 0x160000
	v_lshl_add_u64 v[204:205], s[18:19], 0, v[130:131]
	s_addc_u32 s1, s19, 0
	s_add_i32 s2, s33, s24
	global_load_lds_dwordx4 v[204:205], off
	v_lshl_add_u64 v[206:207], s[0:1], 0, v[202:203]
	s_mov_b32 m0, s2
	v_lshl_add_u64 v[212:213], s[20:21], 0, v[130:131]
	global_load_lds_dwordx4 v[206:207], off
	v_lshl_add_u64 v[206:207], s[0:1], 0, v[130:131]
	s_add_i32 m0, s2, 0x2000
	s_nop 0
	global_load_lds_dwordx4 v[206:207], off
	v_lshl_add_u64 v[206:207], s[20:21], 0, v[202:203]
	s_mov_b32 m0, s25
	s_nop 0
	global_load_lds_dwordx4 v[206:207], off
	s_mov_b32 m0, s26
	s_nop 0
	global_load_lds_dwordx4 v[212:213], off
	s_waitcnt vmcnt(8)
	s_waitcnt lgkmcnt(0)
	s_setprio 1
	s_barrier
	v_mfma_f32_16x16x32_bf16 v[62:65], v[140:143], v[172:175], v[62:65]
	v_mfma_f32_16x16x32_bf16 v[58:61], v[148:151], v[172:175], v[58:61]
	v_mfma_f32_16x16x32_bf16 v[54:57], v[140:143], v[180:183], v[54:57]
	v_mfma_f32_16x16x32_bf16 v[50:53], v[148:151], v[180:183], v[50:53]
	v_mfma_f32_16x16x32_bf16 v[38:41], v[140:143], v[188:191], v[38:41]
	v_mfma_f32_16x16x32_bf16 v[34:37], v[148:151], v[188:191], v[34:37]
	v_mfma_f32_16x16x32_bf16 v[22:25], v[140:143], v[196:199], v[22:25]
	v_mfma_f32_16x16x32_bf16 v[18:21], v[148:151], v[196:199], v[18:21]
	v_mfma_f32_16x16x32_bf16 v[62:65], v[144:147], v[176:179], v[62:65]
	v_mfma_f32_16x16x32_bf16 v[58:61], v[152:155], v[176:179], v[58:61]
	v_mfma_f32_16x16x32_bf16 v[54:57], v[144:147], v[184:187], v[54:57]
	v_mfma_f32_16x16x32_bf16 v[50:53], v[152:155], v[184:187], v[50:53]
	v_mfma_f32_16x16x32_bf16 v[38:41], v[144:147], v[192:195], v[38:41]
	v_mfma_f32_16x16x32_bf16 v[34:37], v[152:155], v[192:195], v[34:37]
	v_mfma_f32_16x16x32_bf16 v[22:25], v[144:147], v[208:211], v[22:25]
	v_mfma_f32_16x16x32_bf16 v[18:21], v[152:155], v[208:211], v[18:21]
	s_setprio 0
	s_setprio 1
	v_mfma_f32_16x16x32_bf16 v[46:49], v[156:159], v[172:175], v[46:49]
	v_mfma_f32_16x16x32_bf16 v[42:45], v[164:167], v[172:175], v[42:45]
	v_mfma_f32_16x16x32_bf16 v[30:33], v[156:159], v[180:183], v[30:33]
	v_mfma_f32_16x16x32_bf16 v[26:29], v[164:167], v[180:183], v[26:29]
	v_mfma_f32_16x16x32_bf16 v[14:17], v[156:159], v[188:191], v[14:17]
	v_mfma_f32_16x16x32_bf16 v[10:13], v[164:167], v[188:191], v[10:13]
	v_mfma_f32_16x16x32_bf16 v[6:9], v[156:159], v[196:199], v[6:9]
	v_mfma_f32_16x16x32_bf16 v[2:5], v[164:167], v[196:199], v[2:5]
	v_mfma_f32_16x16x32_bf16 v[46:49], v[160:163], v[176:179], v[46:49]
	v_mfma_f32_16x16x32_bf16 v[42:45], v[168:171], v[176:179], v[42:45]
	v_mfma_f32_16x16x32_bf16 v[30:33], v[160:163], v[184:187], v[30:33]
	v_mfma_f32_16x16x32_bf16 v[26:29], v[168:171], v[184:187], v[26:29]
	v_mfma_f32_16x16x32_bf16 v[14:17], v[160:163], v[192:195], v[14:17]
	v_mfma_f32_16x16x32_bf16 v[10:13], v[168:171], v[192:195], v[10:13]
	v_mfma_f32_16x16x32_bf16 v[6:9], v[160:163], v[208:211], v[6:9]
	v_mfma_f32_16x16x32_bf16 v[2:5], v[168:171], v[208:211], v[2:5]
	s_barrier
	s_setprio 0
	s_add_i32 s2, 0, 0x18000
	s_add_i32 s3, 0, 0x1c000
	v_add_u32_e32 v152, s2, v136
	v_add_u32_e32 v168, s3, v136
	ds_read_b128 v[140:143], v152
	ds_read_b128 v[144:147], v152 offset:1024
	ds_read_b128 v[148:151], v152 offset:2048
	ds_read_b128 v[152:155], v152 offset:3072
	ds_read_b128 v[156:159], v168
	ds_read_b128 v[160:163], v168 offset:1024
	ds_read_b128 v[164:167], v168 offset:2048
	ds_read_b128 v[168:171], v168 offset:3072
	s_add_u32 s0, s20, 0x160000
	s_addc_u32 s1, s21, 0
	s_mov_b32 m0, s27
	v_lshl_add_u64 v[214:215], s[0:1], 0, v[202:203]
	ds_read_b128 v[172:175], v139 offset:32768
	ds_read_b128 v[176:179], v139 offset:33792
	ds_read_b128 v[180:183], v139 offset:34816
	ds_read_b128 v[184:187], v139 offset:35840
	ds_read_b128 v[188:191], v139 offset:36864
	ds_read_b128 v[192:195], v139 offset:37888
	ds_read_b128 v[196:199], v139 offset:38912
	ds_read_b128 v[208:211], v139 offset:39936
	global_load_lds_dwordx4 v[214:215], off
	v_lshl_add_u64 v[214:215], s[0:1], 0, v[130:131]
	s_mov_b32 m0, s28
	s_nop 0
	global_load_lds_dwordx4 v[214:215], off
	s_waitcnt vmcnt(8)
	s_waitcnt lgkmcnt(0)
	s_setprio 1
	s_barrier
	v_mfma_f32_16x16x32_bf16 v[126:129], v[140:143], v[172:175], v[126:129]
	v_mfma_f32_16x16x32_bf16 v[122:125], v[148:151], v[172:175], v[122:125]
	v_mfma_f32_16x16x32_bf16 v[118:121], v[140:143], v[180:183], v[118:121]
	v_mfma_f32_16x16x32_bf16 v[114:117], v[148:151], v[180:183], v[114:117]
	v_mfma_f32_16x16x32_bf16 v[106:109], v[140:143], v[188:191], v[106:109]
	v_mfma_f32_16x16x32_bf16 v[98:101], v[148:151], v[188:191], v[98:101]
	v_mfma_f32_16x16x32_bf16 v[90:93], v[140:143], v[196:199], v[90:93]
	v_mfma_f32_16x16x32_bf16 v[82:85], v[148:151], v[196:199], v[82:85]
	v_mfma_f32_16x16x32_bf16 v[126:129], v[144:147], v[176:179], v[126:129]
	v_mfma_f32_16x16x32_bf16 v[122:125], v[152:155], v[176:179], v[122:125]
	v_mfma_f32_16x16x32_bf16 v[118:121], v[144:147], v[184:187], v[118:121]
	v_mfma_f32_16x16x32_bf16 v[114:117], v[152:155], v[184:187], v[114:117]
	v_mfma_f32_16x16x32_bf16 v[106:109], v[144:147], v[192:195], v[106:109]
	v_mfma_f32_16x16x32_bf16 v[98:101], v[152:155], v[192:195], v[98:101]
	v_mfma_f32_16x16x32_bf16 v[90:93], v[144:147], v[208:211], v[90:93]
	v_mfma_f32_16x16x32_bf16 v[82:85], v[152:155], v[208:211], v[82:85]
	s_setprio 0
	s_setprio 1
	v_mfma_f32_16x16x32_bf16 v[110:113], v[156:159], v[172:175], v[110:113]
	v_mfma_f32_16x16x32_bf16 v[102:105], v[164:167], v[172:175], v[102:105]
	v_mfma_f32_16x16x32_bf16 v[94:97], v[156:159], v[180:183], v[94:97]
	v_mfma_f32_16x16x32_bf16 v[86:89], v[164:167], v[180:183], v[86:89]
	v_mfma_f32_16x16x32_bf16 v[78:81], v[156:159], v[188:191], v[78:81]
	v_mfma_f32_16x16x32_bf16 v[74:77], v[164:167], v[188:191], v[74:77]
	v_mfma_f32_16x16x32_bf16 v[70:73], v[156:159], v[196:199], v[70:73]
	v_mfma_f32_16x16x32_bf16 v[66:69], v[164:167], v[196:199], v[66:69]
	v_mfma_f32_16x16x32_bf16 v[110:113], v[160:163], v[176:179], v[110:113]
	v_mfma_f32_16x16x32_bf16 v[102:105], v[168:171], v[176:179], v[102:105]
	v_mfma_f32_16x16x32_bf16 v[94:97], v[160:163], v[184:187], v[94:97]
	v_mfma_f32_16x16x32_bf16 v[86:89], v[168:171], v[184:187], v[86:89]
	v_mfma_f32_16x16x32_bf16 v[78:81], v[160:163], v[192:195], v[78:81]
	v_mfma_f32_16x16x32_bf16 v[74:77], v[168:171], v[192:195], v[74:77]
	v_mfma_f32_16x16x32_bf16 v[70:73], v[160:163], v[208:211], v[70:73]
	v_mfma_f32_16x16x32_bf16 v[66:69], v[168:171], v[208:211], v[66:69]
	s_barrier
	s_setprio 0
	s_add_i32 s0, s2, s24
	v_lshl_add_u64 v[200:201], v[200:201], 0, s[80:81]
	s_mov_b32 m0, s0
	ds_read_b128 v[172:175], v139 offset:49152
	ds_read_b128 v[176:179], v139 offset:50176
	ds_read_b128 v[180:183], v139 offset:51200
	ds_read_b128 v[184:187], v139 offset:52224
	ds_read_b128 v[188:191], v139 offset:53248
	ds_read_b128 v[192:195], v139 offset:54272
	ds_read_b128 v[196:199], v139 offset:55296
	ds_read_b128 v[208:211], v139 offset:56320
	global_load_lds_dwordx4 v[200:201], off
	s_add_i32 m0, s0, 0x2000
	s_add_u32 s0, s18, 0x160080
	v_lshl_add_u64 v[200:201], v[204:205], 0, s[80:81]
	s_addc_u32 s1, s19, 0
	s_add_i32 s2, s3, s24
	global_load_lds_dwordx4 v[200:201], off
	v_lshl_add_u64 v[200:201], s[0:1], 0, v[202:203]
	s_mov_b32 m0, s2
	s_nop 0
	global_load_lds_dwordx4 v[200:201], off
	v_lshl_add_u64 v[200:201], s[0:1], 0, v[130:131]
	s_add_i32 m0, s2, 0x2000
	s_nop 0
	global_load_lds_dwordx4 v[200:201], off
	v_lshl_add_u64 v[200:201], v[206:207], 0, s[80:81]
	s_mov_b32 m0, s29
	s_nop 0
	global_load_lds_dwordx4 v[200:201], off
	v_lshl_add_u64 v[200:201], v[212:213], 0, s[80:81]
	s_mov_b32 m0, s30
	s_nop 0
	global_load_lds_dwordx4 v[200:201], off
	s_waitcnt vmcnt(8)
	s_waitcnt lgkmcnt(0)
	s_setprio 1
	s_barrier
	v_mfma_f32_16x16x32_bf16 v[62:65], v[140:143], v[172:175], v[62:65]
	v_mfma_f32_16x16x32_bf16 v[58:61], v[148:151], v[172:175], v[58:61]
	v_mfma_f32_16x16x32_bf16 v[54:57], v[140:143], v[180:183], v[54:57]
	v_mfma_f32_16x16x32_bf16 v[50:53], v[148:151], v[180:183], v[50:53]
	v_mfma_f32_16x16x32_bf16 v[38:41], v[140:143], v[188:191], v[38:41]
	v_mfma_f32_16x16x32_bf16 v[34:37], v[148:151], v[188:191], v[34:37]
	v_mfma_f32_16x16x32_bf16 v[22:25], v[140:143], v[196:199], v[22:25]
	v_mfma_f32_16x16x32_bf16 v[18:21], v[148:151], v[196:199], v[18:21]
	v_mfma_f32_16x16x32_bf16 v[62:65], v[144:147], v[176:179], v[62:65]
	v_mfma_f32_16x16x32_bf16 v[58:61], v[152:155], v[176:179], v[58:61]
	v_mfma_f32_16x16x32_bf16 v[54:57], v[144:147], v[184:187], v[54:57]
	v_mfma_f32_16x16x32_bf16 v[50:53], v[152:155], v[184:187], v[50:53]
	v_mfma_f32_16x16x32_bf16 v[38:41], v[144:147], v[192:195], v[38:41]
	v_mfma_f32_16x16x32_bf16 v[34:37], v[152:155], v[192:195], v[34:37]
	v_mfma_f32_16x16x32_bf16 v[22:25], v[144:147], v[208:211], v[22:25]
	v_mfma_f32_16x16x32_bf16 v[18:21], v[152:155], v[208:211], v[18:21]
	s_setprio 0
	s_setprio 1
	v_mfma_f32_16x16x32_bf16 v[46:49], v[156:159], v[172:175], v[46:49]
	v_mfma_f32_16x16x32_bf16 v[42:45], v[164:167], v[172:175], v[42:45]
	v_mfma_f32_16x16x32_bf16 v[30:33], v[156:159], v[180:183], v[30:33]
	v_mfma_f32_16x16x32_bf16 v[26:29], v[164:167], v[180:183], v[26:29]
	v_mfma_f32_16x16x32_bf16 v[14:17], v[156:159], v[188:191], v[14:17]
	v_mfma_f32_16x16x32_bf16 v[10:13], v[164:167], v[188:191], v[10:13]
	v_mfma_f32_16x16x32_bf16 v[6:9], v[156:159], v[196:199], v[6:9]
	v_mfma_f32_16x16x32_bf16 v[2:5], v[164:167], v[196:199], v[2:5]
	v_mfma_f32_16x16x32_bf16 v[46:49], v[160:163], v[176:179], v[46:49]
	v_mfma_f32_16x16x32_bf16 v[42:45], v[168:171], v[176:179], v[42:45]
	v_mfma_f32_16x16x32_bf16 v[30:33], v[160:163], v[184:187], v[30:33]
	v_mfma_f32_16x16x32_bf16 v[26:29], v[168:171], v[184:187], v[26:29]
	v_mfma_f32_16x16x32_bf16 v[14:17], v[160:163], v[192:195], v[14:17]
	v_mfma_f32_16x16x32_bf16 v[10:13], v[168:171], v[192:195], v[10:13]
	v_mfma_f32_16x16x32_bf16 v[6:9], v[160:163], v[208:211], v[6:9]
	v_mfma_f32_16x16x32_bf16 v[2:5], v[168:171], v[208:211], v[2:5]
	s_barrier
	s_setprio 0
	s_add_i32 s59, s59, 2
	s_add_u32 s49, s49, 0x100
	s_addc_u32 s58, s58, 0
	s_cmp_gt_u32 s59, 5
	s_mov_b64 s[2:3], s[4:5]
	s_cbranch_scc0 .LBB0_990
	s_and_b64 vcc, exec, s[10:11]
	s_cbranch_vccz .LBB0_993
	s_barrier

.LBB0_1115:
	ds_read_b128 v[180:183], v147
	ds_read_b128 v[184:187], v147 offset:1024
	ds_read_b128 v[188:191], v147 offset:2048
	ds_read_b128 v[192:195], v147 offset:3072
	ds_read_b128 v[196:199], v147 offset:4096
	ds_read_b128 v[208:211], v147 offset:5120
	ds_read_b128 v[212:215], v147 offset:6144
	ds_read_b128 v[216:219], v147 offset:7168
	s_add_u32 s0, s22, 0xfff80080
	s_addc_u32 s1, s23, -1
	s_add_i32 s33, 0, 0x10000
	s_cmp_eq_u32 s58, 28
	s_cselect_b32 s5, s17, s1
	s_cselect_b32 s4, s39, s0
	v_add_u32_e32 v143, s33, v145
	s_cselect_b32 s3, s15, s49
	s_cselect_b32 s2, s40, s41
	s_add_i32 s55, 0, 0x14000
	ds_read_b128 v[148:151], v143
	ds_read_b128 v[152:155], v143 offset:1024
	ds_read_b128 v[156:159], v143 offset:2048
	ds_read_b128 v[160:163], v143 offset:3072
	v_add_u32_e32 v143, s55, v145
	ds_read_b128 v[164:167], v143
	ds_read_b128 v[168:171], v143 offset:1024
	ds_read_b128 v[172:175], v143 offset:2048
	ds_read_b128 v[176:179], v143 offset:3072
	v_lshl_add_u64 v[200:201], s[22:23], 0, v[138:139]
	s_add_i32 m0, s27, 0xc000
	global_load_lds_dwordx4 v[200:201], off
	v_lshl_add_u64 v[200:201], s[22:23], 0, v[140:141]
	s_add_i32 m0, s27, 0xe000
	s_nop 0
	global_load_lds_dwordx4 v[200:201], off
	s_waitcnt vmcnt(8)
	s_waitcnt lgkmcnt(0)
	s_setprio 1
	s_barrier
	v_mfma_f32_16x16x32_bf16 v[126:129], v[148:151], v[180:183], v[126:129]
	v_mfma_f32_16x16x32_bf16 v[122:125], v[156:159], v[180:183], v[122:125]
	v_mfma_f32_16x16x32_bf16 v[110:113], v[148:151], v[188:191], v[110:113]
	v_mfma_f32_16x16x32_bf16 v[106:109], v[156:159], v[188:191], v[106:109]
	v_mfma_f32_16x16x32_bf16 v[94:97], v[148:151], v[196:199], v[94:97]
	v_mfma_f32_16x16x32_bf16 v[90:93], v[156:159], v[196:199], v[90:93]
	v_mfma_f32_16x16x32_bf16 v[78:81], v[148:151], v[212:215], v[78:81]
	v_mfma_f32_16x16x32_bf16 v[74:77], v[156:159], v[212:215], v[74:77]
	v_mfma_f32_16x16x32_bf16 v[126:129], v[152:155], v[184:187], v[126:129]
	v_mfma_f32_16x16x32_bf16 v[122:125], v[160:163], v[184:187], v[122:125]
	v_mfma_f32_16x16x32_bf16 v[110:113], v[152:155], v[192:195], v[110:113]
	v_mfma_f32_16x16x32_bf16 v[106:109], v[160:163], v[192:195], v[106:109]
	v_mfma_f32_16x16x32_bf16 v[94:97], v[152:155], v[208:211], v[94:97]
	v_mfma_f32_16x16x32_bf16 v[90:93], v[160:163], v[208:211], v[90:93]
	v_mfma_f32_16x16x32_bf16 v[78:81], v[152:155], v[216:219], v[78:81]
	v_mfma_f32_16x16x32_bf16 v[74:77], v[160:163], v[216:219], v[74:77]
	s_setprio 0
	s_setprio 1
	v_mfma_f32_16x16x32_bf16 v[118:121], v[164:167], v[180:183], v[118:121]
	v_mfma_f32_16x16x32_bf16 v[114:117], v[172:175], v[180:183], v[114:117]
	v_mfma_f32_16x16x32_bf16 v[102:105], v[164:167], v[188:191], v[102:105]
	v_mfma_f32_16x16x32_bf16 v[98:101], v[172:175], v[188:191], v[98:101]
	v_mfma_f32_16x16x32_bf16 v[86:89], v[164:167], v[196:199], v[86:89]
	v_mfma_f32_16x16x32_bf16 v[82:85], v[172:175], v[196:199], v[82:85]
	v_mfma_f32_16x16x32_bf16 v[70:73], v[164:167], v[212:215], v[70:73]
	v_mfma_f32_16x16x32_bf16 v[66:69], v[172:175], v[212:215], v[66:69]
	v_mfma_f32_16x16x32_bf16 v[118:121], v[168:171], v[184:187], v[118:121]
	v_mfma_f32_16x16x32_bf16 v[114:117], v[176:179], v[184:187], v[114:117]
	v_mfma_f32_16x16x32_bf16 v[102:105], v[168:171], v[192:195], v[102:105]
	v_mfma_f32_16x16x32_bf16 v[98:101], v[176:179], v[192:195], v[98:101]
	v_mfma_f32_16x16x32_bf16 v[86:89], v[168:171], v[208:211], v[86:89]
	v_mfma_f32_16x16x32_bf16 v[82:85], v[176:179], v[208:211], v[82:85]
	v_mfma_f32_16x16x32_bf16 v[70:73], v[168:171], v[216:219], v[70:73]
	v_mfma_f32_16x16x32_bf16 v[66:69], v[176:179], v[216:219], v[66:69]
	s_barrier
	s_setprio 0
	s_add_i32 s0, s33, s26
	v_lshl_add_u64 v[200:201], s[2:3], 0, v[134:135]
	s_mov_b32 m0, s0
	ds_read_b128 v[180:183], v147 offset:16384
	ds_read_b128 v[184:187], v147 offset:17408
	ds_read_b128 v[188:191], v147 offset:18432
	ds_read_b128 v[192:195], v147 offset:19456
	ds_read_b128 v[196:199], v147 offset:20480
	ds_read_b128 v[208:211], v147 offset:21504
	ds_read_b128 v[212:215], v147 offset:22528
	ds_read_b128 v[216:219], v147 offset:23552
	global_load_lds_dwordx4 v[200:201], off
	s_add_i32 m0, s0, 0x2000
	s_add_u32 s0, s2, 0x80000
	v_lshl_add_u64 v[204:205], s[2:3], 0, v[130:131]
	s_addc_u32 s1, s3, 0
	s_add_i32 s33, s55, s26
	global_load_lds_dwordx4 v[204:205], off
	v_lshl_add_u64 v[206:207], s[0:1], 0, v[134:135]
	s_mov_b32 m0, s33
	v_lshl_add_u64 v[220:221], s[4:5], 0, v[132:133]
	global_load_lds_dwordx4 v[206:207], off
	v_lshl_add_u64 v[206:207], s[0:1], 0, v[130:131]
	s_add_i32 m0, s33, 0x2000
	s_nop 0
	global_load_lds_dwordx4 v[206:207], off
	v_lshl_add_u64 v[206:207], s[4:5], 0, v[136:137]
	s_mov_b32 m0, s27
	s_nop 0
	global_load_lds_dwordx4 v[206:207], off
	s_mov_b32 m0, s28
	s_nop 0
	global_load_lds_dwordx4 v[220:221], off
	s_waitcnt vmcnt(8)
	s_waitcnt lgkmcnt(0)
	s_setprio 1
	s_barrier
	v_mfma_f32_16x16x32_bf16 v[62:65], v[148:151], v[180:183], v[62:65]
	v_mfma_f32_16x16x32_bf16 v[58:61], v[156:159], v[180:183], v[58:61]
	v_mfma_f32_16x16x32_bf16 v[46:49], v[148:151], v[188:191], v[46:49]
	v_mfma_f32_16x16x32_bf16 v[42:45], v[156:159], v[188:191], v[42:45]
	v_mfma_f32_16x16x32_bf16 v[30:33], v[148:151], v[196:199], v[30:33]
	v_mfma_f32_16x16x32_bf16 v[26:29], v[156:159], v[196:199], v[26:29]
	v_mfma_f32_16x16x32_bf16 v[14:17], v[148:151], v[212:215], v[14:17]
	v_mfma_f32_16x16x32_bf16 v[10:13], v[156:159], v[212:215], v[10:13]
	v_mfma_f32_16x16x32_bf16 v[62:65], v[152:155], v[184:187], v[62:65]
	v_mfma_f32_16x16x32_bf16 v[58:61], v[160:163], v[184:187], v[58:61]
	v_mfma_f32_16x16x32_bf16 v[46:49], v[152:155], v[192:195], v[46:49]
	v_mfma_f32_16x16x32_bf16 v[42:45], v[160:163], v[192:195], v[42:45]
	v_mfma_f32_16x16x32_bf16 v[30:33], v[152:155], v[208:211], v[30:33]
	v_mfma_f32_16x16x32_bf16 v[26:29], v[160:163], v[208:211], v[26:29]
	v_mfma_f32_16x16x32_bf16 v[14:17], v[152:155], v[216:219], v[14:17]
	v_mfma_f32_16x16x32_bf16 v[10:13], v[160:163], v[216:219], v[10:13]
	s_setprio 0
	s_setprio 1
	v_mfma_f32_16x16x32_bf16 v[54:57], v[164:167], v[180:183], v[54:57]
	v_mfma_f32_16x16x32_bf16 v[50:53], v[172:175], v[180:183], v[50:53]
	v_mfma_f32_16x16x32_bf16 v[38:41], v[164:167], v[188:191], v[38:41]
	v_mfma_f32_16x16x32_bf16 v[34:37], v[172:175], v[188:191], v[34:37]
	v_mfma_f32_16x16x32_bf16 v[22:25], v[164:167], v[196:199], v[22:25]
	v_mfma_f32_16x16x32_bf16 v[18:21], v[172:175], v[196:199], v[18:21]
	v_mfma_f32_16x16x32_bf16 v[6:9], v[164:167], v[212:215], v[6:9]
	v_mfma_f32_16x16x32_bf16 v[2:5], v[172:175], v[212:215], v[2:5]
	v_mfma_f32_16x16x32_bf16 v[54:57], v[168:171], v[184:187], v[54:57]
	v_mfma_f32_16x16x32_bf16 v[50:53], v[176:179], v[184:187], v[50:53]
	v_mfma_f32_16x16x32_bf16 v[38:41], v[168:171], v[192:195], v[38:41]
	v_mfma_f32_16x16x32_bf16 v[34:37], v[176:179], v[192:195], v[34:37]
	v_mfma_f32_16x16x32_bf16 v[22:25], v[168:171], v[208:211], v[22:25]
	v_mfma_f32_16x16x32_bf16 v[18:21], v[176:179], v[208:211], v[18:21]
	v_mfma_f32_16x16x32_bf16 v[6:9], v[168:171], v[216:219], v[6:9]
	v_mfma_f32_16x16x32_bf16 v[2:5], v[176:179], v[216:219], v[2:5]
	s_barrier
	s_setprio 0
	s_add_i32 s33, 0, 0x18000
	v_add_u32_e32 v143, s33, v145
	s_add_i32 s55, 0, 0x1c000
	ds_read_b128 v[148:151], v143
	ds_read_b128 v[152:155], v143 offset:1024
	ds_read_b128 v[156:159], v143 offset:2048
	ds_read_b128 v[160:163], v143 offset:3072
	v_add_u32_e32 v143, s55, v145
	ds_read_b128 v[164:167], v143
	ds_read_b128 v[168:171], v143 offset:1024
	ds_read_b128 v[172:175], v143 offset:2048
	ds_read_b128 v[176:179], v143 offset:3072
	s_add_u32 s0, s4, 0x80000
	s_addc_u32 s1, s5, 0
	s_mov_b32 m0, s29
	v_lshl_add_u64 v[222:223], s[0:1], 0, v[136:137]
	ds_read_b128 v[180:183], v147 offset:32768
	ds_read_b128 v[184:187], v147 offset:33792
	ds_read_b128 v[188:191], v147 offset:34816
	ds_read_b128 v[192:195], v147 offset:35840
	ds_read_b128 v[196:199], v147 offset:36864
	ds_read_b128 v[208:211], v147 offset:37888
	ds_read_b128 v[212:215], v147 offset:38912
	ds_read_b128 v[216:219], v147 offset:39936
	global_load_lds_dwordx4 v[222:223], off
	v_lshl_add_u64 v[222:223], s[0:1], 0, v[132:133]
	s_mov_b32 m0, s30
	s_nop 0
	global_load_lds_dwordx4 v[222:223], off
	s_waitcnt vmcnt(8)
	s_waitcnt lgkmcnt(0)
	s_setprio 1
	s_barrier
	v_mfma_f32_16x16x32_bf16 v[126:129], v[148:151], v[180:183], v[126:129]
	v_mfma_f32_16x16x32_bf16 v[122:125], v[156:159], v[180:183], v[122:125]
	v_mfma_f32_16x16x32_bf16 v[110:113], v[148:151], v[188:191], v[110:113]
	v_mfma_f32_16x16x32_bf16 v[106:109], v[156:159], v[188:191], v[106:109]
	v_mfma_f32_16x16x32_bf16 v[94:97], v[148:151], v[196:199], v[94:97]
	v_mfma_f32_16x16x32_bf16 v[90:93], v[156:159], v[196:199], v[90:93]
	v_mfma_f32_16x16x32_bf16 v[78:81], v[148:151], v[212:215], v[78:81]
	v_mfma_f32_16x16x32_bf16 v[74:77], v[156:159], v[212:215], v[74:77]
	v_mfma_f32_16x16x32_bf16 v[126:129], v[152:155], v[184:187], v[126:129]
	v_mfma_f32_16x16x32_bf16 v[122:125], v[160:163], v[184:187], v[122:125]
	v_mfma_f32_16x16x32_bf16 v[110:113], v[152:155], v[192:195], v[110:113]
	v_mfma_f32_16x16x32_bf16 v[106:109], v[160:163], v[192:195], v[106:109]
	v_mfma_f32_16x16x32_bf16 v[94:97], v[152:155], v[208:211], v[94:97]
	v_mfma_f32_16x16x32_bf16 v[90:93], v[160:163], v[208:211], v[90:93]
	v_mfma_f32_16x16x32_bf16 v[78:81], v[152:155], v[216:219], v[78:81]
	v_mfma_f32_16x16x32_bf16 v[74:77], v[160:163], v[216:219], v[74:77]
	s_setprio 0
	s_setprio 1
	v_mfma_f32_16x16x32_bf16 v[118:121], v[164:167], v[180:183], v[118:121]
	v_mfma_f32_16x16x32_bf16 v[114:117], v[172:175], v[180:183], v[114:117]
	v_mfma_f32_16x16x32_bf16 v[102:105], v[164:167], v[188:191], v[102:105]
	v_mfma_f32_16x16x32_bf16 v[98:101], v[172:175], v[188:191], v[98:101]
	v_mfma_f32_16x16x32_bf16 v[86:89], v[164:167], v[196:199], v[86:89]
	v_mfma_f32_16x16x32_bf16 v[82:85], v[172:175], v[196:199], v[82:85]
	v_mfma_f32_16x16x32_bf16 v[70:73], v[164:167], v[212:215], v[70:73]
	v_mfma_f32_16x16x32_bf16 v[66:69], v[172:175], v[212:215], v[66:69]
	v_mfma_f32_16x16x32_bf16 v[118:121], v[168:171], v[184:187], v[118:121]
	v_mfma_f32_16x16x32_bf16 v[114:117], v[176:179], v[184:187], v[114:117]
	v_mfma_f32_16x16x32_bf16 v[102:105], v[168:171], v[192:195], v[102:105]
	v_mfma_f32_16x16x32_bf16 v[98:101], v[176:179], v[192:195], v[98:101]
	v_mfma_f32_16x16x32_bf16 v[86:89], v[168:171], v[208:211], v[86:89]
	v_mfma_f32_16x16x32_bf16 v[82:85], v[176:179], v[208:211], v[82:85]
	v_mfma_f32_16x16x32_bf16 v[70:73], v[168:171], v[216:219], v[70:73]
	v_mfma_f32_16x16x32_bf16 v[66:69], v[176:179], v[216:219], v[66:69]
	s_barrier
	s_setprio 0
	s_add_i32 s0, s33, s26
	v_lshl_add_u64 v[200:201], v[200:201], 0, s[80:81]
	s_mov_b32 m0, s0
	ds_read_b128 v[180:183], v147 offset:49152
	ds_read_b128 v[184:187], v147 offset:50176
	ds_read_b128 v[188:191], v147 offset:51200
	ds_read_b128 v[192:195], v147 offset:52224
	ds_read_b128 v[196:199], v147 offset:53248
	ds_read_b128 v[208:211], v147 offset:54272
	ds_read_b128 v[212:215], v147 offset:55296
	ds_read_b128 v[216:219], v147 offset:56320
	global_load_lds_dwordx4 v[200:201], off
	s_add_i32 m0, s0, 0x2000
	s_add_u32 s0, s2, 0x80080
	v_lshl_add_u64 v[200:201], v[204:205], 0, s[80:81]
	s_addc_u32 s1, s3, 0
	s_add_i32 s2, s55, s26
	global_load_lds_dwordx4 v[200:201], off
	v_lshl_add_u64 v[200:201], s[0:1], 0, v[134:135]
	s_mov_b32 m0, s2
	s_nop 0
	global_load_lds_dwordx4 v[200:201], off
	v_lshl_add_u64 v[200:201], s[0:1], 0, v[130:131]
	s_add_i32 m0, s2, 0x2000
	s_nop 0
	global_load_lds_dwordx4 v[200:201], off
	v_lshl_add_u64 v[200:201], v[206:207], 0, s[80:81]
	s_mov_b32 m0, s34
	s_nop 0
	global_load_lds_dwordx4 v[200:201], off
	v_lshl_add_u64 v[200:201], v[220:221], 0, s[80:81]
	s_mov_b32 m0, s35
	s_nop 0
	global_load_lds_dwordx4 v[200:201], off
	s_waitcnt vmcnt(8)
	s_waitcnt lgkmcnt(0)
	s_setprio 1
	s_barrier
	v_mfma_f32_16x16x32_bf16 v[62:65], v[148:151], v[180:183], v[62:65]
	v_mfma_f32_16x16x32_bf16 v[58:61], v[156:159], v[180:183], v[58:61]
	v_mfma_f32_16x16x32_bf16 v[46:49], v[148:151], v[188:191], v[46:49]
	v_mfma_f32_16x16x32_bf16 v[42:45], v[156:159], v[188:191], v[42:45]
	v_mfma_f32_16x16x32_bf16 v[30:33], v[148:151], v[196:199], v[30:33]
	v_mfma_f32_16x16x32_bf16 v[26:29], v[156:159], v[196:199], v[26:29]
	v_mfma_f32_16x16x32_bf16 v[14:17], v[148:151], v[212:215], v[14:17]
	v_mfma_f32_16x16x32_bf16 v[10:13], v[156:159], v[212:215], v[10:13]
	v_mfma_f32_16x16x32_bf16 v[62:65], v[152:155], v[184:187], v[62:65]
	v_mfma_f32_16x16x32_bf16 v[58:61], v[160:163], v[184:187], v[58:61]
	v_mfma_f32_16x16x32_bf16 v[46:49], v[152:155], v[192:195], v[46:49]
	v_mfma_f32_16x16x32_bf16 v[42:45], v[160:163], v[192:195], v[42:45]
	v_mfma_f32_16x16x32_bf16 v[30:33], v[152:155], v[208:211], v[30:33]
	v_mfma_f32_16x16x32_bf16 v[26:29], v[160:163], v[208:211], v[26:29]
	v_mfma_f32_16x16x32_bf16 v[14:17], v[152:155], v[216:219], v[14:17]
	v_mfma_f32_16x16x32_bf16 v[10:13], v[160:163], v[216:219], v[10:13]
	s_setprio 0
	s_setprio 1
	v_mfma_f32_16x16x32_bf16 v[54:57], v[164:167], v[180:183], v[54:57]
	v_mfma_f32_16x16x32_bf16 v[50:53], v[172:175], v[180:183], v[50:53]
	v_mfma_f32_16x16x32_bf16 v[38:41], v[164:167], v[188:191], v[38:41]
	v_mfma_f32_16x16x32_bf16 v[34:37], v[172:175], v[188:191], v[34:37]
	v_mfma_f32_16x16x32_bf16 v[22:25], v[164:167], v[196:199], v[22:25]
	v_mfma_f32_16x16x32_bf16 v[18:21], v[172:175], v[196:199], v[18:21]
	v_mfma_f32_16x16x32_bf16 v[6:9], v[164:167], v[212:215], v[6:9]
	v_mfma_f32_16x16x32_bf16 v[2:5], v[172:175], v[212:215], v[2:5]
	v_mfma_f32_16x16x32_bf16 v[54:57], v[168:171], v[184:187], v[54:57]
	v_mfma_f32_16x16x32_bf16 v[50:53], v[176:179], v[184:187], v[50:53]
	v_mfma_f32_16x16x32_bf16 v[38:41], v[168:171], v[192:195], v[38:41]
	v_mfma_f32_16x16x32_bf16 v[34:37], v[176:179], v[192:195], v[34:37]
	v_mfma_f32_16x16x32_bf16 v[22:25], v[168:171], v[208:211], v[22:25]
	v_mfma_f32_16x16x32_bf16 v[18:21], v[176:179], v[208:211], v[18:21]
	v_mfma_f32_16x16x32_bf16 v[6:9], v[168:171], v[216:219], v[6:9]
	v_mfma_f32_16x16x32_bf16 v[2:5], v[176:179], v[216:219], v[2:5]
	s_barrier
	s_setprio 0
	s_add_i32 s58, s58, 2
	s_add_u32 s22, s22, 0x100
	s_addc_u32 s23, s23, 0
	s_add_u32 s41, s41, 0x100
	s_addc_u32 s49, s49, 0
	s_cmp_gt_u32 s58, 29
	s_cbranch_scc0 .LBB0_1115
	s_and_b64 vcc, exec, s[10:11]
	s_cbranch_vccz .LBB0_1118
	s_barrier

.LBB0_1363:
	ds_read_b128 v[180:183], v146
	ds_read_b128 v[184:187], v146 offset:1024
	ds_read_b128 v[188:191], v146 offset:2048
	ds_read_b128 v[192:195], v146 offset:3072
	ds_read_b128 v[196:199], v146 offset:4096
	ds_read_b128 v[208:211], v146 offset:5120
	ds_read_b128 v[212:215], v146 offset:6144
	ds_read_b128 v[216:219], v146 offset:7168
	s_add_u32 s0, s20, 0xfffe0080
	s_addc_u32 s1, s21, -1
	s_add_i32 s33, 0, 0x10000
	s_cmp_eq_u32 s59, 4
	s_cselect_b32 s5, s38, s1
	s_cselect_b32 s4, s39, s0
	v_add_u32_e32 v147, s33, v143
	s_cselect_b32 s3, s40, s58
	s_cselect_b32 s2, s41, s49
	s_add_i32 s55, 0, 0x14000
	ds_read_b128 v[148:151], v147
	ds_read_b128 v[152:155], v147 offset:1024
	ds_read_b128 v[156:159], v147 offset:2048
	ds_read_b128 v[160:163], v147 offset:3072
	v_add_u32_e32 v147, s55, v143
	ds_read_b128 v[164:167], v147
	ds_read_b128 v[168:171], v147 offset:1024
	ds_read_b128 v[172:175], v147 offset:2048
	ds_read_b128 v[176:179], v147 offset:3072
	v_lshl_add_u64 v[200:201], s[20:21], 0, v[138:139]
	s_add_i32 m0, s25, 0xc000
	global_load_lds_dwordx4 v[200:201], off
	v_lshl_add_u64 v[200:201], s[20:21], 0, v[140:141]
	s_add_i32 m0, s25, 0xe000
	s_nop 0
	global_load_lds_dwordx4 v[200:201], off
	s_waitcnt vmcnt(8)
	s_waitcnt lgkmcnt(0)
	s_setprio 1
	s_barrier
	v_mfma_f32_16x16x32_bf16 v[126:129], v[148:151], v[180:183], v[126:129]
	v_mfma_f32_16x16x32_bf16 v[122:125], v[156:159], v[180:183], v[122:125]
	v_mfma_f32_16x16x32_bf16 v[110:113], v[148:151], v[188:191], v[110:113]
	v_mfma_f32_16x16x32_bf16 v[106:109], v[156:159], v[188:191], v[106:109]
	v_mfma_f32_16x16x32_bf16 v[94:97], v[148:151], v[196:199], v[94:97]
	v_mfma_f32_16x16x32_bf16 v[90:93], v[156:159], v[196:199], v[90:93]
	v_mfma_f32_16x16x32_bf16 v[78:81], v[148:151], v[212:215], v[78:81]
	v_mfma_f32_16x16x32_bf16 v[74:77], v[156:159], v[212:215], v[74:77]
	v_mfma_f32_16x16x32_bf16 v[126:129], v[152:155], v[184:187], v[126:129]
	v_mfma_f32_16x16x32_bf16 v[122:125], v[160:163], v[184:187], v[122:125]
	v_mfma_f32_16x16x32_bf16 v[110:113], v[152:155], v[192:195], v[110:113]
	v_mfma_f32_16x16x32_bf16 v[106:109], v[160:163], v[192:195], v[106:109]
	v_mfma_f32_16x16x32_bf16 v[94:97], v[152:155], v[208:211], v[94:97]
	v_mfma_f32_16x16x32_bf16 v[90:93], v[160:163], v[208:211], v[90:93]
	v_mfma_f32_16x16x32_bf16 v[78:81], v[152:155], v[216:219], v[78:81]
	v_mfma_f32_16x16x32_bf16 v[74:77], v[160:163], v[216:219], v[74:77]
	s_setprio 0
	s_setprio 1
	v_mfma_f32_16x16x32_bf16 v[118:121], v[164:167], v[180:183], v[118:121]
	v_mfma_f32_16x16x32_bf16 v[114:117], v[172:175], v[180:183], v[114:117]
	v_mfma_f32_16x16x32_bf16 v[102:105], v[164:167], v[188:191], v[102:105]
	v_mfma_f32_16x16x32_bf16 v[98:101], v[172:175], v[188:191], v[98:101]
	v_mfma_f32_16x16x32_bf16 v[86:89], v[164:167], v[196:199], v[86:89]
	v_mfma_f32_16x16x32_bf16 v[82:85], v[172:175], v[196:199], v[82:85]
	v_mfma_f32_16x16x32_bf16 v[70:73], v[164:167], v[212:215], v[70:73]
	v_mfma_f32_16x16x32_bf16 v[66:69], v[172:175], v[212:215], v[66:69]
	v_mfma_f32_16x16x32_bf16 v[118:121], v[168:171], v[184:187], v[118:121]
	v_mfma_f32_16x16x32_bf16 v[114:117], v[176:179], v[184:187], v[114:117]
	v_mfma_f32_16x16x32_bf16 v[102:105], v[168:171], v[192:195], v[102:105]
	v_mfma_f32_16x16x32_bf16 v[98:101], v[176:179], v[192:195], v[98:101]
	v_mfma_f32_16x16x32_bf16 v[86:89], v[168:171], v[208:211], v[86:89]
	v_mfma_f32_16x16x32_bf16 v[82:85], v[176:179], v[208:211], v[82:85]
	v_mfma_f32_16x16x32_bf16 v[70:73], v[168:171], v[216:219], v[70:73]
	v_mfma_f32_16x16x32_bf16 v[66:69], v[176:179], v[216:219], v[66:69]
	s_barrier
	s_setprio 0
	s_add_i32 s0, s33, s24
	v_lshl_add_u64 v[200:201], s[2:3], 0, v[134:135]
	s_mov_b32 m0, s0
	ds_read_b128 v[180:183], v146 offset:16384
	ds_read_b128 v[184:187], v146 offset:17408
	ds_read_b128 v[188:191], v146 offset:18432
	ds_read_b128 v[192:195], v146 offset:19456
	ds_read_b128 v[196:199], v146 offset:20480
	ds_read_b128 v[208:211], v146 offset:21504
	ds_read_b128 v[212:215], v146 offset:22528
	ds_read_b128 v[216:219], v146 offset:23552
	global_load_lds_dwordx4 v[200:201], off
	s_add_i32 m0, s0, 0x2000
	s_add_u32 s0, s2, 0x20000
	v_lshl_add_u64 v[204:205], s[2:3], 0, v[130:131]
	s_addc_u32 s1, s3, 0
	s_add_i32 s33, s55, s24
	global_load_lds_dwordx4 v[204:205], off
	v_lshl_add_u64 v[206:207], s[0:1], 0, v[134:135]
	s_mov_b32 m0, s33
	v_lshl_add_u64 v[220:221], s[4:5], 0, v[132:133]
	global_load_lds_dwordx4 v[206:207], off
	v_lshl_add_u64 v[206:207], s[0:1], 0, v[130:131]
	s_add_i32 m0, s33, 0x2000
	s_nop 0
	global_load_lds_dwordx4 v[206:207], off
	v_lshl_add_u64 v[206:207], s[4:5], 0, v[136:137]
	s_mov_b32 m0, s25
	s_nop 0
	global_load_lds_dwordx4 v[206:207], off
	s_mov_b32 m0, s26
	s_nop 0
	global_load_lds_dwordx4 v[220:221], off
	s_waitcnt vmcnt(8)
	s_waitcnt lgkmcnt(0)
	s_setprio 1
	s_barrier
	v_mfma_f32_16x16x32_bf16 v[62:65], v[148:151], v[180:183], v[62:65]
	v_mfma_f32_16x16x32_bf16 v[58:61], v[156:159], v[180:183], v[58:61]
	v_mfma_f32_16x16x32_bf16 v[46:49], v[148:151], v[188:191], v[46:49]
	v_mfma_f32_16x16x32_bf16 v[42:45], v[156:159], v[188:191], v[42:45]
	v_mfma_f32_16x16x32_bf16 v[30:33], v[148:151], v[196:199], v[30:33]
	v_mfma_f32_16x16x32_bf16 v[26:29], v[156:159], v[196:199], v[26:29]
	v_mfma_f32_16x16x32_bf16 v[14:17], v[148:151], v[212:215], v[14:17]
	v_mfma_f32_16x16x32_bf16 v[10:13], v[156:159], v[212:215], v[10:13]
	v_mfma_f32_16x16x32_bf16 v[62:65], v[152:155], v[184:187], v[62:65]
	v_mfma_f32_16x16x32_bf16 v[58:61], v[160:163], v[184:187], v[58:61]
	v_mfma_f32_16x16x32_bf16 v[46:49], v[152:155], v[192:195], v[46:49]
	v_mfma_f32_16x16x32_bf16 v[42:45], v[160:163], v[192:195], v[42:45]
	v_mfma_f32_16x16x32_bf16 v[30:33], v[152:155], v[208:211], v[30:33]
	v_mfma_f32_16x16x32_bf16 v[26:29], v[160:163], v[208:211], v[26:29]
	v_mfma_f32_16x16x32_bf16 v[14:17], v[152:155], v[216:219], v[14:17]
	v_mfma_f32_16x16x32_bf16 v[10:13], v[160:163], v[216:219], v[10:13]
	s_setprio 0
	s_setprio 1
	v_mfma_f32_16x16x32_bf16 v[54:57], v[164:167], v[180:183], v[54:57]
	v_mfma_f32_16x16x32_bf16 v[50:53], v[172:175], v[180:183], v[50:53]
	v_mfma_f32_16x16x32_bf16 v[38:41], v[164:167], v[188:191], v[38:41]
	v_mfma_f32_16x16x32_bf16 v[34:37], v[172:175], v[188:191], v[34:37]
	v_mfma_f32_16x16x32_bf16 v[22:25], v[164:167], v[196:199], v[22:25]
	v_mfma_f32_16x16x32_bf16 v[18:21], v[172:175], v[196:199], v[18:21]
	v_mfma_f32_16x16x32_bf16 v[6:9], v[164:167], v[212:215], v[6:9]
	v_mfma_f32_16x16x32_bf16 v[2:5], v[172:175], v[212:215], v[2:5]
	v_mfma_f32_16x16x32_bf16 v[54:57], v[168:171], v[184:187], v[54:57]
	v_mfma_f32_16x16x32_bf16 v[50:53], v[176:179], v[184:187], v[50:53]
	v_mfma_f32_16x16x32_bf16 v[38:41], v[168:171], v[192:195], v[38:41]
	v_mfma_f32_16x16x32_bf16 v[34:37], v[176:179], v[192:195], v[34:37]
	v_mfma_f32_16x16x32_bf16 v[22:25], v[168:171], v[208:211], v[22:25]
	v_mfma_f32_16x16x32_bf16 v[18:21], v[176:179], v[208:211], v[18:21]
	v_mfma_f32_16x16x32_bf16 v[6:9], v[168:171], v[216:219], v[6:9]
	v_mfma_f32_16x16x32_bf16 v[2:5], v[176:179], v[216:219], v[2:5]
	s_barrier
	s_setprio 0
	s_add_i32 s33, 0, 0x18000
	v_add_u32_e32 v147, s33, v143
	s_add_i32 s55, 0, 0x1c000
	ds_read_b128 v[148:151], v147
	ds_read_b128 v[152:155], v147 offset:1024
	ds_read_b128 v[156:159], v147 offset:2048
	ds_read_b128 v[160:163], v147 offset:3072
	v_add_u32_e32 v147, s55, v143
	ds_read_b128 v[164:167], v147
	ds_read_b128 v[168:171], v147 offset:1024
	ds_read_b128 v[172:175], v147 offset:2048
	ds_read_b128 v[176:179], v147 offset:3072
	s_add_u32 s0, s4, 0x20000
	s_addc_u32 s1, s5, 0
	s_mov_b32 m0, s27
	v_lshl_add_u64 v[222:223], s[0:1], 0, v[136:137]
	ds_read_b128 v[180:183], v146 offset:32768
	ds_read_b128 v[184:187], v146 offset:33792
	ds_read_b128 v[188:191], v146 offset:34816
	ds_read_b128 v[192:195], v146 offset:35840
	ds_read_b128 v[196:199], v146 offset:36864
	ds_read_b128 v[208:211], v146 offset:37888
	ds_read_b128 v[212:215], v146 offset:38912
	ds_read_b128 v[216:219], v146 offset:39936
	global_load_lds_dwordx4 v[222:223], off
	v_lshl_add_u64 v[222:223], s[0:1], 0, v[132:133]
	s_mov_b32 m0, s28
	s_nop 0
	global_load_lds_dwordx4 v[222:223], off
	s_waitcnt vmcnt(8)
	s_waitcnt lgkmcnt(0)
	s_setprio 1
	s_barrier
	v_mfma_f32_16x16x32_bf16 v[126:129], v[148:151], v[180:183], v[126:129]
	v_mfma_f32_16x16x32_bf16 v[122:125], v[156:159], v[180:183], v[122:125]
	v_mfma_f32_16x16x32_bf16 v[110:113], v[148:151], v[188:191], v[110:113]
	v_mfma_f32_16x16x32_bf16 v[106:109], v[156:159], v[188:191], v[106:109]
	v_mfma_f32_16x16x32_bf16 v[94:97], v[148:151], v[196:199], v[94:97]
	v_mfma_f32_16x16x32_bf16 v[90:93], v[156:159], v[196:199], v[90:93]
	v_mfma_f32_16x16x32_bf16 v[78:81], v[148:151], v[212:215], v[78:81]
	v_mfma_f32_16x16x32_bf16 v[74:77], v[156:159], v[212:215], v[74:77]
	v_mfma_f32_16x16x32_bf16 v[126:129], v[152:155], v[184:187], v[126:129]
	v_mfma_f32_16x16x32_bf16 v[122:125], v[160:163], v[184:187], v[122:125]
	v_mfma_f32_16x16x32_bf16 v[110:113], v[152:155], v[192:195], v[110:113]
	v_mfma_f32_16x16x32_bf16 v[106:109], v[160:163], v[192:195], v[106:109]
	v_mfma_f32_16x16x32_bf16 v[94:97], v[152:155], v[208:211], v[94:97]
	v_mfma_f32_16x16x32_bf16 v[90:93], v[160:163], v[208:211], v[90:93]
	v_mfma_f32_16x16x32_bf16 v[78:81], v[152:155], v[216:219], v[78:81]
	v_mfma_f32_16x16x32_bf16 v[74:77], v[160:163], v[216:219], v[74:77]
	s_setprio 0
	s_setprio 1
	v_mfma_f32_16x16x32_bf16 v[118:121], v[164:167], v[180:183], v[118:121]
	v_mfma_f32_16x16x32_bf16 v[114:117], v[172:175], v[180:183], v[114:117]
	v_mfma_f32_16x16x32_bf16 v[102:105], v[164:167], v[188:191], v[102:105]
	v_mfma_f32_16x16x32_bf16 v[98:101], v[172:175], v[188:191], v[98:101]
	v_mfma_f32_16x16x32_bf16 v[86:89], v[164:167], v[196:199], v[86:89]
	v_mfma_f32_16x16x32_bf16 v[82:85], v[172:175], v[196:199], v[82:85]
	v_mfma_f32_16x16x32_bf16 v[70:73], v[164:167], v[212:215], v[70:73]
	v_mfma_f32_16x16x32_bf16 v[66:69], v[172:175], v[212:215], v[66:69]
	v_mfma_f32_16x16x32_bf16 v[118:121], v[168:171], v[184:187], v[118:121]
	v_mfma_f32_16x16x32_bf16 v[114:117], v[176:179], v[184:187], v[114:117]
	v_mfma_f32_16x16x32_bf16 v[102:105], v[168:171], v[192:195], v[102:105]
	v_mfma_f32_16x16x32_bf16 v[98:101], v[176:179], v[192:195], v[98:101]
	v_mfma_f32_16x16x32_bf16 v[86:89], v[168:171], v[208:211], v[86:89]
	v_mfma_f32_16x16x32_bf16 v[82:85], v[176:179], v[208:211], v[82:85]
	v_mfma_f32_16x16x32_bf16 v[70:73], v[168:171], v[216:219], v[70:73]
	v_mfma_f32_16x16x32_bf16 v[66:69], v[176:179], v[216:219], v[66:69]
	s_barrier
	s_setprio 0
	s_add_i32 s0, s33, s24
	v_lshl_add_u64 v[200:201], v[200:201], 0, s[80:81]
	s_mov_b32 m0, s0
	ds_read_b128 v[180:183], v146 offset:49152
	ds_read_b128 v[184:187], v146 offset:50176
	ds_read_b128 v[188:191], v146 offset:51200
	ds_read_b128 v[192:195], v146 offset:52224
	ds_read_b128 v[196:199], v146 offset:53248
	ds_read_b128 v[208:211], v146 offset:54272
	ds_read_b128 v[212:215], v146 offset:55296
	ds_read_b128 v[216:219], v146 offset:56320
	global_load_lds_dwordx4 v[200:201], off
	s_add_i32 m0, s0, 0x2000
	s_add_u32 s0, s2, 0x20080
	v_lshl_add_u64 v[200:201], v[204:205], 0, s[80:81]
	s_addc_u32 s1, s3, 0
	s_add_i32 s2, s55, s24
	global_load_lds_dwordx4 v[200:201], off
	v_lshl_add_u64 v[200:201], s[0:1], 0, v[134:135]
	s_mov_b32 m0, s2
	s_nop 0
	global_load_lds_dwordx4 v[200:201], off
	v_lshl_add_u64 v[200:201], s[0:1], 0, v[130:131]
	s_add_i32 m0, s2, 0x2000
	s_nop 0
	global_load_lds_dwordx4 v[200:201], off
	v_lshl_add_u64 v[200:201], v[206:207], 0, s[80:81]
	s_mov_b32 m0, s29
	s_nop 0
	global_load_lds_dwordx4 v[200:201], off
	v_lshl_add_u64 v[200:201], v[220:221], 0, s[80:81]
	s_mov_b32 m0, s30
	s_nop 0
	global_load_lds_dwordx4 v[200:201], off
	s_waitcnt vmcnt(8)
	s_waitcnt lgkmcnt(0)
	s_setprio 1
	s_barrier
	v_mfma_f32_16x16x32_bf16 v[62:65], v[148:151], v[180:183], v[62:65]
	v_mfma_f32_16x16x32_bf16 v[58:61], v[156:159], v[180:183], v[58:61]
	v_mfma_f32_16x16x32_bf16 v[46:49], v[148:151], v[188:191], v[46:49]
	v_mfma_f32_16x16x32_bf16 v[42:45], v[156:159], v[188:191], v[42:45]
	v_mfma_f32_16x16x32_bf16 v[30:33], v[148:151], v[196:199], v[30:33]
	v_mfma_f32_16x16x32_bf16 v[26:29], v[156:159], v[196:199], v[26:29]
	v_mfma_f32_16x16x32_bf16 v[14:17], v[148:151], v[212:215], v[14:17]
	v_mfma_f32_16x16x32_bf16 v[10:13], v[156:159], v[212:215], v[10:13]
	v_mfma_f32_16x16x32_bf16 v[62:65], v[152:155], v[184:187], v[62:65]
	v_mfma_f32_16x16x32_bf16 v[58:61], v[160:163], v[184:187], v[58:61]
	v_mfma_f32_16x16x32_bf16 v[46:49], v[152:155], v[192:195], v[46:49]
	v_mfma_f32_16x16x32_bf16 v[42:45], v[160:163], v[192:195], v[42:45]
	v_mfma_f32_16x16x32_bf16 v[30:33], v[152:155], v[208:211], v[30:33]
	v_mfma_f32_16x16x32_bf16 v[26:29], v[160:163], v[208:211], v[26:29]
	v_mfma_f32_16x16x32_bf16 v[14:17], v[152:155], v[216:219], v[14:17]
	v_mfma_f32_16x16x32_bf16 v[10:13], v[160:163], v[216:219], v[10:13]
	s_setprio 0
	s_setprio 1
	v_mfma_f32_16x16x32_bf16 v[54:57], v[164:167], v[180:183], v[54:57]
	v_mfma_f32_16x16x32_bf16 v[50:53], v[172:175], v[180:183], v[50:53]
	v_mfma_f32_16x16x32_bf16 v[38:41], v[164:167], v[188:191], v[38:41]
	v_mfma_f32_16x16x32_bf16 v[34:37], v[172:175], v[188:191], v[34:37]
	v_mfma_f32_16x16x32_bf16 v[22:25], v[164:167], v[196:199], v[22:25]
	v_mfma_f32_16x16x32_bf16 v[18:21], v[172:175], v[196:199], v[18:21]
	v_mfma_f32_16x16x32_bf16 v[6:9], v[164:167], v[212:215], v[6:9]
	v_mfma_f32_16x16x32_bf16 v[2:5], v[172:175], v[212:215], v[2:5]
	v_mfma_f32_16x16x32_bf16 v[54:57], v[168:171], v[184:187], v[54:57]
	v_mfma_f32_16x16x32_bf16 v[50:53], v[176:179], v[184:187], v[50:53]
	v_mfma_f32_16x16x32_bf16 v[38:41], v[168:171], v[192:195], v[38:41]
	v_mfma_f32_16x16x32_bf16 v[34:37], v[176:179], v[192:195], v[34:37]
	v_mfma_f32_16x16x32_bf16 v[22:25], v[168:171], v[208:211], v[22:25]
	v_mfma_f32_16x16x32_bf16 v[18:21], v[176:179], v[208:211], v[18:21]
	v_mfma_f32_16x16x32_bf16 v[6:9], v[168:171], v[216:219], v[6:9]
	v_mfma_f32_16x16x32_bf16 v[2:5], v[176:179], v[216:219], v[2:5]
	s_barrier
	s_setprio 0
	s_add_i32 s59, s59, 2
	s_add_u32 s20, s20, 0x100
	s_addc_u32 s21, s21, 0
	s_add_u32 s49, s49, 0x100
	s_addc_u32 s58, s58, 0
	s_cmp_gt_u32 s59, 5
	s_cbranch_scc0 .LBB0_1363
	s_and_b64 vcc, exec, s[14:15]
	s_cbranch_vccz .LBB0_1366
	s_barrier

.LBB0_1428:
	ds_read_b128 v[172:175], v189
	ds_read_b128 v[176:179], v189 offset:1024
	ds_read_b128 v[180:183], v189 offset:2048
	ds_read_b128 v[190:193], v189 offset:3072
	ds_read_b128 v[194:197], v189 offset:4096
	ds_read_b128 v[198:201], v189 offset:5120
	ds_read_b128 v[208:211], v189 offset:6144
	ds_read_b128 v[212:215], v189 offset:7168
	s_add_u32 s0, s26, 0xfff80080
	s_addc_u32 s1, s27, -1
	s_add_i32 s33, 0, 0x10000
	s_cmp_eq_u32 s61, 28
	s_cselect_b32 s5, s17, s1
	s_cselect_b32 s4, s49, s0
	s_cselect_b32 s3, s15, s60
	s_cselect_b32 s2, s58, s59
	s_add_i32 s55, 0, 0x14000
	v_add_u32_e32 v142, s33, v187
	v_add_u32_e32 v158, s55, v187
	ds_read_b128 v[126:129], v142
	ds_read_b128 v[134:137], v142 offset:1024
	ds_read_b128 v[138:141], v142 offset:2048
	ds_read_b128 v[142:145], v142 offset:3072
	ds_read_b128 v[146:149], v158
	ds_read_b128 v[150:153], v158 offset:1024
	ds_read_b128 v[154:157], v158 offset:2048
	ds_read_b128 v[158:161], v158 offset:3072
	v_lshl_add_u64 v[184:185], s[26:27], 0, v[168:169]
	s_add_i32 m0, s23, 0xc000
	global_load_lds_dwordx4 v[184:185], off
	v_lshl_add_u64 v[184:185], s[26:27], 0, v[170:171]
	s_add_i32 m0, s23, 0xe000
	s_nop 0
	global_load_lds_dwordx4 v[184:185], off
	s_waitcnt vmcnt(8)
	s_waitcnt lgkmcnt(0)
	s_setprio 1
	s_barrier
	v_mfma_f32_16x16x32_bf16 v[130:133], v[126:129], v[172:175], v[130:133]
	v_mfma_f32_16x16x32_bf16 v[118:121], v[138:141], v[172:175], v[118:121]
	v_mfma_f32_16x16x32_bf16 v[110:113], v[126:129], v[180:183], v[110:113]
	v_mfma_f32_16x16x32_bf16 v[102:105], v[138:141], v[180:183], v[102:105]
	v_mfma_f32_16x16x32_bf16 v[94:97], v[126:129], v[194:197], v[94:97]
	v_mfma_f32_16x16x32_bf16 v[86:89], v[138:141], v[194:197], v[86:89]
	v_mfma_f32_16x16x32_bf16 v[78:81], v[126:129], v[208:211], v[78:81]
	v_mfma_f32_16x16x32_bf16 v[70:73], v[138:141], v[208:211], v[70:73]
	v_mfma_f32_16x16x32_bf16 v[130:133], v[134:137], v[176:179], v[130:133]
	v_mfma_f32_16x16x32_bf16 v[118:121], v[142:145], v[176:179], v[118:121]
	v_mfma_f32_16x16x32_bf16 v[110:113], v[134:137], v[190:193], v[110:113]
	v_mfma_f32_16x16x32_bf16 v[102:105], v[142:145], v[190:193], v[102:105]
	v_mfma_f32_16x16x32_bf16 v[94:97], v[134:137], v[198:201], v[94:97]
	v_mfma_f32_16x16x32_bf16 v[86:89], v[142:145], v[198:201], v[86:89]
	v_mfma_f32_16x16x32_bf16 v[78:81], v[134:137], v[212:215], v[78:81]
	v_mfma_f32_16x16x32_bf16 v[70:73], v[142:145], v[212:215], v[70:73]
	s_setprio 0
	s_setprio 1
	v_mfma_f32_16x16x32_bf16 v[122:125], v[146:149], v[172:175], v[122:125]
	v_mfma_f32_16x16x32_bf16 v[114:117], v[154:157], v[172:175], v[114:117]
	v_mfma_f32_16x16x32_bf16 v[106:109], v[146:149], v[180:183], v[106:109]
	v_mfma_f32_16x16x32_bf16 v[98:101], v[154:157], v[180:183], v[98:101]
	v_mfma_f32_16x16x32_bf16 v[90:93], v[146:149], v[194:197], v[90:93]
	v_mfma_f32_16x16x32_bf16 v[82:85], v[154:157], v[194:197], v[82:85]
	v_mfma_f32_16x16x32_bf16 v[74:77], v[146:149], v[208:211], v[74:77]
	v_mfma_f32_16x16x32_bf16 v[66:69], v[154:157], v[208:211], v[66:69]
	v_mfma_f32_16x16x32_bf16 v[122:125], v[150:153], v[176:179], v[122:125]
	v_mfma_f32_16x16x32_bf16 v[114:117], v[158:161], v[176:179], v[114:117]
	v_mfma_f32_16x16x32_bf16 v[106:109], v[150:153], v[190:193], v[106:109]
	v_mfma_f32_16x16x32_bf16 v[98:101], v[158:161], v[190:193], v[98:101]
	v_mfma_f32_16x16x32_bf16 v[90:93], v[150:153], v[198:201], v[90:93]
	v_mfma_f32_16x16x32_bf16 v[82:85], v[158:161], v[198:201], v[82:85]
	v_mfma_f32_16x16x32_bf16 v[74:77], v[150:153], v[212:215], v[74:77]
	v_mfma_f32_16x16x32_bf16 v[66:69], v[158:161], v[212:215], v[66:69]
	s_barrier
	s_setprio 0
	s_add_i32 s0, s33, s34
	v_lshl_add_u64 v[184:185], s[2:3], 0, v[202:203]
	s_mov_b32 m0, s0
	ds_read_b128 v[172:175], v189 offset:16384
	ds_read_b128 v[176:179], v189 offset:17408
	ds_read_b128 v[180:183], v189 offset:18432
	ds_read_b128 v[190:193], v189 offset:19456
	ds_read_b128 v[194:197], v189 offset:20480
	ds_read_b128 v[198:201], v189 offset:21504
	ds_read_b128 v[208:211], v189 offset:22528
	ds_read_b128 v[212:215], v189 offset:23552
	global_load_lds_dwordx4 v[184:185], off
	s_add_i32 m0, s0, 0x2000
	s_add_u32 s0, s2, 0x80000
	v_lshl_add_u64 v[204:205], s[2:3], 0, v[162:163]
	s_addc_u32 s1, s3, 0
	s_add_i32 s33, s55, s34
	global_load_lds_dwordx4 v[204:205], off
	v_lshl_add_u64 v[206:207], s[0:1], 0, v[202:203]
	s_mov_b32 m0, s33
	v_lshl_add_u64 v[216:217], s[4:5], 0, v[164:165]
	global_load_lds_dwordx4 v[206:207], off
	v_lshl_add_u64 v[206:207], s[0:1], 0, v[162:163]
	s_add_i32 m0, s33, 0x2000
	s_nop 0
	global_load_lds_dwordx4 v[206:207], off
	v_lshl_add_u64 v[206:207], s[4:5], 0, v[166:167]
	s_mov_b32 m0, s23
	s_nop 0
	global_load_lds_dwordx4 v[206:207], off
	s_mov_b32 m0, s25
	s_nop 0
	global_load_lds_dwordx4 v[216:217], off
	s_waitcnt vmcnt(8)
	s_waitcnt lgkmcnt(0)
	s_setprio 1
	s_barrier
	v_mfma_f32_16x16x32_bf16 v[62:65], v[126:129], v[172:175], v[62:65]
	v_mfma_f32_16x16x32_bf16 v[54:57], v[138:141], v[172:175], v[54:57]
	v_mfma_f32_16x16x32_bf16 v[46:49], v[126:129], v[180:183], v[46:49]
	v_mfma_f32_16x16x32_bf16 v[38:41], v[138:141], v[180:183], v[38:41]
	v_mfma_f32_16x16x32_bf16 v[30:33], v[126:129], v[194:197], v[30:33]
	v_mfma_f32_16x16x32_bf16 v[22:25], v[138:141], v[194:197], v[22:25]
	v_mfma_f32_16x16x32_bf16 v[14:17], v[126:129], v[208:211], v[14:17]
	v_mfma_f32_16x16x32_bf16 v[6:9], v[138:141], v[208:211], v[6:9]
	v_mfma_f32_16x16x32_bf16 v[62:65], v[134:137], v[176:179], v[62:65]
	v_mfma_f32_16x16x32_bf16 v[54:57], v[142:145], v[176:179], v[54:57]
	v_mfma_f32_16x16x32_bf16 v[46:49], v[134:137], v[190:193], v[46:49]
	v_mfma_f32_16x16x32_bf16 v[38:41], v[142:145], v[190:193], v[38:41]
	v_mfma_f32_16x16x32_bf16 v[30:33], v[134:137], v[198:201], v[30:33]
	v_mfma_f32_16x16x32_bf16 v[22:25], v[142:145], v[198:201], v[22:25]
	v_mfma_f32_16x16x32_bf16 v[14:17], v[134:137], v[212:215], v[14:17]
	v_mfma_f32_16x16x32_bf16 v[6:9], v[142:145], v[212:215], v[6:9]
	s_setprio 0
	s_setprio 1
	v_mfma_f32_16x16x32_bf16 v[58:61], v[146:149], v[172:175], v[58:61]
	v_mfma_f32_16x16x32_bf16 v[50:53], v[154:157], v[172:175], v[50:53]
	v_mfma_f32_16x16x32_bf16 v[42:45], v[146:149], v[180:183], v[42:45]
	v_mfma_f32_16x16x32_bf16 v[34:37], v[154:157], v[180:183], v[34:37]
	v_mfma_f32_16x16x32_bf16 v[26:29], v[146:149], v[194:197], v[26:29]
	v_mfma_f32_16x16x32_bf16 v[18:21], v[154:157], v[194:197], v[18:21]
	v_mfma_f32_16x16x32_bf16 v[10:13], v[146:149], v[208:211], v[10:13]
	v_mfma_f32_16x16x32_bf16 v[2:5], v[154:157], v[208:211], v[2:5]
	v_mfma_f32_16x16x32_bf16 v[58:61], v[150:153], v[176:179], v[58:61]
	v_mfma_f32_16x16x32_bf16 v[50:53], v[158:161], v[176:179], v[50:53]
	v_mfma_f32_16x16x32_bf16 v[42:45], v[150:153], v[190:193], v[42:45]
	v_mfma_f32_16x16x32_bf16 v[34:37], v[158:161], v[190:193], v[34:37]
	v_mfma_f32_16x16x32_bf16 v[26:29], v[150:153], v[198:201], v[26:29]
	v_mfma_f32_16x16x32_bf16 v[18:21], v[158:161], v[198:201], v[18:21]
	v_mfma_f32_16x16x32_bf16 v[10:13], v[150:153], v[212:215], v[10:13]
	v_mfma_f32_16x16x32_bf16 v[2:5], v[158:161], v[212:215], v[2:5]
	s_barrier
	s_setprio 0
	s_add_i32 s33, 0, 0x18000
	s_add_i32 s55, 0, 0x1c000
	v_add_u32_e32 v142, s33, v187
	v_add_u32_e32 v158, s55, v187
	ds_read_b128 v[126:129], v142
	ds_read_b128 v[134:137], v142 offset:1024
	ds_read_b128 v[138:141], v142 offset:2048
	ds_read_b128 v[142:145], v142 offset:3072
	ds_read_b128 v[146:149], v158
	ds_read_b128 v[150:153], v158 offset:1024
	ds_read_b128 v[154:157], v158 offset:2048
	ds_read_b128 v[158:161], v158 offset:3072
	s_add_u32 s0, s4, 0x80000
	s_addc_u32 s1, s5, 0
	s_mov_b32 m0, s35
	v_lshl_add_u64 v[218:219], s[0:1], 0, v[166:167]
	ds_read_b128 v[172:175], v189 offset:32768
	ds_read_b128 v[176:179], v189 offset:33792
	ds_read_b128 v[180:183], v189 offset:34816
	ds_read_b128 v[190:193], v189 offset:35840
	ds_read_b128 v[194:197], v189 offset:36864
	ds_read_b128 v[198:201], v189 offset:37888
	ds_read_b128 v[208:211], v189 offset:38912
	ds_read_b128 v[212:215], v189 offset:39936
	global_load_lds_dwordx4 v[218:219], off
	v_lshl_add_u64 v[218:219], s[0:1], 0, v[164:165]
	s_mov_b32 m0, s36
	s_nop 0
	global_load_lds_dwordx4 v[218:219], off
	s_waitcnt vmcnt(8)
	s_waitcnt lgkmcnt(0)
	s_setprio 1
	s_barrier
	v_mfma_f32_16x16x32_bf16 v[130:133], v[126:129], v[172:175], v[130:133]
	v_mfma_f32_16x16x32_bf16 v[118:121], v[138:141], v[172:175], v[118:121]
	v_mfma_f32_16x16x32_bf16 v[110:113], v[126:129], v[180:183], v[110:113]
	v_mfma_f32_16x16x32_bf16 v[102:105], v[138:141], v[180:183], v[102:105]
	v_mfma_f32_16x16x32_bf16 v[94:97], v[126:129], v[194:197], v[94:97]
	v_mfma_f32_16x16x32_bf16 v[86:89], v[138:141], v[194:197], v[86:89]
	v_mfma_f32_16x16x32_bf16 v[78:81], v[126:129], v[208:211], v[78:81]
	v_mfma_f32_16x16x32_bf16 v[70:73], v[138:141], v[208:211], v[70:73]
	v_mfma_f32_16x16x32_bf16 v[130:133], v[134:137], v[176:179], v[130:133]
	v_mfma_f32_16x16x32_bf16 v[118:121], v[142:145], v[176:179], v[118:121]
	v_mfma_f32_16x16x32_bf16 v[110:113], v[134:137], v[190:193], v[110:113]
	v_mfma_f32_16x16x32_bf16 v[102:105], v[142:145], v[190:193], v[102:105]
	v_mfma_f32_16x16x32_bf16 v[94:97], v[134:137], v[198:201], v[94:97]
	v_mfma_f32_16x16x32_bf16 v[86:89], v[142:145], v[198:201], v[86:89]
	v_mfma_f32_16x16x32_bf16 v[78:81], v[134:137], v[212:215], v[78:81]
	v_mfma_f32_16x16x32_bf16 v[70:73], v[142:145], v[212:215], v[70:73]
	s_setprio 0
	s_setprio 1
	v_mfma_f32_16x16x32_bf16 v[122:125], v[146:149], v[172:175], v[122:125]
	v_mfma_f32_16x16x32_bf16 v[114:117], v[154:157], v[172:175], v[114:117]
	v_mfma_f32_16x16x32_bf16 v[106:109], v[146:149], v[180:183], v[106:109]
	v_mfma_f32_16x16x32_bf16 v[98:101], v[154:157], v[180:183], v[98:101]
	v_mfma_f32_16x16x32_bf16 v[90:93], v[146:149], v[194:197], v[90:93]
	v_mfma_f32_16x16x32_bf16 v[82:85], v[154:157], v[194:197], v[82:85]
	v_mfma_f32_16x16x32_bf16 v[74:77], v[146:149], v[208:211], v[74:77]
	v_mfma_f32_16x16x32_bf16 v[66:69], v[154:157], v[208:211], v[66:69]
	v_mfma_f32_16x16x32_bf16 v[122:125], v[150:153], v[176:179], v[122:125]
	v_mfma_f32_16x16x32_bf16 v[114:117], v[158:161], v[176:179], v[114:117]
	v_mfma_f32_16x16x32_bf16 v[106:109], v[150:153], v[190:193], v[106:109]
	v_mfma_f32_16x16x32_bf16 v[98:101], v[158:161], v[190:193], v[98:101]
	v_mfma_f32_16x16x32_bf16 v[90:93], v[150:153], v[198:201], v[90:93]
	v_mfma_f32_16x16x32_bf16 v[82:85], v[158:161], v[198:201], v[82:85]
	v_mfma_f32_16x16x32_bf16 v[74:77], v[150:153], v[212:215], v[74:77]
	v_mfma_f32_16x16x32_bf16 v[66:69], v[158:161], v[212:215], v[66:69]
	s_barrier
	s_setprio 0
	s_add_i32 s0, s33, s34
	v_lshl_add_u64 v[184:185], v[184:185], 0, s[80:81]
	s_mov_b32 m0, s0
	ds_read_b128 v[172:175], v189 offset:49152
	ds_read_b128 v[176:179], v189 offset:50176
	ds_read_b128 v[180:183], v189 offset:51200
	ds_read_b128 v[190:193], v189 offset:52224
	ds_read_b128 v[194:197], v189 offset:53248
	ds_read_b128 v[198:201], v189 offset:54272
	ds_read_b128 v[208:211], v189 offset:55296
	ds_read_b128 v[212:215], v189 offset:56320
	global_load_lds_dwordx4 v[184:185], off
	s_add_i32 m0, s0, 0x2000
	s_add_u32 s0, s2, 0x80080
	v_lshl_add_u64 v[184:185], v[204:205], 0, s[80:81]
	s_addc_u32 s1, s3, 0
	s_add_i32 s2, s55, s34
	global_load_lds_dwordx4 v[184:185], off
	v_lshl_add_u64 v[184:185], s[0:1], 0, v[202:203]
	s_mov_b32 m0, s2
	s_nop 0
	global_load_lds_dwordx4 v[184:185], off
	v_lshl_add_u64 v[184:185], s[0:1], 0, v[162:163]
	s_add_i32 m0, s2, 0x2000
	s_nop 0
	global_load_lds_dwordx4 v[184:185], off
	v_lshl_add_u64 v[184:185], v[206:207], 0, s[80:81]
	s_mov_b32 m0, s39
	s_nop 0
	global_load_lds_dwordx4 v[184:185], off
	v_lshl_add_u64 v[184:185], v[216:217], 0, s[80:81]
	s_mov_b32 m0, s40
	s_nop 0
	global_load_lds_dwordx4 v[184:185], off
	s_waitcnt vmcnt(8)
	s_waitcnt lgkmcnt(0)
	s_setprio 1
	s_barrier
	v_mfma_f32_16x16x32_bf16 v[62:65], v[126:129], v[172:175], v[62:65]
	v_mfma_f32_16x16x32_bf16 v[54:57], v[138:141], v[172:175], v[54:57]
	v_mfma_f32_16x16x32_bf16 v[46:49], v[126:129], v[180:183], v[46:49]
	v_mfma_f32_16x16x32_bf16 v[38:41], v[138:141], v[180:183], v[38:41]
	v_mfma_f32_16x16x32_bf16 v[30:33], v[126:129], v[194:197], v[30:33]
	v_mfma_f32_16x16x32_bf16 v[22:25], v[138:141], v[194:197], v[22:25]
	v_mfma_f32_16x16x32_bf16 v[14:17], v[126:129], v[208:211], v[14:17]
	v_mfma_f32_16x16x32_bf16 v[6:9], v[138:141], v[208:211], v[6:9]
	v_mfma_f32_16x16x32_bf16 v[62:65], v[134:137], v[176:179], v[62:65]
	v_mfma_f32_16x16x32_bf16 v[54:57], v[142:145], v[176:179], v[54:57]
	v_mfma_f32_16x16x32_bf16 v[46:49], v[134:137], v[190:193], v[46:49]
	v_mfma_f32_16x16x32_bf16 v[38:41], v[142:145], v[190:193], v[38:41]
	v_mfma_f32_16x16x32_bf16 v[30:33], v[134:137], v[198:201], v[30:33]
	v_mfma_f32_16x16x32_bf16 v[22:25], v[142:145], v[198:201], v[22:25]
	v_mfma_f32_16x16x32_bf16 v[14:17], v[134:137], v[212:215], v[14:17]
	v_mfma_f32_16x16x32_bf16 v[6:9], v[142:145], v[212:215], v[6:9]
	s_setprio 0
	s_setprio 1
	v_mfma_f32_16x16x32_bf16 v[58:61], v[146:149], v[172:175], v[58:61]
	v_mfma_f32_16x16x32_bf16 v[50:53], v[154:157], v[172:175], v[50:53]
	v_mfma_f32_16x16x32_bf16 v[42:45], v[146:149], v[180:183], v[42:45]
	v_mfma_f32_16x16x32_bf16 v[34:37], v[154:157], v[180:183], v[34:37]
	v_mfma_f32_16x16x32_bf16 v[26:29], v[146:149], v[194:197], v[26:29]
	v_mfma_f32_16x16x32_bf16 v[18:21], v[154:157], v[194:197], v[18:21]
	v_mfma_f32_16x16x32_bf16 v[10:13], v[146:149], v[208:211], v[10:13]
	v_mfma_f32_16x16x32_bf16 v[2:5], v[154:157], v[208:211], v[2:5]
	v_mfma_f32_16x16x32_bf16 v[58:61], v[150:153], v[176:179], v[58:61]
	v_mfma_f32_16x16x32_bf16 v[50:53], v[158:161], v[176:179], v[50:53]
	v_mfma_f32_16x16x32_bf16 v[42:45], v[150:153], v[190:193], v[42:45]
	v_mfma_f32_16x16x32_bf16 v[34:37], v[158:161], v[190:193], v[34:37]
	v_mfma_f32_16x16x32_bf16 v[26:29], v[150:153], v[198:201], v[26:29]
	v_mfma_f32_16x16x32_bf16 v[18:21], v[158:161], v[198:201], v[18:21]
	v_mfma_f32_16x16x32_bf16 v[10:13], v[150:153], v[212:215], v[10:13]
	v_mfma_f32_16x16x32_bf16 v[2:5], v[158:161], v[212:215], v[2:5]
	s_barrier
	s_setprio 0
	s_add_i32 s61, s61, 2
	s_add_u32 s26, s26, 0x100
	s_addc_u32 s27, s27, 0
	s_add_u32 s59, s59, 0x100
	s_addc_u32 s60, s60, 0
	s_cmp_gt_u32 s61, 29
	s_cbranch_scc0 .LBB0_1428
	s_and_b64 vcc, exec, s[10:11]
	s_cbranch_vccz .LBB0_1431
	s_barrier

.LBB0_1594:
	ds_read_b128 v[178:181], v145
	ds_read_b128 v[182:185], v145 offset:1024
	ds_read_b128 v[186:189], v145 offset:2048
	ds_read_b128 v[190:193], v145 offset:3072
	ds_read_b128 v[194:197], v145 offset:4096
	ds_read_b128 v[198:201], v145 offset:5120
	ds_read_b128 v[208:211], v145 offset:6144
	ds_read_b128 v[212:215], v145 offset:7168
	s_add_u32 s0, s28, 0xfff80080
	s_addc_u32 s1, s29, -1
	s_add_i32 s33, 0, 0x10000
	s_cmp_eq_u32 s61, 28
	s_cselect_b32 s5, s19, s1
	s_cselect_b32 s4, s49, s0
	v_add_u32_e32 v140, s33, v143
	s_cselect_b32 s3, s17, s60
	s_cselect_b32 s2, s58, s59
	s_add_i32 s55, 0, 0x14000
	ds_read_b128 v[146:149], v140
	ds_read_b128 v[150:153], v140 offset:1024
	ds_read_b128 v[154:157], v140 offset:2048
	ds_read_b128 v[158:161], v140 offset:3072
	v_add_u32_e32 v140, s55, v143
	ds_read_b128 v[162:165], v140
	ds_read_b128 v[166:169], v140 offset:1024
	ds_read_b128 v[170:173], v140 offset:2048
	ds_read_b128 v[174:177], v140 offset:3072
	v_lshl_add_u64 v[140:141], s[28:29], 0, v[136:137]
	s_add_i32 m0, s25, 0xc000
	global_load_lds_dwordx4 v[140:141], off
	v_lshl_add_u64 v[140:141], s[28:29], 0, v[138:139]
	s_add_i32 m0, s25, 0xe000
	s_nop 0
	global_load_lds_dwordx4 v[140:141], off
	s_waitcnt vmcnt(8)
	s_waitcnt lgkmcnt(0)
	s_setprio 1
	s_barrier
	v_mfma_f32_16x16x32_bf16 v[126:129], v[146:149], v[178:181], v[126:129]
	v_mfma_f32_16x16x32_bf16 v[118:121], v[154:157], v[178:181], v[118:121]
	v_mfma_f32_16x16x32_bf16 v[110:113], v[146:149], v[186:189], v[110:113]
	v_mfma_f32_16x16x32_bf16 v[102:105], v[154:157], v[186:189], v[102:105]
	v_mfma_f32_16x16x32_bf16 v[94:97], v[146:149], v[194:197], v[94:97]
	v_mfma_f32_16x16x32_bf16 v[86:89], v[154:157], v[194:197], v[86:89]
	v_mfma_f32_16x16x32_bf16 v[78:81], v[146:149], v[208:211], v[78:81]
	v_mfma_f32_16x16x32_bf16 v[70:73], v[154:157], v[208:211], v[70:73]
	v_mfma_f32_16x16x32_bf16 v[126:129], v[150:153], v[182:185], v[126:129]
	v_mfma_f32_16x16x32_bf16 v[118:121], v[158:161], v[182:185], v[118:121]
	v_mfma_f32_16x16x32_bf16 v[110:113], v[150:153], v[190:193], v[110:113]
	v_mfma_f32_16x16x32_bf16 v[102:105], v[158:161], v[190:193], v[102:105]
	v_mfma_f32_16x16x32_bf16 v[94:97], v[150:153], v[198:201], v[94:97]
	v_mfma_f32_16x16x32_bf16 v[86:89], v[158:161], v[198:201], v[86:89]
	v_mfma_f32_16x16x32_bf16 v[78:81], v[150:153], v[212:215], v[78:81]
	v_mfma_f32_16x16x32_bf16 v[70:73], v[158:161], v[212:215], v[70:73]
	s_setprio 0
	s_setprio 1
	v_mfma_f32_16x16x32_bf16 v[122:125], v[162:165], v[178:181], v[122:125]
	v_mfma_f32_16x16x32_bf16 v[114:117], v[170:173], v[178:181], v[114:117]
	v_mfma_f32_16x16x32_bf16 v[106:109], v[162:165], v[186:189], v[106:109]
	v_mfma_f32_16x16x32_bf16 v[98:101], v[170:173], v[186:189], v[98:101]
	v_mfma_f32_16x16x32_bf16 v[90:93], v[162:165], v[194:197], v[90:93]
	v_mfma_f32_16x16x32_bf16 v[82:85], v[170:173], v[194:197], v[82:85]
	v_mfma_f32_16x16x32_bf16 v[74:77], v[162:165], v[208:211], v[74:77]
	v_mfma_f32_16x16x32_bf16 v[66:69], v[170:173], v[208:211], v[66:69]
	v_mfma_f32_16x16x32_bf16 v[122:125], v[166:169], v[182:185], v[122:125]
	v_mfma_f32_16x16x32_bf16 v[114:117], v[174:177], v[182:185], v[114:117]
	v_mfma_f32_16x16x32_bf16 v[106:109], v[166:169], v[190:193], v[106:109]
	v_mfma_f32_16x16x32_bf16 v[98:101], v[174:177], v[190:193], v[98:101]
	v_mfma_f32_16x16x32_bf16 v[90:93], v[166:169], v[198:201], v[90:93]
	v_mfma_f32_16x16x32_bf16 v[82:85], v[174:177], v[198:201], v[82:85]
	v_mfma_f32_16x16x32_bf16 v[74:77], v[166:169], v[212:215], v[74:77]
	v_mfma_f32_16x16x32_bf16 v[66:69], v[174:177], v[212:215], v[66:69]
	s_barrier
	s_setprio 0
	s_add_i32 s0, s33, s36
	v_lshl_add_u64 v[140:141], s[2:3], 0, v[202:203]
	s_mov_b32 m0, s0
	ds_read_b128 v[178:181], v145 offset:16384
	ds_read_b128 v[182:185], v145 offset:17408
	ds_read_b128 v[186:189], v145 offset:18432
	ds_read_b128 v[190:193], v145 offset:19456
	ds_read_b128 v[194:197], v145 offset:20480
	ds_read_b128 v[198:201], v145 offset:21504
	ds_read_b128 v[208:211], v145 offset:22528
	ds_read_b128 v[212:215], v145 offset:23552
	global_load_lds_dwordx4 v[140:141], off
	s_add_i32 m0, s0, 0x2000
	s_add_u32 s0, s2, 0x80000
	v_lshl_add_u64 v[204:205], s[2:3], 0, v[130:131]
	s_addc_u32 s1, s3, 0
	s_add_i32 s33, s55, s36
	global_load_lds_dwordx4 v[204:205], off
	v_lshl_add_u64 v[206:207], s[0:1], 0, v[202:203]
	s_mov_b32 m0, s33
	v_lshl_add_u64 v[216:217], s[4:5], 0, v[132:133]
	global_load_lds_dwordx4 v[206:207], off
	v_lshl_add_u64 v[206:207], s[0:1], 0, v[130:131]
	s_add_i32 m0, s33, 0x2000
	s_nop 0
	global_load_lds_dwordx4 v[206:207], off
	v_lshl_add_u64 v[206:207], s[4:5], 0, v[134:135]
	s_mov_b32 m0, s25
	s_nop 0
	global_load_lds_dwordx4 v[206:207], off
	s_mov_b32 m0, s27
	s_nop 0
	global_load_lds_dwordx4 v[216:217], off
	s_waitcnt vmcnt(8)
	s_waitcnt lgkmcnt(0)
	s_setprio 1
	s_barrier
	v_mfma_f32_16x16x32_bf16 v[62:65], v[146:149], v[178:181], v[62:65]
	v_mfma_f32_16x16x32_bf16 v[54:57], v[154:157], v[178:181], v[54:57]
	v_mfma_f32_16x16x32_bf16 v[46:49], v[146:149], v[186:189], v[46:49]
	v_mfma_f32_16x16x32_bf16 v[38:41], v[154:157], v[186:189], v[38:41]
	v_mfma_f32_16x16x32_bf16 v[30:33], v[146:149], v[194:197], v[30:33]
	v_mfma_f32_16x16x32_bf16 v[22:25], v[154:157], v[194:197], v[22:25]
	v_mfma_f32_16x16x32_bf16 v[14:17], v[146:149], v[208:211], v[14:17]
	v_mfma_f32_16x16x32_bf16 v[6:9], v[154:157], v[208:211], v[6:9]
	v_mfma_f32_16x16x32_bf16 v[62:65], v[150:153], v[182:185], v[62:65]
	v_mfma_f32_16x16x32_bf16 v[54:57], v[158:161], v[182:185], v[54:57]
	v_mfma_f32_16x16x32_bf16 v[46:49], v[150:153], v[190:193], v[46:49]
	v_mfma_f32_16x16x32_bf16 v[38:41], v[158:161], v[190:193], v[38:41]
	v_mfma_f32_16x16x32_bf16 v[30:33], v[150:153], v[198:201], v[30:33]
	v_mfma_f32_16x16x32_bf16 v[22:25], v[158:161], v[198:201], v[22:25]
	v_mfma_f32_16x16x32_bf16 v[14:17], v[150:153], v[212:215], v[14:17]
	v_mfma_f32_16x16x32_bf16 v[6:9], v[158:161], v[212:215], v[6:9]
	s_setprio 0
	s_setprio 1
	v_mfma_f32_16x16x32_bf16 v[58:61], v[162:165], v[178:181], v[58:61]
	v_mfma_f32_16x16x32_bf16 v[50:53], v[170:173], v[178:181], v[50:53]
	v_mfma_f32_16x16x32_bf16 v[42:45], v[162:165], v[186:189], v[42:45]
	v_mfma_f32_16x16x32_bf16 v[34:37], v[170:173], v[186:189], v[34:37]
	v_mfma_f32_16x16x32_bf16 v[26:29], v[162:165], v[194:197], v[26:29]
	v_mfma_f32_16x16x32_bf16 v[18:21], v[170:173], v[194:197], v[18:21]
	v_mfma_f32_16x16x32_bf16 v[10:13], v[162:165], v[208:211], v[10:13]
	v_mfma_f32_16x16x32_bf16 v[2:5], v[170:173], v[208:211], v[2:5]
	v_mfma_f32_16x16x32_bf16 v[58:61], v[166:169], v[182:185], v[58:61]
	v_mfma_f32_16x16x32_bf16 v[50:53], v[174:177], v[182:185], v[50:53]
	v_mfma_f32_16x16x32_bf16 v[42:45], v[166:169], v[190:193], v[42:45]
	v_mfma_f32_16x16x32_bf16 v[34:37], v[174:177], v[190:193], v[34:37]
	v_mfma_f32_16x16x32_bf16 v[26:29], v[166:169], v[198:201], v[26:29]
	v_mfma_f32_16x16x32_bf16 v[18:21], v[174:177], v[198:201], v[18:21]
	v_mfma_f32_16x16x32_bf16 v[10:13], v[166:169], v[212:215], v[10:13]
	v_mfma_f32_16x16x32_bf16 v[2:5], v[174:177], v[212:215], v[2:5]
	s_barrier
	s_setprio 0
	s_add_i32 s33, 0, 0x18000
	s_add_i32 s55, 0, 0x1c000
	v_add_u32_e32 v158, s33, v143
	v_add_u32_e32 v174, s55, v143
	ds_read_b128 v[146:149], v158
	ds_read_b128 v[150:153], v158 offset:1024
	ds_read_b128 v[154:157], v158 offset:2048
	ds_read_b128 v[158:161], v158 offset:3072
	ds_read_b128 v[162:165], v174
	ds_read_b128 v[166:169], v174 offset:1024
	ds_read_b128 v[170:173], v174 offset:2048
	ds_read_b128 v[174:177], v174 offset:3072
	s_add_u32 s0, s4, 0x80000
	s_addc_u32 s1, s5, 0
	s_mov_b32 m0, s37
	v_lshl_add_u64 v[218:219], s[0:1], 0, v[134:135]
	ds_read_b128 v[178:181], v145 offset:32768
	ds_read_b128 v[182:185], v145 offset:33792
	ds_read_b128 v[186:189], v145 offset:34816
	ds_read_b128 v[190:193], v145 offset:35840
	ds_read_b128 v[194:197], v145 offset:36864
	ds_read_b128 v[198:201], v145 offset:37888
	ds_read_b128 v[208:211], v145 offset:38912
	ds_read_b128 v[212:215], v145 offset:39936
	global_load_lds_dwordx4 v[218:219], off
	v_lshl_add_u64 v[218:219], s[0:1], 0, v[132:133]
	s_mov_b32 m0, s38
	s_nop 0
	global_load_lds_dwordx4 v[218:219], off
	s_waitcnt vmcnt(8)
	s_waitcnt lgkmcnt(0)
	s_setprio 1
	s_barrier
	v_mfma_f32_16x16x32_bf16 v[126:129], v[146:149], v[178:181], v[126:129]
	v_mfma_f32_16x16x32_bf16 v[118:121], v[154:157], v[178:181], v[118:121]
	v_mfma_f32_16x16x32_bf16 v[110:113], v[146:149], v[186:189], v[110:113]
	v_mfma_f32_16x16x32_bf16 v[102:105], v[154:157], v[186:189], v[102:105]
	v_mfma_f32_16x16x32_bf16 v[94:97], v[146:149], v[194:197], v[94:97]
	v_mfma_f32_16x16x32_bf16 v[86:89], v[154:157], v[194:197], v[86:89]
	v_mfma_f32_16x16x32_bf16 v[78:81], v[146:149], v[208:211], v[78:81]
	v_mfma_f32_16x16x32_bf16 v[70:73], v[154:157], v[208:211], v[70:73]
	v_mfma_f32_16x16x32_bf16 v[126:129], v[150:153], v[182:185], v[126:129]
	v_mfma_f32_16x16x32_bf16 v[118:121], v[158:161], v[182:185], v[118:121]
	v_mfma_f32_16x16x32_bf16 v[110:113], v[150:153], v[190:193], v[110:113]
	v_mfma_f32_16x16x32_bf16 v[102:105], v[158:161], v[190:193], v[102:105]
	v_mfma_f32_16x16x32_bf16 v[94:97], v[150:153], v[198:201], v[94:97]
	v_mfma_f32_16x16x32_bf16 v[86:89], v[158:161], v[198:201], v[86:89]
	v_mfma_f32_16x16x32_bf16 v[78:81], v[150:153], v[212:215], v[78:81]
	v_mfma_f32_16x16x32_bf16 v[70:73], v[158:161], v[212:215], v[70:73]
	s_setprio 0
	s_setprio 1
	v_mfma_f32_16x16x32_bf16 v[122:125], v[162:165], v[178:181], v[122:125]
	v_mfma_f32_16x16x32_bf16 v[114:117], v[170:173], v[178:181], v[114:117]
	v_mfma_f32_16x16x32_bf16 v[106:109], v[162:165], v[186:189], v[106:109]
	v_mfma_f32_16x16x32_bf16 v[98:101], v[170:173], v[186:189], v[98:101]
	v_mfma_f32_16x16x32_bf16 v[90:93], v[162:165], v[194:197], v[90:93]
	v_mfma_f32_16x16x32_bf16 v[82:85], v[170:173], v[194:197], v[82:85]
	v_mfma_f32_16x16x32_bf16 v[74:77], v[162:165], v[208:211], v[74:77]
	v_mfma_f32_16x16x32_bf16 v[66:69], v[170:173], v[208:211], v[66:69]
	v_mfma_f32_16x16x32_bf16 v[122:125], v[166:169], v[182:185], v[122:125]
	v_mfma_f32_16x16x32_bf16 v[114:117], v[174:177], v[182:185], v[114:117]
	v_mfma_f32_16x16x32_bf16 v[106:109], v[166:169], v[190:193], v[106:109]
	v_mfma_f32_16x16x32_bf16 v[98:101], v[174:177], v[190:193], v[98:101]
	v_mfma_f32_16x16x32_bf16 v[90:93], v[166:169], v[198:201], v[90:93]
	v_mfma_f32_16x16x32_bf16 v[82:85], v[174:177], v[198:201], v[82:85]
	v_mfma_f32_16x16x32_bf16 v[74:77], v[166:169], v[212:215], v[74:77]
	v_mfma_f32_16x16x32_bf16 v[66:69], v[174:177], v[212:215], v[66:69]
	s_barrier
	s_setprio 0
	s_add_i32 s0, s33, s36
	v_lshl_add_u64 v[140:141], v[140:141], 0, s[80:81]
	s_mov_b32 m0, s0
	ds_read_b128 v[178:181], v145 offset:49152
	ds_read_b128 v[182:185], v145 offset:50176
	ds_read_b128 v[186:189], v145 offset:51200
	ds_read_b128 v[190:193], v145 offset:52224
	ds_read_b128 v[194:197], v145 offset:53248
	ds_read_b128 v[198:201], v145 offset:54272
	ds_read_b128 v[208:211], v145 offset:55296
	ds_read_b128 v[212:215], v145 offset:56320
	global_load_lds_dwordx4 v[140:141], off
	s_add_i32 m0, s0, 0x2000
	s_add_u32 s0, s2, 0x80080
	v_lshl_add_u64 v[140:141], v[204:205], 0, s[80:81]
	s_addc_u32 s1, s3, 0
	s_add_i32 s2, s55, s36
	global_load_lds_dwordx4 v[140:141], off
	v_lshl_add_u64 v[140:141], s[0:1], 0, v[202:203]
	s_mov_b32 m0, s2
	s_nop 0
	global_load_lds_dwordx4 v[140:141], off
	v_lshl_add_u64 v[140:141], s[0:1], 0, v[130:131]
	s_add_i32 m0, s2, 0x2000
	s_nop 0
	global_load_lds_dwordx4 v[140:141], off
	v_lshl_add_u64 v[140:141], v[206:207], 0, s[80:81]
	s_mov_b32 m0, s39
	s_nop 0
	global_load_lds_dwordx4 v[140:141], off
	v_lshl_add_u64 v[140:141], v[216:217], 0, s[80:81]
	s_mov_b32 m0, s40
	s_nop 0
	global_load_lds_dwordx4 v[140:141], off
	s_waitcnt vmcnt(8)
	s_waitcnt lgkmcnt(0)
	s_setprio 1
	s_barrier
	v_mfma_f32_16x16x32_bf16 v[62:65], v[146:149], v[178:181], v[62:65]
	v_mfma_f32_16x16x32_bf16 v[54:57], v[154:157], v[178:181], v[54:57]
	v_mfma_f32_16x16x32_bf16 v[46:49], v[146:149], v[186:189], v[46:49]
	v_mfma_f32_16x16x32_bf16 v[38:41], v[154:157], v[186:189], v[38:41]
	v_mfma_f32_16x16x32_bf16 v[30:33], v[146:149], v[194:197], v[30:33]
	v_mfma_f32_16x16x32_bf16 v[22:25], v[154:157], v[194:197], v[22:25]
	v_mfma_f32_16x16x32_bf16 v[14:17], v[146:149], v[208:211], v[14:17]
	v_mfma_f32_16x16x32_bf16 v[6:9], v[154:157], v[208:211], v[6:9]
	v_mfma_f32_16x16x32_bf16 v[62:65], v[150:153], v[182:185], v[62:65]
	v_mfma_f32_16x16x32_bf16 v[54:57], v[158:161], v[182:185], v[54:57]
	v_mfma_f32_16x16x32_bf16 v[46:49], v[150:153], v[190:193], v[46:49]
	v_mfma_f32_16x16x32_bf16 v[38:41], v[158:161], v[190:193], v[38:41]
	v_mfma_f32_16x16x32_bf16 v[30:33], v[150:153], v[198:201], v[30:33]
	v_mfma_f32_16x16x32_bf16 v[22:25], v[158:161], v[198:201], v[22:25]
	v_mfma_f32_16x16x32_bf16 v[14:17], v[150:153], v[212:215], v[14:17]
	v_mfma_f32_16x16x32_bf16 v[6:9], v[158:161], v[212:215], v[6:9]
	s_setprio 0
	s_setprio 1
	v_mfma_f32_16x16x32_bf16 v[58:61], v[162:165], v[178:181], v[58:61]
	v_mfma_f32_16x16x32_bf16 v[50:53], v[170:173], v[178:181], v[50:53]
	v_mfma_f32_16x16x32_bf16 v[42:45], v[162:165], v[186:189], v[42:45]
	v_mfma_f32_16x16x32_bf16 v[34:37], v[170:173], v[186:189], v[34:37]
	v_mfma_f32_16x16x32_bf16 v[26:29], v[162:165], v[194:197], v[26:29]
	v_mfma_f32_16x16x32_bf16 v[18:21], v[170:173], v[194:197], v[18:21]
	v_mfma_f32_16x16x32_bf16 v[10:13], v[162:165], v[208:211], v[10:13]
	v_mfma_f32_16x16x32_bf16 v[2:5], v[170:173], v[208:211], v[2:5]
	v_mfma_f32_16x16x32_bf16 v[58:61], v[166:169], v[182:185], v[58:61]
	v_mfma_f32_16x16x32_bf16 v[50:53], v[174:177], v[182:185], v[50:53]
	v_mfma_f32_16x16x32_bf16 v[42:45], v[166:169], v[190:193], v[42:45]
	v_mfma_f32_16x16x32_bf16 v[34:37], v[174:177], v[190:193], v[34:37]
	v_mfma_f32_16x16x32_bf16 v[26:29], v[166:169], v[198:201], v[26:29]
	v_mfma_f32_16x16x32_bf16 v[18:21], v[174:177], v[198:201], v[18:21]
	v_mfma_f32_16x16x32_bf16 v[10:13], v[166:169], v[212:215], v[10:13]
	v_mfma_f32_16x16x32_bf16 v[2:5], v[174:177], v[212:215], v[2:5]
	s_barrier
	s_setprio 0
	s_add_i32 s61, s61, 2
	s_add_u32 s28, s28, 0x100
	s_addc_u32 s29, s29, 0
	s_add_u32 s59, s59, 0x100
	s_addc_u32 s60, s60, 0
	s_cmp_gt_u32 s61, 29
	s_cbranch_scc0 .LBB0_1594
	s_and_b64 vcc, exec, s[14:15]
	s_cbranch_vccz .LBB0_1597
	s_barrier

.LBB0_1718:
	ds_read_b128 v[146:149], v239
	ds_read_b128 v[158:161], v239 offset:1024
	ds_read_b128 v[166:169], v239 offset:2048
	ds_read_b128 v[174:177], v239 offset:3072
	ds_read_b128 v[178:181], v239 offset:4096
	ds_read_b128 v[182:185], v239 offset:5120
	ds_read_b128 v[186:189], v239 offset:6144
	ds_read_b128 v[190:193], v239 offset:7168
	s_add_u32 s18, s4, 0x100
	s_addc_u32 s19, s5, 0
	s_add_i32 s0, 0, 0x10000
	s_cmpk_eq_i32 s59, 0x54
	s_cselect_b32 s23, s9, s19
	s_cselect_b32 s22, s8, s18
	s_cselect_b32 s21, s17, s58
	s_cselect_b32 s20, s16, s49
	s_add_i32 s33, 0, 0x14000
	v_add_u32_e32 v98, s0, v205
	v_add_u32_e32 v134, s33, v205
	ds_read_b128 v[78:81], v98
	ds_read_b128 v[82:85], v98 offset:1024
	ds_read_b128 v[94:97], v98 offset:2048
	ds_read_b128 v[98:101], v98 offset:3072
	ds_read_b128 v[106:109], v134
	ds_read_b128 v[110:113], v134 offset:1024
	ds_read_b128 v[126:129], v134 offset:2048
	ds_read_b128 v[134:137], v134 offset:3072
	v_lshl_add_u64 v[194:195], s[4:5], 0, v[214:215]
	s_add_i32 m0, s27, 0xc000
	global_load_lds_dwordx4 v[194:195], off
	v_lshl_add_u64 v[194:195], s[4:5], 0, v[216:217]
	s_add_i32 m0, s27, 0xe000
	s_nop 0
	global_load_lds_dwordx4 v[194:195], off
	s_waitcnt vmcnt(8)
	s_waitcnt lgkmcnt(0)
	s_setprio 1
	s_barrier
	v_mfma_f32_16x16x32_bf16 v[170:173], v[78:81], v[146:149], v[170:173]
	v_mfma_f32_16x16x32_bf16 v[162:165], v[94:97], v[146:149], v[162:165]
	v_mfma_f32_16x16x32_bf16 v[142:145], v[78:81], v[166:169], v[142:145]
	v_mfma_f32_16x16x32_bf16 v[138:141], v[94:97], v[166:169], v[138:141]
	v_mfma_f32_16x16x32_bf16 v[118:121], v[78:81], v[178:181], v[118:121]
	v_mfma_f32_16x16x32_bf16 v[114:117], v[94:97], v[178:181], v[114:117]
	v_mfma_f32_16x16x32_bf16 v[86:89], v[78:81], v[186:189], v[86:89]
	v_mfma_f32_16x16x32_bf16 v[74:77], v[94:97], v[186:189], v[74:77]
	v_mfma_f32_16x16x32_bf16 v[170:173], v[82:85], v[158:161], v[170:173]
	v_mfma_f32_16x16x32_bf16 v[162:165], v[98:101], v[158:161], v[162:165]
	v_mfma_f32_16x16x32_bf16 v[142:145], v[82:85], v[174:177], v[142:145]
	v_mfma_f32_16x16x32_bf16 v[138:141], v[98:101], v[174:177], v[138:141]
	v_mfma_f32_16x16x32_bf16 v[118:121], v[82:85], v[182:185], v[118:121]
	v_mfma_f32_16x16x32_bf16 v[114:117], v[98:101], v[182:185], v[114:117]
	v_mfma_f32_16x16x32_bf16 v[86:89], v[82:85], v[190:193], v[86:89]
	v_mfma_f32_16x16x32_bf16 v[74:77], v[98:101], v[190:193], v[74:77]
	s_setprio 0
	s_setprio 1
	v_mfma_f32_16x16x32_bf16 v[154:157], v[106:109], v[146:149], v[154:157]
	v_mfma_f32_16x16x32_bf16 v[130:133], v[106:109], v[166:169], v[130:133]
	v_mfma_f32_16x16x32_bf16 v[122:125], v[126:129], v[166:169], v[122:125]
	v_mfma_f32_16x16x32_bf16 v[102:105], v[106:109], v[178:181], v[102:105]
	v_mfma_f32_16x16x32_bf16 v[90:93], v[126:129], v[178:181], v[90:93]
	v_mfma_f32_16x16x32_bf16 v[70:73], v[106:109], v[186:189], v[70:73]
	v_mfma_f32_16x16x32_bf16 v[66:69], v[126:129], v[186:189], v[66:69]
	v_mfma_f32_16x16x32_bf16 v[154:157], v[110:113], v[158:161], v[154:157]
	v_mfma_f32_16x16x32_bf16 v[146:149], v[126:129], v[146:149], v[150:153]
	v_mfma_f32_16x16x32_bf16 v[130:133], v[110:113], v[174:177], v[130:133]
	v_mfma_f32_16x16x32_bf16 v[122:125], v[134:137], v[174:177], v[122:125]
	v_mfma_f32_16x16x32_bf16 v[102:105], v[110:113], v[182:185], v[102:105]
	v_mfma_f32_16x16x32_bf16 v[90:93], v[134:137], v[182:185], v[90:93]
	v_mfma_f32_16x16x32_bf16 v[70:73], v[110:113], v[190:193], v[70:73]
	v_mfma_f32_16x16x32_bf16 v[66:69], v[134:137], v[190:193], v[66:69]
	v_mfma_f32_16x16x32_bf16 v[146:149], v[134:137], v[158:161], v[146:149]
	s_barrier
	s_setprio 0
	s_add_i32 s0, s0, s26
	v_lshl_add_u64 v[194:195], s[20:21], 0, v[202:203]
	s_mov_b32 m0, s0
	ds_read_b128 v[150:153], v239 offset:16384
	ds_read_b128 v[158:161], v239 offset:17408
	ds_read_b128 v[166:169], v239 offset:18432
	ds_read_b128 v[174:177], v239 offset:19456
	ds_read_b128 v[178:181], v239 offset:20480
	ds_read_b128 v[182:185], v239 offset:21504
	ds_read_b128 v[186:189], v239 offset:22528
	ds_read_b128 v[190:193], v239 offset:23552
	global_load_lds_dwordx4 v[194:195], off
	s_add_i32 m0, s0, 0x2000
	s_add_u32 s0, s20, 0x160000
	v_lshl_add_u64 v[196:197], s[20:21], 0, v[208:209]
	s_addc_u32 s1, s21, 0
	s_add_i32 s4, s33, s26
	global_load_lds_dwordx4 v[196:197], off
	v_lshl_add_u64 v[198:199], s[0:1], 0, v[202:203]
	s_mov_b32 m0, s4
	v_lshl_add_u64 v[200:201], s[22:23], 0, v[210:211]
	global_load_lds_dwordx4 v[198:199], off
	v_lshl_add_u64 v[198:199], s[0:1], 0, v[208:209]
	s_add_i32 m0, s4, 0x2000
	s_nop 0
	global_load_lds_dwordx4 v[198:199], off
	v_lshl_add_u64 v[198:199], s[22:23], 0, v[212:213]
	s_mov_b32 m0, s27
	s_nop 0
	global_load_lds_dwordx4 v[198:199], off
	s_mov_b32 m0, s28
	s_nop 0
	global_load_lds_dwordx4 v[200:201], off
	s_waitcnt vmcnt(8)
	s_waitcnt lgkmcnt(0)
	s_setprio 1
	s_barrier
	v_mfma_f32_16x16x32_bf16 v[62:65], v[78:81], v[150:153], v[62:65]
	v_mfma_f32_16x16x32_bf16 v[58:61], v[94:97], v[150:153], v[58:61]
	v_mfma_f32_16x16x32_bf16 v[46:49], v[78:81], v[166:169], v[46:49]
	v_mfma_f32_16x16x32_bf16 v[42:45], v[94:97], v[166:169], v[42:45]
	v_mfma_f32_16x16x32_bf16 v[30:33], v[78:81], v[178:181], v[30:33]
	v_mfma_f32_16x16x32_bf16 v[26:29], v[94:97], v[178:181], v[26:29]
	v_mfma_f32_16x16x32_bf16 v[14:17], v[78:81], v[186:189], v[14:17]
	v_mfma_f32_16x16x32_bf16 v[10:13], v[94:97], v[186:189], v[10:13]
	v_mfma_f32_16x16x32_bf16 v[62:65], v[82:85], v[158:161], v[62:65]
	v_mfma_f32_16x16x32_bf16 v[58:61], v[98:101], v[158:161], v[58:61]
	v_mfma_f32_16x16x32_bf16 v[46:49], v[82:85], v[174:177], v[46:49]
	v_mfma_f32_16x16x32_bf16 v[42:45], v[98:101], v[174:177], v[42:45]
	v_mfma_f32_16x16x32_bf16 v[30:33], v[82:85], v[182:185], v[30:33]
	v_mfma_f32_16x16x32_bf16 v[26:29], v[98:101], v[182:185], v[26:29]
	v_mfma_f32_16x16x32_bf16 v[14:17], v[82:85], v[190:193], v[14:17]
	v_mfma_f32_16x16x32_bf16 v[10:13], v[98:101], v[190:193], v[10:13]
	s_setprio 0
	s_setprio 1
	v_mfma_f32_16x16x32_bf16 v[54:57], v[106:109], v[150:153], v[54:57]
	v_mfma_f32_16x16x32_bf16 v[50:53], v[126:129], v[150:153], v[50:53]
	v_mfma_f32_16x16x32_bf16 v[38:41], v[106:109], v[166:169], v[38:41]
	v_mfma_f32_16x16x32_bf16 v[34:37], v[126:129], v[166:169], v[34:37]
	v_mfma_f32_16x16x32_bf16 v[22:25], v[106:109], v[178:181], v[22:25]
	v_mfma_f32_16x16x32_bf16 v[18:21], v[126:129], v[178:181], v[18:21]
	v_mfma_f32_16x16x32_bf16 v[6:9], v[106:109], v[186:189], v[6:9]
	v_mfma_f32_16x16x32_bf16 v[2:5], v[126:129], v[186:189], v[2:5]
	v_mfma_f32_16x16x32_bf16 v[54:57], v[110:113], v[158:161], v[54:57]
	v_mfma_f32_16x16x32_bf16 v[50:53], v[134:137], v[158:161], v[50:53]
	v_mfma_f32_16x16x32_bf16 v[38:41], v[110:113], v[174:177], v[38:41]
	v_mfma_f32_16x16x32_bf16 v[34:37], v[134:137], v[174:177], v[34:37]
	v_mfma_f32_16x16x32_bf16 v[22:25], v[110:113], v[182:185], v[22:25]
	v_mfma_f32_16x16x32_bf16 v[18:21], v[134:137], v[182:185], v[18:21]
	v_mfma_f32_16x16x32_bf16 v[6:9], v[110:113], v[190:193], v[6:9]
	v_mfma_f32_16x16x32_bf16 v[2:5], v[134:137], v[190:193], v[2:5]
	s_barrier
	s_setprio 0
	s_add_i32 s4, 0, 0x18000
	s_add_i32 s5, 0, 0x1c000
	v_add_u32_e32 v98, s4, v205
	v_add_u32_e32 v134, s5, v205
	ds_read_b128 v[78:81], v98
	ds_read_b128 v[82:85], v98 offset:1024
	ds_read_b128 v[94:97], v98 offset:2048
	ds_read_b128 v[98:101], v98 offset:3072
	ds_read_b128 v[106:109], v134
	ds_read_b128 v[110:113], v134 offset:1024
	ds_read_b128 v[126:129], v134 offset:2048
	ds_read_b128 v[134:137], v134 offset:3072
	s_add_u32 s0, s22, 0x160000
	s_addc_u32 s1, s23, 0
	s_mov_b32 m0, s29
	v_lshl_add_u64 v[206:207], s[0:1], 0, v[212:213]
	ds_read_b128 v[150:153], v239 offset:32768
	ds_read_b128 v[158:161], v239 offset:33792
	ds_read_b128 v[166:169], v239 offset:34816
	ds_read_b128 v[174:177], v239 offset:35840
	ds_read_b128 v[178:181], v239 offset:36864
	ds_read_b128 v[182:185], v239 offset:37888
	ds_read_b128 v[186:189], v239 offset:38912
	ds_read_b128 v[190:193], v239 offset:39936
	global_load_lds_dwordx4 v[206:207], off
	v_lshl_add_u64 v[206:207], s[0:1], 0, v[210:211]
	s_mov_b32 m0, s30
	s_nop 0
	global_load_lds_dwordx4 v[206:207], off
	s_waitcnt vmcnt(8)
	s_waitcnt lgkmcnt(0)
	s_setprio 1
	s_barrier
	v_mfma_f32_16x16x32_bf16 v[170:173], v[78:81], v[150:153], v[170:173]
	v_mfma_f32_16x16x32_bf16 v[162:165], v[94:97], v[150:153], v[162:165]
	v_mfma_f32_16x16x32_bf16 v[142:145], v[78:81], v[166:169], v[142:145]
	v_mfma_f32_16x16x32_bf16 v[138:141], v[94:97], v[166:169], v[138:141]
	v_mfma_f32_16x16x32_bf16 v[118:121], v[78:81], v[178:181], v[118:121]
	v_mfma_f32_16x16x32_bf16 v[114:117], v[94:97], v[178:181], v[114:117]
	v_mfma_f32_16x16x32_bf16 v[86:89], v[78:81], v[186:189], v[86:89]
	v_mfma_f32_16x16x32_bf16 v[74:77], v[94:97], v[186:189], v[74:77]
	v_mfma_f32_16x16x32_bf16 v[170:173], v[82:85], v[158:161], v[170:173]
	v_mfma_f32_16x16x32_bf16 v[162:165], v[98:101], v[158:161], v[162:165]
	v_mfma_f32_16x16x32_bf16 v[142:145], v[82:85], v[174:177], v[142:145]
	v_mfma_f32_16x16x32_bf16 v[138:141], v[98:101], v[174:177], v[138:141]
	v_mfma_f32_16x16x32_bf16 v[118:121], v[82:85], v[182:185], v[118:121]
	v_mfma_f32_16x16x32_bf16 v[114:117], v[98:101], v[182:185], v[114:117]
	v_mfma_f32_16x16x32_bf16 v[86:89], v[82:85], v[190:193], v[86:89]
	v_mfma_f32_16x16x32_bf16 v[74:77], v[98:101], v[190:193], v[74:77]
	s_setprio 0
	s_setprio 1
	v_mfma_f32_16x16x32_bf16 v[154:157], v[106:109], v[150:153], v[154:157]
	v_mfma_f32_16x16x32_bf16 v[146:149], v[126:129], v[150:153], v[146:149]
	v_mfma_f32_16x16x32_bf16 v[130:133], v[106:109], v[166:169], v[130:133]
	v_mfma_f32_16x16x32_bf16 v[122:125], v[126:129], v[166:169], v[122:125]
	v_mfma_f32_16x16x32_bf16 v[102:105], v[106:109], v[178:181], v[102:105]
	v_mfma_f32_16x16x32_bf16 v[90:93], v[126:129], v[178:181], v[90:93]
	v_mfma_f32_16x16x32_bf16 v[70:73], v[106:109], v[186:189], v[70:73]
	v_mfma_f32_16x16x32_bf16 v[66:69], v[126:129], v[186:189], v[66:69]
	v_mfma_f32_16x16x32_bf16 v[154:157], v[110:113], v[158:161], v[154:157]
	v_mfma_f32_16x16x32_bf16 v[150:153], v[134:137], v[158:161], v[146:149]
	v_mfma_f32_16x16x32_bf16 v[130:133], v[110:113], v[174:177], v[130:133]
	v_mfma_f32_16x16x32_bf16 v[122:125], v[134:137], v[174:177], v[122:125]
	v_mfma_f32_16x16x32_bf16 v[102:105], v[110:113], v[182:185], v[102:105]
	v_mfma_f32_16x16x32_bf16 v[90:93], v[134:137], v[182:185], v[90:93]
	v_mfma_f32_16x16x32_bf16 v[70:73], v[110:113], v[190:193], v[70:73]
	v_mfma_f32_16x16x32_bf16 v[66:69], v[134:137], v[190:193], v[66:69]
	s_barrier
	s_setprio 0
	s_add_i32 s0, s4, s26
	v_lshl_add_u64 v[194:195], v[194:195], 0, s[80:81]
	s_mov_b32 m0, s0
	ds_read_b128 v[146:149], v239 offset:49152
	ds_read_b128 v[158:161], v239 offset:50176
	ds_read_b128 v[166:169], v239 offset:51200
	ds_read_b128 v[174:177], v239 offset:52224
	ds_read_b128 v[178:181], v239 offset:53248
	ds_read_b128 v[182:185], v239 offset:54272
	ds_read_b128 v[186:189], v239 offset:55296
	ds_read_b128 v[190:193], v239 offset:56320
	global_load_lds_dwordx4 v[194:195], off
	s_add_i32 m0, s0, 0x2000
	s_add_u32 s0, s20, 0x160080
	v_lshl_add_u64 v[194:195], v[196:197], 0, s[80:81]
	s_addc_u32 s1, s21, 0
	s_add_i32 s4, s5, s26
	global_load_lds_dwordx4 v[194:195], off
	v_lshl_add_u64 v[194:195], s[0:1], 0, v[202:203]
	s_mov_b32 m0, s4
	s_nop 0
	global_load_lds_dwordx4 v[194:195], off
	v_lshl_add_u64 v[194:195], s[0:1], 0, v[208:209]
	s_add_i32 m0, s4, 0x2000
	s_nop 0
	global_load_lds_dwordx4 v[194:195], off
	v_lshl_add_u64 v[194:195], v[198:199], 0, s[80:81]
	s_mov_b32 m0, s35
	s_nop 0
	global_load_lds_dwordx4 v[194:195], off
	v_lshl_add_u64 v[194:195], v[200:201], 0, s[80:81]
	s_mov_b32 m0, s36
	s_nop 0
	global_load_lds_dwordx4 v[194:195], off
	s_waitcnt vmcnt(8)
	s_waitcnt lgkmcnt(0)
	s_setprio 1
	s_barrier
	v_mfma_f32_16x16x32_bf16 v[62:65], v[78:81], v[146:149], v[62:65]
	v_mfma_f32_16x16x32_bf16 v[58:61], v[94:97], v[146:149], v[58:61]
	v_mfma_f32_16x16x32_bf16 v[46:49], v[78:81], v[166:169], v[46:49]
	v_mfma_f32_16x16x32_bf16 v[42:45], v[94:97], v[166:169], v[42:45]
	v_mfma_f32_16x16x32_bf16 v[30:33], v[78:81], v[178:181], v[30:33]
	v_mfma_f32_16x16x32_bf16 v[26:29], v[94:97], v[178:181], v[26:29]
	v_mfma_f32_16x16x32_bf16 v[14:17], v[78:81], v[186:189], v[14:17]
	v_mfma_f32_16x16x32_bf16 v[10:13], v[94:97], v[186:189], v[10:13]
	v_mfma_f32_16x16x32_bf16 v[62:65], v[82:85], v[158:161], v[62:65]
	v_mfma_f32_16x16x32_bf16 v[58:61], v[98:101], v[158:161], v[58:61]
	v_mfma_f32_16x16x32_bf16 v[46:49], v[82:85], v[174:177], v[46:49]
	v_mfma_f32_16x16x32_bf16 v[42:45], v[98:101], v[174:177], v[42:45]
	v_mfma_f32_16x16x32_bf16 v[30:33], v[82:85], v[182:185], v[30:33]
	v_mfma_f32_16x16x32_bf16 v[26:29], v[98:101], v[182:185], v[26:29]
	v_mfma_f32_16x16x32_bf16 v[14:17], v[82:85], v[190:193], v[14:17]
	v_mfma_f32_16x16x32_bf16 v[10:13], v[98:101], v[190:193], v[10:13]
	s_setprio 0
	s_setprio 1
	v_mfma_f32_16x16x32_bf16 v[54:57], v[106:109], v[146:149], v[54:57]
	v_mfma_f32_16x16x32_bf16 v[50:53], v[126:129], v[146:149], v[50:53]
	v_mfma_f32_16x16x32_bf16 v[38:41], v[106:109], v[166:169], v[38:41]
	v_mfma_f32_16x16x32_bf16 v[34:37], v[126:129], v[166:169], v[34:37]
	v_mfma_f32_16x16x32_bf16 v[22:25], v[106:109], v[178:181], v[22:25]
	v_mfma_f32_16x16x32_bf16 v[18:21], v[126:129], v[178:181], v[18:21]
	v_mfma_f32_16x16x32_bf16 v[6:9], v[106:109], v[186:189], v[6:9]
	v_mfma_f32_16x16x32_bf16 v[2:5], v[126:129], v[186:189], v[2:5]
	v_mfma_f32_16x16x32_bf16 v[54:57], v[110:113], v[158:161], v[54:57]
	v_mfma_f32_16x16x32_bf16 v[50:53], v[134:137], v[158:161], v[50:53]
	v_mfma_f32_16x16x32_bf16 v[38:41], v[110:113], v[174:177], v[38:41]
	v_mfma_f32_16x16x32_bf16 v[34:37], v[134:137], v[174:177], v[34:37]
	v_mfma_f32_16x16x32_bf16 v[22:25], v[110:113], v[182:185], v[22:25]
	v_mfma_f32_16x16x32_bf16 v[18:21], v[134:137], v[182:185], v[18:21]
	v_mfma_f32_16x16x32_bf16 v[6:9], v[110:113], v[190:193], v[6:9]
	v_mfma_f32_16x16x32_bf16 v[2:5], v[134:137], v[190:193], v[2:5]
	s_barrier
	s_setprio 0
	s_add_i32 s59, s59, 2
	s_add_u32 s49, s49, 0x100
	s_addc_u32 s58, s58, 0
	s_cmpk_gt_u32 s59, 0x55
	s_mov_b64 s[4:5], s[18:19]
	s_cbranch_scc0 .LBB0_1718
	s_and_b64 vcc, exec, s[14:15]
	s_cbranch_vccz .LBB0_1721
	s_barrier

.LBB0_1739:
	ds_read_b128 v[172:175], v139
	ds_read_b128 v[176:179], v139 offset:1024
	ds_read_b128 v[180:183], v139 offset:2048
	ds_read_b128 v[184:187], v139 offset:3072
	ds_read_b128 v[188:191], v139 offset:4096
	ds_read_b128 v[192:195], v139 offset:5120
	ds_read_b128 v[196:199], v139 offset:6144
	ds_read_b128 v[208:211], v139 offset:7168
	s_add_u32 s16, s14, 0x100
	s_addc_u32 s17, s15, 0
	s_add_i32 s0, 0, 0x10000
	s_cmp_eq_u32 s49, 4
	s_cselect_b32 s21, s9, s17
	s_cselect_b32 s20, s8, s16
	s_cselect_b32 s19, s11, s41
	s_cselect_b32 s18, s10, s40
	s_add_i32 s33, 0, 0x14000
	v_add_u32_e32 v152, s0, v136
	v_add_u32_e32 v168, s33, v136
	ds_read_b128 v[140:143], v152
	ds_read_b128 v[144:147], v152 offset:1024
	ds_read_b128 v[148:151], v152 offset:2048
	ds_read_b128 v[152:155], v152 offset:3072
	ds_read_b128 v[156:159], v168
	ds_read_b128 v[160:163], v168 offset:1024
	ds_read_b128 v[164:167], v168 offset:2048
	ds_read_b128 v[168:171], v168 offset:3072
	v_lshl_add_u64 v[200:201], s[14:15], 0, v[132:133]
	s_add_i32 m0, s23, 0xc000
	global_load_lds_dwordx4 v[200:201], off
	v_lshl_add_u64 v[200:201], s[14:15], 0, v[134:135]
	s_add_i32 m0, s23, 0xe000
	s_nop 0
	global_load_lds_dwordx4 v[200:201], off
	s_waitcnt vmcnt(8)
	s_waitcnt lgkmcnt(0)
	s_setprio 1
	s_barrier
	v_mfma_f32_16x16x32_bf16 v[126:129], v[140:143], v[172:175], v[126:129]
	v_mfma_f32_16x16x32_bf16 v[122:125], v[148:151], v[172:175], v[122:125]
	v_mfma_f32_16x16x32_bf16 v[118:121], v[140:143], v[180:183], v[118:121]
	v_mfma_f32_16x16x32_bf16 v[114:117], v[148:151], v[180:183], v[114:117]
	v_mfma_f32_16x16x32_bf16 v[106:109], v[140:143], v[188:191], v[106:109]
	v_mfma_f32_16x16x32_bf16 v[98:101], v[148:151], v[188:191], v[98:101]
	v_mfma_f32_16x16x32_bf16 v[90:93], v[140:143], v[196:199], v[90:93]
	v_mfma_f32_16x16x32_bf16 v[82:85], v[148:151], v[196:199], v[82:85]
	v_mfma_f32_16x16x32_bf16 v[126:129], v[144:147], v[176:179], v[126:129]
	v_mfma_f32_16x16x32_bf16 v[122:125], v[152:155], v[176:179], v[122:125]
	v_mfma_f32_16x16x32_bf16 v[118:121], v[144:147], v[184:187], v[118:121]
	v_mfma_f32_16x16x32_bf16 v[114:117], v[152:155], v[184:187], v[114:117]
	v_mfma_f32_16x16x32_bf16 v[106:109], v[144:147], v[192:195], v[106:109]
	v_mfma_f32_16x16x32_bf16 v[98:101], v[152:155], v[192:195], v[98:101]
	v_mfma_f32_16x16x32_bf16 v[90:93], v[144:147], v[208:211], v[90:93]
	v_mfma_f32_16x16x32_bf16 v[82:85], v[152:155], v[208:211], v[82:85]
	s_setprio 0
	s_setprio 1
	v_mfma_f32_16x16x32_bf16 v[110:113], v[156:159], v[172:175], v[110:113]
	v_mfma_f32_16x16x32_bf16 v[102:105], v[164:167], v[172:175], v[102:105]
	v_mfma_f32_16x16x32_bf16 v[94:97], v[156:159], v[180:183], v[94:97]
	v_mfma_f32_16x16x32_bf16 v[86:89], v[164:167], v[180:183], v[86:89]
	v_mfma_f32_16x16x32_bf16 v[78:81], v[156:159], v[188:191], v[78:81]
	v_mfma_f32_16x16x32_bf16 v[74:77], v[164:167], v[188:191], v[74:77]
	v_mfma_f32_16x16x32_bf16 v[70:73], v[156:159], v[196:199], v[70:73]
	v_mfma_f32_16x16x32_bf16 v[66:69], v[164:167], v[196:199], v[66:69]
	v_mfma_f32_16x16x32_bf16 v[110:113], v[160:163], v[176:179], v[110:113]
	v_mfma_f32_16x16x32_bf16 v[102:105], v[168:171], v[176:179], v[102:105]
	v_mfma_f32_16x16x32_bf16 v[94:97], v[160:163], v[184:187], v[94:97]
	v_mfma_f32_16x16x32_bf16 v[86:89], v[168:171], v[184:187], v[86:89]
	v_mfma_f32_16x16x32_bf16 v[78:81], v[160:163], v[192:195], v[78:81]
	v_mfma_f32_16x16x32_bf16 v[74:77], v[168:171], v[192:195], v[74:77]
	v_mfma_f32_16x16x32_bf16 v[70:73], v[160:163], v[208:211], v[70:73]
	v_mfma_f32_16x16x32_bf16 v[66:69], v[168:171], v[208:211], v[66:69]
	s_barrier
	s_setprio 0
	s_add_i32 s0, s0, s22
	v_lshl_add_u64 v[200:201], s[18:19], 0, v[202:203]
	s_mov_b32 m0, s0
	ds_read_b128 v[172:175], v139 offset:16384
	ds_read_b128 v[176:179], v139 offset:17408
	ds_read_b128 v[180:183], v139 offset:18432
	ds_read_b128 v[184:187], v139 offset:19456
	ds_read_b128 v[188:191], v139 offset:20480
	ds_read_b128 v[192:195], v139 offset:21504
	ds_read_b128 v[196:199], v139 offset:22528
	ds_read_b128 v[208:211], v139 offset:23552
	global_load_lds_dwordx4 v[200:201], off
	s_add_i32 m0, s0, 0x2000
	s_add_u32 s0, s18, 0x160000
	v_lshl_add_u64 v[204:205], s[18:19], 0, v[130:131]
	s_addc_u32 s1, s19, 0
	s_add_i32 s14, s33, s22
	global_load_lds_dwordx4 v[204:205], off
	v_lshl_add_u64 v[206:207], s[0:1], 0, v[202:203]
	s_mov_b32 m0, s14
	v_lshl_add_u64 v[212:213], s[20:21], 0, v[130:131]
	global_load_lds_dwordx4 v[206:207], off
	v_lshl_add_u64 v[206:207], s[0:1], 0, v[130:131]
	s_add_i32 m0, s14, 0x2000
	s_nop 0
	global_load_lds_dwordx4 v[206:207], off
	v_lshl_add_u64 v[206:207], s[20:21], 0, v[202:203]
	s_mov_b32 m0, s23
	s_nop 0
	global_load_lds_dwordx4 v[206:207], off
	s_mov_b32 m0, s26
	s_nop 0
	global_load_lds_dwordx4 v[212:213], off
	s_waitcnt vmcnt(8)
	s_waitcnt lgkmcnt(0)
	s_setprio 1
	s_barrier
	v_mfma_f32_16x16x32_bf16 v[62:65], v[140:143], v[172:175], v[62:65]
	v_mfma_f32_16x16x32_bf16 v[58:61], v[148:151], v[172:175], v[58:61]
	v_mfma_f32_16x16x32_bf16 v[54:57], v[140:143], v[180:183], v[54:57]
	v_mfma_f32_16x16x32_bf16 v[50:53], v[148:151], v[180:183], v[50:53]
	v_mfma_f32_16x16x32_bf16 v[38:41], v[140:143], v[188:191], v[38:41]
	v_mfma_f32_16x16x32_bf16 v[34:37], v[148:151], v[188:191], v[34:37]
	v_mfma_f32_16x16x32_bf16 v[22:25], v[140:143], v[196:199], v[22:25]
	v_mfma_f32_16x16x32_bf16 v[18:21], v[148:151], v[196:199], v[18:21]
	v_mfma_f32_16x16x32_bf16 v[62:65], v[144:147], v[176:179], v[62:65]
	v_mfma_f32_16x16x32_bf16 v[58:61], v[152:155], v[176:179], v[58:61]
	v_mfma_f32_16x16x32_bf16 v[54:57], v[144:147], v[184:187], v[54:57]
	v_mfma_f32_16x16x32_bf16 v[50:53], v[152:155], v[184:187], v[50:53]
	v_mfma_f32_16x16x32_bf16 v[38:41], v[144:147], v[192:195], v[38:41]
	v_mfma_f32_16x16x32_bf16 v[34:37], v[152:155], v[192:195], v[34:37]
	v_mfma_f32_16x16x32_bf16 v[22:25], v[144:147], v[208:211], v[22:25]
	v_mfma_f32_16x16x32_bf16 v[18:21], v[152:155], v[208:211], v[18:21]
	s_setprio 0
	s_setprio 1
	v_mfma_f32_16x16x32_bf16 v[46:49], v[156:159], v[172:175], v[46:49]
	v_mfma_f32_16x16x32_bf16 v[42:45], v[164:167], v[172:175], v[42:45]
	v_mfma_f32_16x16x32_bf16 v[30:33], v[156:159], v[180:183], v[30:33]
	v_mfma_f32_16x16x32_bf16 v[26:29], v[164:167], v[180:183], v[26:29]
	v_mfma_f32_16x16x32_bf16 v[14:17], v[156:159], v[188:191], v[14:17]
	v_mfma_f32_16x16x32_bf16 v[10:13], v[164:167], v[188:191], v[10:13]
	v_mfma_f32_16x16x32_bf16 v[6:9], v[156:159], v[196:199], v[6:9]
	v_mfma_f32_16x16x32_bf16 v[2:5], v[164:167], v[196:199], v[2:5]
	v_mfma_f32_16x16x32_bf16 v[46:49], v[160:163], v[176:179], v[46:49]
	v_mfma_f32_16x16x32_bf16 v[42:45], v[168:171], v[176:179], v[42:45]
	v_mfma_f32_16x16x32_bf16 v[30:33], v[160:163], v[184:187], v[30:33]
	v_mfma_f32_16x16x32_bf16 v[26:29], v[168:171], v[184:187], v[26:29]
	v_mfma_f32_16x16x32_bf16 v[14:17], v[160:163], v[192:195], v[14:17]
	v_mfma_f32_16x16x32_bf16 v[10:13], v[168:171], v[192:195], v[10:13]
	v_mfma_f32_16x16x32_bf16 v[6:9], v[160:163], v[208:211], v[6:9]
	v_mfma_f32_16x16x32_bf16 v[2:5], v[168:171], v[208:211], v[2:5]
	s_barrier
	s_setprio 0
	s_add_i32 s14, 0, 0x18000
	s_add_i32 s15, 0, 0x1c000
	v_add_u32_e32 v152, s14, v136
	v_add_u32_e32 v168, s15, v136
	ds_read_b128 v[140:143], v152
	ds_read_b128 v[144:147], v152 offset:1024
	ds_read_b128 v[148:151], v152 offset:2048
	ds_read_b128 v[152:155], v152 offset:3072
	ds_read_b128 v[156:159], v168
	ds_read_b128 v[160:163], v168 offset:1024
	ds_read_b128 v[164:167], v168 offset:2048
	ds_read_b128 v[168:171], v168 offset:3072
	s_add_u32 s0, s20, 0x160000
	s_addc_u32 s1, s21, 0
	s_mov_b32 m0, s27
	v_lshl_add_u64 v[214:215], s[0:1], 0, v[202:203]
	ds_read_b128 v[172:175], v139 offset:32768
	ds_read_b128 v[176:179], v139 offset:33792
	ds_read_b128 v[180:183], v139 offset:34816
	ds_read_b128 v[184:187], v139 offset:35840
	ds_read_b128 v[188:191], v139 offset:36864
	ds_read_b128 v[192:195], v139 offset:37888
	ds_read_b128 v[196:199], v139 offset:38912
	ds_read_b128 v[208:211], v139 offset:39936
	global_load_lds_dwordx4 v[214:215], off
	v_lshl_add_u64 v[214:215], s[0:1], 0, v[130:131]
	s_mov_b32 m0, s28
	s_nop 0
	global_load_lds_dwordx4 v[214:215], off
	s_waitcnt vmcnt(8)
	s_waitcnt lgkmcnt(0)
	s_setprio 1
	s_barrier
	v_mfma_f32_16x16x32_bf16 v[126:129], v[140:143], v[172:175], v[126:129]
	v_mfma_f32_16x16x32_bf16 v[122:125], v[148:151], v[172:175], v[122:125]
	v_mfma_f32_16x16x32_bf16 v[118:121], v[140:143], v[180:183], v[118:121]
	v_mfma_f32_16x16x32_bf16 v[114:117], v[148:151], v[180:183], v[114:117]
	v_mfma_f32_16x16x32_bf16 v[106:109], v[140:143], v[188:191], v[106:109]
	v_mfma_f32_16x16x32_bf16 v[98:101], v[148:151], v[188:191], v[98:101]
	v_mfma_f32_16x16x32_bf16 v[90:93], v[140:143], v[196:199], v[90:93]
	v_mfma_f32_16x16x32_bf16 v[82:85], v[148:151], v[196:199], v[82:85]
	v_mfma_f32_16x16x32_bf16 v[126:129], v[144:147], v[176:179], v[126:129]
	v_mfma_f32_16x16x32_bf16 v[122:125], v[152:155], v[176:179], v[122:125]
	v_mfma_f32_16x16x32_bf16 v[118:121], v[144:147], v[184:187], v[118:121]
	v_mfma_f32_16x16x32_bf16 v[114:117], v[152:155], v[184:187], v[114:117]
	v_mfma_f32_16x16x32_bf16 v[106:109], v[144:147], v[192:195], v[106:109]
	v_mfma_f32_16x16x32_bf16 v[98:101], v[152:155], v[192:195], v[98:101]
	v_mfma_f32_16x16x32_bf16 v[90:93], v[144:147], v[208:211], v[90:93]
	v_mfma_f32_16x16x32_bf16 v[82:85], v[152:155], v[208:211], v[82:85]
	s_setprio 0
	s_setprio 1
	v_mfma_f32_16x16x32_bf16 v[110:113], v[156:159], v[172:175], v[110:113]
	v_mfma_f32_16x16x32_bf16 v[102:105], v[164:167], v[172:175], v[102:105]
	v_mfma_f32_16x16x32_bf16 v[94:97], v[156:159], v[180:183], v[94:97]
	v_mfma_f32_16x16x32_bf16 v[86:89], v[164:167], v[180:183], v[86:89]
	v_mfma_f32_16x16x32_bf16 v[78:81], v[156:159], v[188:191], v[78:81]
	v_mfma_f32_16x16x32_bf16 v[74:77], v[164:167], v[188:191], v[74:77]
	v_mfma_f32_16x16x32_bf16 v[70:73], v[156:159], v[196:199], v[70:73]
	v_mfma_f32_16x16x32_bf16 v[66:69], v[164:167], v[196:199], v[66:69]
	v_mfma_f32_16x16x32_bf16 v[110:113], v[160:163], v[176:179], v[110:113]
	v_mfma_f32_16x16x32_bf16 v[102:105], v[168:171], v[176:179], v[102:105]
	v_mfma_f32_16x16x32_bf16 v[94:97], v[160:163], v[184:187], v[94:97]
	v_mfma_f32_16x16x32_bf16 v[86:89], v[168:171], v[184:187], v[86:89]
	v_mfma_f32_16x16x32_bf16 v[78:81], v[160:163], v[192:195], v[78:81]
	v_mfma_f32_16x16x32_bf16 v[74:77], v[168:171], v[192:195], v[74:77]
	v_mfma_f32_16x16x32_bf16 v[70:73], v[160:163], v[208:211], v[70:73]
	v_mfma_f32_16x16x32_bf16 v[66:69], v[168:171], v[208:211], v[66:69]
	s_barrier
	s_setprio 0
	s_add_i32 s0, s14, s22
	v_lshl_add_u64 v[200:201], v[200:201], 0, s[80:81]
	s_mov_b32 m0, s0
	ds_read_b128 v[172:175], v139 offset:49152
	ds_read_b128 v[176:179], v139 offset:50176
	ds_read_b128 v[180:183], v139 offset:51200
	ds_read_b128 v[184:187], v139 offset:52224
	ds_read_b128 v[188:191], v139 offset:53248
	ds_read_b128 v[192:195], v139 offset:54272
	ds_read_b128 v[196:199], v139 offset:55296
	ds_read_b128 v[208:211], v139 offset:56320
	global_load_lds_dwordx4 v[200:201], off
	s_add_i32 m0, s0, 0x2000
	s_add_u32 s0, s18, 0x160080
	v_lshl_add_u64 v[200:201], v[204:205], 0, s[80:81]
	s_addc_u32 s1, s19, 0
	s_add_i32 s14, s15, s22
	global_load_lds_dwordx4 v[200:201], off
	v_lshl_add_u64 v[200:201], s[0:1], 0, v[202:203]
	s_mov_b32 m0, s14
	s_nop 0
	global_load_lds_dwordx4 v[200:201], off
	v_lshl_add_u64 v[200:201], s[0:1], 0, v[130:131]
	s_add_i32 m0, s14, 0x2000
	s_nop 0
	global_load_lds_dwordx4 v[200:201], off
	v_lshl_add_u64 v[200:201], v[206:207], 0, s[80:81]
	s_mov_b32 m0, s29
	s_nop 0
	global_load_lds_dwordx4 v[200:201], off
	v_lshl_add_u64 v[200:201], v[212:213], 0, s[80:81]
	s_mov_b32 m0, s30
	s_nop 0
	global_load_lds_dwordx4 v[200:201], off
	s_waitcnt vmcnt(8)
	s_waitcnt lgkmcnt(0)
	s_setprio 1
	s_barrier
	v_mfma_f32_16x16x32_bf16 v[62:65], v[140:143], v[172:175], v[62:65]
	v_mfma_f32_16x16x32_bf16 v[58:61], v[148:151], v[172:175], v[58:61]
	v_mfma_f32_16x16x32_bf16 v[54:57], v[140:143], v[180:183], v[54:57]
	v_mfma_f32_16x16x32_bf16 v[50:53], v[148:151], v[180:183], v[50:53]
	v_mfma_f32_16x16x32_bf16 v[38:41], v[140:143], v[188:191], v[38:41]
	v_mfma_f32_16x16x32_bf16 v[34:37], v[148:151], v[188:191], v[34:37]
	v_mfma_f32_16x16x32_bf16 v[22:25], v[140:143], v[196:199], v[22:25]
	v_mfma_f32_16x16x32_bf16 v[18:21], v[148:151], v[196:199], v[18:21]
	v_mfma_f32_16x16x32_bf16 v[62:65], v[144:147], v[176:179], v[62:65]
	v_mfma_f32_16x16x32_bf16 v[58:61], v[152:155], v[176:179], v[58:61]
	v_mfma_f32_16x16x32_bf16 v[54:57], v[144:147], v[184:187], v[54:57]
	v_mfma_f32_16x16x32_bf16 v[50:53], v[152:155], v[184:187], v[50:53]
	v_mfma_f32_16x16x32_bf16 v[38:41], v[144:147], v[192:195], v[38:41]
	v_mfma_f32_16x16x32_bf16 v[34:37], v[152:155], v[192:195], v[34:37]
	v_mfma_f32_16x16x32_bf16 v[22:25], v[144:147], v[208:211], v[22:25]
	v_mfma_f32_16x16x32_bf16 v[18:21], v[152:155], v[208:211], v[18:21]
	s_setprio 0
	s_setprio 1
	v_mfma_f32_16x16x32_bf16 v[46:49], v[156:159], v[172:175], v[46:49]
	v_mfma_f32_16x16x32_bf16 v[42:45], v[164:167], v[172:175], v[42:45]
	v_mfma_f32_16x16x32_bf16 v[30:33], v[156:159], v[180:183], v[30:33]
	v_mfma_f32_16x16x32_bf16 v[26:29], v[164:167], v[180:183], v[26:29]
	v_mfma_f32_16x16x32_bf16 v[14:17], v[156:159], v[188:191], v[14:17]
	v_mfma_f32_16x16x32_bf16 v[10:13], v[164:167], v[188:191], v[10:13]
	v_mfma_f32_16x16x32_bf16 v[6:9], v[156:159], v[196:199], v[6:9]
	v_mfma_f32_16x16x32_bf16 v[2:5], v[164:167], v[196:199], v[2:5]
	v_mfma_f32_16x16x32_bf16 v[46:49], v[160:163], v[176:179], v[46:49]
	v_mfma_f32_16x16x32_bf16 v[42:45], v[168:171], v[176:179], v[42:45]
	v_mfma_f32_16x16x32_bf16 v[30:33], v[160:163], v[184:187], v[30:33]
	v_mfma_f32_16x16x32_bf16 v[26:29], v[168:171], v[184:187], v[26:29]
	v_mfma_f32_16x16x32_bf16 v[14:17], v[160:163], v[192:195], v[14:17]
	v_mfma_f32_16x16x32_bf16 v[10:13], v[168:171], v[192:195], v[10:13]
	v_mfma_f32_16x16x32_bf16 v[6:9], v[160:163], v[208:211], v[6:9]
	v_mfma_f32_16x16x32_bf16 v[2:5], v[168:171], v[208:211], v[2:5]
	s_barrier
	s_setprio 0
	s_add_i32 s49, s49, 2
	s_add_u32 s40, s40, 0x100
	s_addc_u32 s41, s41, 0
	s_cmp_gt_u32 s49, 5
	s_mov_b64 s[14:15], s[16:17]
	s_cbranch_scc0 .LBB0_1739
	s_and_b64 vcc, exec, s[6:7]
	s_cbranch_vccz .LBB0_1742
	s_barrier
